# v18: v17 variant - moved LDS-DMA loads issued after each SP1 segment's own DMA (after the ds_reads) instead of at the segment start
# baseline (speedup 1.0000x reference)
; #define PG8_WAIT_V(n) asm volatile("s_waitcnt vmcnt(" #n ")" ::: "memory")
; #define PG8_WAIT_L(n) asm volatile("s_waitcnt lgkmcnt(" #n ")" ::: "memory")
; #define PG8_BAR __builtin_amdgcn_s_barrier()
; #define PG8_SCHED __builtin_amdgcn_sched_barrier(0)
;     ...
;         for (int t = 0; t < nt; t += 2) {
;             const bool last = (t == nt - 2);
;             const char* a1 = cA + (size_t)(t + 1) * kstep;
;             const char* a2 = last ? nA : cA + (size_t)(t + 2) * kstep; const char* b2 = last ? nB : cB + (size_t)(t + 2) * kstep;
;             const char* a3 = a2 + kstep; const char* b3 = b2 + kstep;
;             if (last && has_next) S.a_ready(nxt);
;             if constexpr (SP2) {
;             PG8_LDB(B0, 0, 0); PG8_LDB(B1, 0, 1); PG8_SCHED; PG8_LDA(At, 0, 0); PG8_STAGE(PG8_SA(1, 1), a1 + hstepA, voffA);
;             PG8_WAIT_V(8); PG8_WAIT_L(0); PG8_BAR; PG8_MMA(0, 0, At, B0); PG8_MMA(0, 1, At, B1); PG8_BAR; PG8_SCHED;
;             if constexpr (!HALFU) PG8_LDA(At, 0, 1); PG8_STAGE(PG8_SB(0, 0), b2, voffB); PG8_STAGE(PG8_SB(0, 1), b2 + hstep, voffB); PG8_STAGE(PG8_SA(0, 0), a2, voffA);
;             PG8_WAIT_V(8); PG8_WAIT_L(0); PG8_BAR; if constexpr (!HALFU) { PG8_MMA(1, 0, At, B0); PG8_MMA(1, 1, At, B1); } PG8_BAR; PG8_SCHED;
.LBB0_317:
	s_add_u32 s98, s14, 0x80
	s_addc_u32 s99, s15, 0
	ds_read_b128 v[128:131], v155
	ds_read_b128 v[132:135], v155 offset:1024
	ds_read_b128 v[164:167], v155 offset:2048
	ds_read_b128 v[168:171], v155 offset:3072
	ds_read_b128 v[172:175], v156
	ds_read_b128 v[176:179], v156 offset:1024
	ds_read_b128 v[180:183], v156 offset:2048
	ds_read_b128 v[184:187], v156 offset:3072
	s_add_u32 s30, s14, 0x100
	s_addc_u32 s31, s15, 0
	s_cmp_eq_u32 s58, 28
	s_cselect_b32 s38, s23, s30
	s_cselect_b32 s39, s7, s31
	s_cselect_b32 s36, s55, s56
	s_cselect_b32 s37, s21, s57
	s_add_u32 s34, s38, 0x80
	s_addc_u32 s35, s39, 0
	s_add_u32 s14, s14, 0x80080
	s_addc_u32 s15, s15, 0
	s_add_i32 m0, s29, 0xc000
	ds_read_b128 v[188:191], v157
	ds_read_b128 v[192:195], v157 offset:1024
	ds_read_b128 v[196:199], v157 offset:2048
	ds_read_b128 v[200:203], v157 offset:3072
	ds_read_b128 v[204:207], v157 offset:4096
	ds_read_b128 v[208:211], v157 offset:5120
	ds_read_b128 v[212:215], v157 offset:6144
	ds_read_b128 v[216:219], v157 offset:7168
	global_load_lds_dwordx4 v252, s[14:15]
	s_add_i32 m0, s29, 0xe000
	s_nop 0
	global_load_lds_dwordx4 v146, s[14:15]
	s_mov_b32 m0, s49
	s_nop 0
	global_load_lds_dwordx4 v252, s[98:99]
	s_mov_b32 m0, s50
	s_nop 0
	global_load_lds_dwordx4 v146, s[98:99]
	s_waitcnt vmcnt(8)
	s_waitcnt lgkmcnt(0)
	s_barrier
	s_setprio 1
	s_waitcnt lgkmcnt(0)
	v_mfma_scale_f32_16x16x128_f8f6f4 v[124:127], v[128:135], v[188:195], v[124:127], v158, v158 op_sel_hi:[0,0,0]
	v_mfma_scale_f32_16x16x128_f8f6f4 v[120:123], v[164:171], v[188:195], v[120:123], v158, v158 op_sel_hi:[0,0,0]
	v_mfma_scale_f32_16x16x128_f8f6f4 v[108:111], v[128:135], v[196:203], v[108:111], v158, v158 op_sel_hi:[0,0,0]
	v_mfma_scale_f32_16x16x128_f8f6f4 v[104:107], v[164:171], v[196:203], v[104:107], v158, v158 op_sel_hi:[0,0,0]
	v_mfma_scale_f32_16x16x128_f8f6f4 v[136:139], v[128:135], v[204:211], v[92:95], v158, v158 op_sel_hi:[0,0,0]
	v_mfma_scale_f32_16x16x128_f8f6f4 v[220:223], v[164:171], v[204:211], v[88:91], v158, v158 op_sel_hi:[0,0,0]
	v_mfma_scale_f32_16x16x128_f8f6f4 v[224:227], v[128:135], v[212:219], v[76:79], v158, v158 op_sel_hi:[0,0,0]
	v_mfma_scale_f32_16x16x128_f8f6f4 v[228:231], v[164:171], v[212:219], v[72:75], v158, v158 op_sel_hi:[0,0,0]
	s_setprio 0
	s_setprio 1
	v_mfma_scale_f32_16x16x128_f8f6f4 v[116:119], v[172:179], v[188:195], v[116:119], v158, v158 op_sel_hi:[0,0,0]
	v_mfma_scale_f32_16x16x128_f8f6f4 v[112:115], v[180:187], v[188:195], v[112:115], v158, v158 op_sel_hi:[0,0,0]
	v_mfma_scale_f32_16x16x128_f8f6f4 v[100:103], v[172:179], v[196:203], v[100:103], v158, v158 op_sel_hi:[0,0,0]
	v_mfma_scale_f32_16x16x128_f8f6f4 v[96:99], v[180:187], v[196:203], v[96:99], v158, v158 op_sel_hi:[0,0,0]
	v_mfma_scale_f32_16x16x128_f8f6f4 v[188:191], v[172:179], v[204:211], v[84:87], v158, v158 op_sel_hi:[0,0,0]
	v_mfma_scale_f32_16x16x128_f8f6f4 v[192:195], v[180:187], v[204:211], v[80:83], v158, v158 op_sel_hi:[0,0,0]
	v_mfma_scale_f32_16x16x128_f8f6f4 v[196:199], v[172:179], v[212:219], v[68:71], v158, v158 op_sel_hi:[0,0,0]
	v_mfma_scale_f32_16x16x128_f8f6f4 v[200:203], v[180:187], v[212:219], v[64:67], v158, v158 op_sel_hi:[0,0,0]
	s_setprio 0
	s_barrier
	s_add_i32 s14, s53, s40
	s_mov_b32 m0, s14
	s_nop 1
	ds_read_b128 v[64:67], v157 offset:16384
	ds_read_b128 v[68:71], v157 offset:17408
	ds_read_b128 v[72:75], v157 offset:18432
	ds_read_b128 v[76:79], v157 offset:19456
	ds_read_b128 v[80:83], v157 offset:20480
	ds_read_b128 v[84:87], v157 offset:21504
	ds_read_b128 v[88:91], v157 offset:22528
	ds_read_b128 v[92:95], v157 offset:23552
	global_load_lds_dwordx4 v144, s[36:37]
	s_add_i32 m0, s14, 0x2000
	s_add_u32 s14, s36, 0x80000
	s_addc_u32 s15, s37, 0
	s_add_i32 s59, s54, s40
	global_load_lds_dwordx4 v148, s[36:37]
	s_mov_b32 m0, s59
	s_nop 0
	global_load_lds_dwordx4 v144, s[14:15]
	s_add_i32 m0, s59, 0x2000
	s_nop 0
	global_load_lds_dwordx4 v148, s[14:15]
	s_waitcnt vmcnt(4)
	s_waitcnt lgkmcnt(0)
	s_barrier
	s_setprio 1
	s_waitcnt lgkmcnt(0)
	v_mfma_scale_f32_16x16x128_f8f6f4 v[60:63], v[128:135], v[64:71], v[60:63], v158, v158 op_sel_hi:[0,0,0]
	v_mfma_scale_f32_16x16x128_f8f6f4 v[56:59], v[164:171], v[64:71], v[56:59], v158, v158 op_sel_hi:[0,0,0]
	v_mfma_scale_f32_16x16x128_f8f6f4 v[204:207], v[128:135], v[72:79], v[44:47], v158, v158 op_sel_hi:[0,0,0]
	v_mfma_scale_f32_16x16x128_f8f6f4 v[208:211], v[164:171], v[72:79], v[40:43], v158, v158 op_sel_hi:[0,0,0]
	v_mfma_scale_f32_16x16x128_f8f6f4 v[212:215], v[128:135], v[80:87], v[28:31], v158, v158 op_sel_hi:[0,0,0]
	v_mfma_scale_f32_16x16x128_f8f6f4 v[216:219], v[164:171], v[80:87], v[24:27], v158, v158 op_sel_hi:[0,0,0]
	v_mfma_scale_f32_16x16x128_f8f6f4 v[232:235], v[128:135], v[88:95], v[12:15], v158, v158 op_sel_hi:[0,0,0]
	v_mfma_scale_f32_16x16x128_f8f6f4 v[236:239], v[164:171], v[88:95], v[8:11], v158, v158 op_sel_hi:[0,0,0]
	s_setprio 0
	s_setprio 1
	v_mfma_scale_f32_16x16x128_f8f6f4 v[52:55], v[172:179], v[64:71], v[52:55], v158, v158 op_sel_hi:[0,0,0]
	v_mfma_scale_f32_16x16x128_f8f6f4 v[48:51], v[180:187], v[64:71], v[48:51], v158, v158 op_sel_hi:[0,0,0]
	v_mfma_scale_f32_16x16x128_f8f6f4 v[240:243], v[172:179], v[72:79], v[36:39], v158, v158 op_sel_hi:[0,0,0]
	v_mfma_scale_f32_16x16x128_f8f6f4 v[244:247], v[180:187], v[72:79], v[32:35], v158, v158 op_sel_hi:[0,0,0]
	v_mfma_scale_f32_16x16x128_f8f6f4 v[248:251], v[172:179], v[80:87], v[20:23], v158, v158 op_sel_hi:[0,0,0]
	v_mfma_scale_f32_16x16x128_f8f6f4 v[150:153], v[180:187], v[80:87], v[16:19], v158, v158 op_sel_hi:[0,0,0]
	v_mfma_scale_f32_16x16x128_f8f6f4 v[160:163], v[172:179], v[88:95], v[4:7], v158, v158 op_sel_hi:[0,0,0]
	v_mfma_scale_f32_16x16x128_f8f6f4 v[140:143], v[180:187], v[88:95], v[0:3], v158, v158 op_sel_hi:[0,0,0]
	s_setprio 0
	s_barrier
; #define PG8_WAIT_V(n) asm volatile("s_waitcnt vmcnt(" #n ")" ::: "memory")
; #define PG8_WAIT_L(n) asm volatile("s_waitcnt lgkmcnt(" #n ")" ::: "memory")
; #define PG8_BAR __builtin_amdgcn_s_barrier()
; #define PG8_SCHED __builtin_amdgcn_sched_barrier(0)
;     ...
;             PG8_LDB(B0, 1, 0); PG8_LDB(B1, 1, 1); PG8_SCHED; PG8_LDA(At, 1, 0); PG8_STAGE(PG8_SA(0, 1), a2 + hstepA, voffA);
;             PG8_WAIT_V(8); PG8_WAIT_L(0); PG8_BAR; PG8_MMA(0, 0, At, B0); PG8_MMA(0, 1, At, B1); PG8_BAR; PG8_SCHED;
;             if constexpr (!HALFU) PG8_LDA(At, 1, 1); PG8_STAGE(PG8_SB(1, 0), b3, voffB); PG8_STAGE(PG8_SB(1, 1), b3 + hstep, voffB); PG8_STAGE(PG8_SA(1, 0), a3, voffA);
;             PG8_WAIT_V(8); PG8_WAIT_L(0); PG8_BAR; if constexpr (!HALFU) { PG8_MMA(1, 0, At, B0); PG8_MMA(1, 1, At, B1); } PG8_BAR; PG8_SCHED;
	s_add_i32 s59, 0, 0x18000
	v_add_u32_e32 v8, s59, v154
	s_add_i32 s60, 0, 0x1c000
	s_nop 1
	ds_read_b128 v[0:3], v8
	ds_read_b128 v[4:7], v8 offset:1024
	ds_read_b128 v[16:19], v8 offset:2048
	ds_read_b128 v[20:23], v8 offset:3072
	v_add_u32_e32 v8, s60, v154
	ds_read_b128 v[128:131], v8
	ds_read_b128 v[132:135], v8 offset:1024
	ds_read_b128 v[164:167], v8 offset:2048
	ds_read_b128 v[168:171], v8 offset:3072
	s_add_u32 s14, s38, 0x80000
	s_addc_u32 s15, s39, 0
	s_mov_b32 m0, s42
	ds_read_b128 v[8:11], v157 offset:32768
	ds_read_b128 v[12:15], v157 offset:33792
	ds_read_b128 v[24:27], v157 offset:34816
	ds_read_b128 v[28:31], v157 offset:35840
	ds_read_b128 v[32:35], v157 offset:36864
	ds_read_b128 v[36:39], v157 offset:37888
	ds_read_b128 v[40:43], v157 offset:38912
	ds_read_b128 v[44:47], v157 offset:39936
	global_load_lds_dwordx4 v252, s[14:15]
	s_mov_b32 m0, s43
	s_nop 0
	global_load_lds_dwordx4 v146, s[14:15]
	s_mov_b32 m0, s29
	s_nop 0
	global_load_lds_dwordx4 v252, s[38:39]
	s_mov_b32 m0, s41
	s_nop 0
	global_load_lds_dwordx4 v146, s[38:39]
	s_waitcnt vmcnt(8)
	s_waitcnt lgkmcnt(0)
	s_barrier
	s_setprio 1
	s_waitcnt lgkmcnt(0)
	v_mfma_scale_f32_16x16x128_f8f6f4 v[124:127], v[0:7], v[8:15], v[124:127], v158, v158 op_sel_hi:[0,0,0]
	v_mfma_scale_f32_16x16x128_f8f6f4 v[120:123], v[16:23], v[8:15], v[120:123], v158, v158 op_sel_hi:[0,0,0]
	v_mfma_scale_f32_16x16x128_f8f6f4 v[108:111], v[0:7], v[24:31], v[108:111], v158, v158 op_sel_hi:[0,0,0]
	v_mfma_scale_f32_16x16x128_f8f6f4 v[104:107], v[16:23], v[24:31], v[104:107], v158, v158 op_sel_hi:[0,0,0]
	v_mfma_scale_f32_16x16x128_f8f6f4 v[92:95], v[0:7], v[32:39], v[136:139], v158, v158 op_sel_hi:[0,0,0]
	v_mfma_scale_f32_16x16x128_f8f6f4 v[88:91], v[16:23], v[32:39], v[220:223], v158, v158 op_sel_hi:[0,0,0]
	v_mfma_scale_f32_16x16x128_f8f6f4 v[76:79], v[0:7], v[40:47], v[224:227], v158, v158 op_sel_hi:[0,0,0]
	v_mfma_scale_f32_16x16x128_f8f6f4 v[72:75], v[16:23], v[40:47], v[228:231], v158, v158 op_sel_hi:[0,0,0]
	s_setprio 0
	s_setprio 1
	v_mfma_scale_f32_16x16x128_f8f6f4 v[116:119], v[128:135], v[8:15], v[116:119], v158, v158 op_sel_hi:[0,0,0]
	v_mfma_scale_f32_16x16x128_f8f6f4 v[112:115], v[164:171], v[8:15], v[112:115], v158, v158 op_sel_hi:[0,0,0]
	v_mfma_scale_f32_16x16x128_f8f6f4 v[100:103], v[128:135], v[24:31], v[100:103], v158, v158 op_sel_hi:[0,0,0]
	v_mfma_scale_f32_16x16x128_f8f6f4 v[96:99], v[164:171], v[24:31], v[96:99], v158, v158 op_sel_hi:[0,0,0]
	v_mfma_scale_f32_16x16x128_f8f6f4 v[84:87], v[128:135], v[32:39], v[188:191], v158, v158 op_sel_hi:[0,0,0]
	v_mfma_scale_f32_16x16x128_f8f6f4 v[80:83], v[164:171], v[32:39], v[192:195], v158, v158 op_sel_hi:[0,0,0]
	v_mfma_scale_f32_16x16x128_f8f6f4 v[68:71], v[128:135], v[40:47], v[196:199], v158, v158 op_sel_hi:[0,0,0]
	v_mfma_scale_f32_16x16x128_f8f6f4 v[64:67], v[164:171], v[40:47], v[200:203], v158, v158 op_sel_hi:[0,0,0]
	s_setprio 0
	s_barrier
	s_add_u32 s14, s36, 0x80
	s_addc_u32 s15, s37, 0
	s_add_i32 s38, s59, s40
	s_mov_b32 m0, s38
	ds_read_b128 v[32:35], v157 offset:49152
	ds_read_b128 v[36:39], v157 offset:50176
	ds_read_b128 v[172:175], v157 offset:51200
	ds_read_b128 v[176:179], v157 offset:52224
	ds_read_b128 v[180:183], v157 offset:53248
	ds_read_b128 v[184:187], v157 offset:54272
	ds_read_b128 v[188:191], v157 offset:55296
	ds_read_b128 v[192:195], v157 offset:56320
	global_load_lds_dwordx4 v144, s[14:15]
	s_add_i32 m0, s38, 0x2000
	v_lshl_add_u64 v[8:9], s[14:15], 0, v[148:149]
	s_add_u32 s14, s36, 0x80080
	s_addc_u32 s15, s37, 0
	s_add_i32 s36, s60, s40
	global_load_lds_dwordx4 v[8:9], off
	s_mov_b32 m0, s36
	s_nop 0
	global_load_lds_dwordx4 v144, s[14:15]
	s_add_i32 m0, s36, 0x2000
	s_nop 0
	global_load_lds_dwordx4 v148, s[14:15]
	s_waitcnt vmcnt(4)
	s_waitcnt lgkmcnt(0)
	s_barrier
	s_setprio 1
	s_waitcnt lgkmcnt(0)
	v_mfma_scale_f32_16x16x128_f8f6f4 v[60:63], v[0:7], v[32:39], v[60:63], v158, v158 op_sel_hi:[0,0,0]
	v_mfma_scale_f32_16x16x128_f8f6f4 v[56:59], v[16:23], v[32:39], v[56:59], v158, v158 op_sel_hi:[0,0,0]
	v_mfma_scale_f32_16x16x128_f8f6f4 v[44:47], v[0:7], v[172:179], v[204:207], v158, v158 op_sel_hi:[0,0,0]
	v_mfma_scale_f32_16x16x128_f8f6f4 v[40:43], v[16:23], v[172:179], v[208:211], v158, v158 op_sel_hi:[0,0,0]
	v_mfma_scale_f32_16x16x128_f8f6f4 v[28:31], v[0:7], v[180:187], v[212:215], v158, v158 op_sel_hi:[0,0,0]
	v_mfma_scale_f32_16x16x128_f8f6f4 v[24:27], v[16:23], v[180:187], v[216:219], v158, v158 op_sel_hi:[0,0,0]
	v_mfma_scale_f32_16x16x128_f8f6f4 v[12:15], v[0:7], v[188:195], v[232:235], v158, v158 op_sel_hi:[0,0,0]
	v_mfma_scale_f32_16x16x128_f8f6f4 v[8:11], v[16:23], v[188:195], v[236:239], v158, v158 op_sel_hi:[0,0,0]
	s_setprio 0
	s_setprio 1
	v_mfma_scale_f32_16x16x128_f8f6f4 v[52:55], v[128:135], v[32:39], v[52:55], v158, v158 op_sel_hi:[0,0,0]
	v_mfma_scale_f32_16x16x128_f8f6f4 v[48:51], v[164:171], v[32:39], v[48:51], v158, v158 op_sel_hi:[0,0,0]
	v_mfma_scale_f32_16x16x128_f8f6f4 v[36:39], v[128:135], v[172:179], v[240:243], v158, v158 op_sel_hi:[0,0,0]
	v_mfma_scale_f32_16x16x128_f8f6f4 v[32:35], v[164:171], v[172:179], v[244:247], v158, v158 op_sel_hi:[0,0,0]
	v_mfma_scale_f32_16x16x128_f8f6f4 v[20:23], v[128:135], v[180:187], v[248:251], v158, v158 op_sel_hi:[0,0,0]
	v_mfma_scale_f32_16x16x128_f8f6f4 v[16:19], v[164:171], v[180:187], v[150:153], v158, v158 op_sel_hi:[0,0,0]
	v_mfma_scale_f32_16x16x128_f8f6f4 v[4:7], v[128:135], v[188:195], v[160:163], v158, v158 op_sel_hi:[0,0,0]
	v_mfma_scale_f32_16x16x128_f8f6f4 v[0:3], v[164:171], v[188:195], v[140:143], v158, v158 op_sel_hi:[0,0,0]
	s_setprio 0
	s_barrier
	s_add_i32 s58, s58, 2
	s_add_u32 s56, s56, 0x100
	s_addc_u32 s57, s57, 0
	s_cmp_gt_u32 s58, 29
	s_mov_b64 s[14:15], s[30:31]
	s_cbranch_scc0 .LBB0_317
	s_and_b64 vcc, exec, s[16:17]
	s_cbranch_vccz .LBB0_320
	s_barrier

; #define PG8_WAIT_V(n) asm volatile("s_waitcnt vmcnt(" #n ")" ::: "memory")
; #define PG8_WAIT_L(n) asm volatile("s_waitcnt lgkmcnt(" #n ")" ::: "memory")
; #define PG8_BAR __builtin_amdgcn_s_barrier()
; #define PG8_SCHED __builtin_amdgcn_sched_barrier(0)
;     ...
;         for (int t = 0; t < nt; t += 2) {
;             const bool last = (t == nt - 2);
;             const char* a1 = cA + (size_t)(t + 1) * kstep;
;             const char* a2 = last ? nA : cA + (size_t)(t + 2) * kstep; const char* b2 = last ? nB : cB + (size_t)(t + 2) * kstep;
;             const char* a3 = a2 + kstep; const char* b3 = b2 + kstep;
;             if (last && has_next) S.a_ready(nxt);
;             if constexpr (SP2) {
;             PG8_LDB(B0, 0, 0); PG8_LDB(B1, 0, 1); PG8_SCHED; PG8_LDA(At, 0, 0); PG8_STAGE(PG8_SA(1, 1), a1 + hstepA, voffA);
;             PG8_WAIT_V(8); PG8_WAIT_L(0); PG8_BAR; PG8_MMA(0, 0, At, B0); PG8_MMA(0, 1, At, B1); PG8_BAR; PG8_SCHED;
;             if constexpr (!HALFU) PG8_LDA(At, 0, 1); PG8_STAGE(PG8_SB(0, 0), b2, voffB); PG8_STAGE(PG8_SB(0, 1), b2 + hstep, voffB); PG8_STAGE(PG8_SA(0, 0), a2, voffA);
;             PG8_WAIT_V(8); PG8_WAIT_L(0); PG8_BAR; if constexpr (!HALFU) { PG8_MMA(1, 0, At, B0); PG8_MMA(1, 1, At, B1); } PG8_BAR; PG8_SCHED;
.LBB0_542:
	s_add_u32 s98, s28, 0x80
	s_addc_u32 s99, s29, 0
	ds_read_b128 v[142:145], v137
	ds_read_b128 v[146:149], v137 offset:1024
	ds_read_b128 v[150:153], v137 offset:2048
	ds_read_b128 v[154:157], v137 offset:3072
	ds_read_b128 v[158:161], v138
	ds_read_b128 v[162:165], v138 offset:1024
	ds_read_b128 v[166:169], v138 offset:2048
	ds_read_b128 v[170:173], v138 offset:3072
	s_add_u32 s30, s28, 0x100
	s_addc_u32 s31, s29, 0
	s_cmp_eq_u32 s61, 12
	s_cselect_b32 s40, s57, s30
	s_cselect_b32 s41, s23, s31
	s_cselect_b32 s38, s58, s59
	s_cselect_b32 s39, s21, s60
	s_add_u32 s36, s40, 0x80
	s_addc_u32 s37, s41, 0
	s_add_u32 s28, s28, 0x40080
	s_addc_u32 s29, s29, 0
	s_add_i32 m0, s45, 0xc000
	ds_read_b128 v[174:177], v139
	ds_read_b128 v[178:181], v139 offset:1024
	ds_read_b128 v[182:185], v139 offset:2048
	ds_read_b128 v[186:189], v139 offset:3072
	ds_read_b128 v[190:193], v139 offset:4096
	ds_read_b128 v[194:197], v139 offset:5120
	ds_read_b128 v[198:201], v139 offset:6144
	ds_read_b128 v[202:205], v139 offset:7168
	global_load_lds_dwordx4 v128, s[28:29]
	s_add_i32 m0, s45, 0xe000
	s_nop 0
	global_load_lds_dwordx4 v130, s[28:29]
	s_mov_b32 m0, s53
	s_nop 0
	global_load_lds_dwordx4 v128, s[98:99]
	s_mov_b32 m0, s54
	s_nop 0
	global_load_lds_dwordx4 v130, s[98:99]
	s_waitcnt vmcnt(8)
	s_waitcnt lgkmcnt(0)
	s_barrier
	s_setprio 1
	s_waitcnt lgkmcnt(0)
	v_mfma_scale_f32_16x16x128_f8f6f4 v[124:127], v[142:149], v[174:181], v[124:127], v140, v140 op_sel_hi:[0,0,0]
	v_mfma_scale_f32_16x16x128_f8f6f4 v[120:123], v[150:157], v[174:181], v[120:123], v140, v140 op_sel_hi:[0,0,0]
	v_mfma_scale_f32_16x16x128_f8f6f4 v[108:111], v[142:149], v[182:189], v[108:111], v140, v140 op_sel_hi:[0,0,0]
	v_mfma_scale_f32_16x16x128_f8f6f4 v[104:107], v[150:157], v[182:189], v[104:107], v140, v140 op_sel_hi:[0,0,0]
	v_mfma_scale_f32_16x16x128_f8f6f4 v[96:99], v[142:149], v[190:197], v[96:99], v140, v140 op_sel_hi:[0,0,0]
	v_mfma_scale_f32_16x16x128_f8f6f4 v[206:209], v[150:157], v[190:197], v[88:91], v140, v140 op_sel_hi:[0,0,0]
	v_mfma_scale_f32_16x16x128_f8f6f4 v[210:213], v[142:149], v[198:205], v[80:83], v140, v140 op_sel_hi:[0,0,0]
	v_mfma_scale_f32_16x16x128_f8f6f4 v[214:217], v[150:157], v[198:205], v[72:75], v140, v140 op_sel_hi:[0,0,0]
	s_setprio 0
	s_setprio 1
	v_mfma_scale_f32_16x16x128_f8f6f4 v[116:119], v[158:165], v[174:181], v[116:119], v140, v140 op_sel_hi:[0,0,0]
	v_mfma_scale_f32_16x16x128_f8f6f4 v[112:115], v[166:173], v[174:181], v[112:115], v140, v140 op_sel_hi:[0,0,0]
	v_mfma_scale_f32_16x16x128_f8f6f4 v[100:103], v[158:165], v[182:189], v[100:103], v140, v140 op_sel_hi:[0,0,0]
	v_mfma_scale_f32_16x16x128_f8f6f4 v[174:177], v[166:173], v[182:189], v[92:95], v140, v140 op_sel_hi:[0,0,0]
	v_mfma_scale_f32_16x16x128_f8f6f4 v[178:181], v[158:165], v[190:197], v[84:87], v140, v140 op_sel_hi:[0,0,0]
	v_mfma_scale_f32_16x16x128_f8f6f4 v[182:185], v[166:173], v[190:197], v[76:79], v140, v140 op_sel_hi:[0,0,0]
	v_mfma_scale_f32_16x16x128_f8f6f4 v[186:189], v[158:165], v[198:205], v[68:71], v140, v140 op_sel_hi:[0,0,0]
	v_mfma_scale_f32_16x16x128_f8f6f4 v[190:193], v[166:173], v[198:205], v[64:67], v140, v140 op_sel_hi:[0,0,0]
	s_setprio 0
	s_barrier
	s_add_i32 s28, s55, s43
	s_mov_b32 m0, s28
	s_nop 1
	ds_read_b128 v[64:67], v139 offset:16384
	ds_read_b128 v[68:71], v139 offset:17408
	ds_read_b128 v[72:75], v139 offset:18432
	ds_read_b128 v[76:79], v139 offset:19456
	ds_read_b128 v[80:83], v139 offset:20480
	ds_read_b128 v[84:87], v139 offset:21504
	ds_read_b128 v[88:91], v139 offset:22528
	ds_read_b128 v[92:95], v139 offset:23552
	global_load_lds_dwordx4 v128, s[38:39]
	s_add_i32 m0, s28, 0x2000
	s_add_u32 s28, s38, 0x40000
	s_addc_u32 s29, s39, 0
	s_add_i32 s62, s56, s43
	global_load_lds_dwordx4 v130, s[38:39]
	s_mov_b32 m0, s62
	s_nop 0
	global_load_lds_dwordx4 v128, s[28:29]
	s_add_i32 m0, s62, 0x2000
	s_nop 0
	global_load_lds_dwordx4 v130, s[28:29]
	s_waitcnt vmcnt(4)
	s_waitcnt lgkmcnt(0)
	s_barrier
	s_setprio 1
	s_waitcnt lgkmcnt(0)
	v_mfma_scale_f32_16x16x128_f8f6f4 v[60:63], v[142:149], v[64:71], v[60:63], v140, v140 op_sel_hi:[0,0,0]
	v_mfma_scale_f32_16x16x128_f8f6f4 v[56:59], v[150:157], v[64:71], v[56:59], v140, v140 op_sel_hi:[0,0,0]
	v_mfma_scale_f32_16x16x128_f8f6f4 v[48:51], v[142:149], v[72:79], v[48:51], v140, v140 op_sel_hi:[0,0,0]
	v_mfma_scale_f32_16x16x128_f8f6f4 v[194:197], v[150:157], v[72:79], v[40:43], v140, v140 op_sel_hi:[0,0,0]
	v_mfma_scale_f32_16x16x128_f8f6f4 v[198:201], v[142:149], v[80:87], v[32:35], v140, v140 op_sel_hi:[0,0,0]
	v_mfma_scale_f32_16x16x128_f8f6f4 v[202:205], v[150:157], v[80:87], v[24:27], v140, v140 op_sel_hi:[0,0,0]
	v_mfma_scale_f32_16x16x128_f8f6f4 v[218:221], v[142:149], v[88:95], v[16:19], v140, v140 op_sel_hi:[0,0,0]
	v_mfma_scale_f32_16x16x128_f8f6f4 v[222:225], v[150:157], v[88:95], v[8:11], v140, v140 op_sel_hi:[0,0,0]
	s_setprio 0
	s_setprio 1
	v_mfma_scale_f32_16x16x128_f8f6f4 v[52:55], v[158:165], v[64:71], v[52:55], v140, v140 op_sel_hi:[0,0,0]
	v_mfma_scale_f32_16x16x128_f8f6f4 v[226:229], v[166:173], v[64:71], v[44:47], v140, v140 op_sel_hi:[0,0,0]
	v_mfma_scale_f32_16x16x128_f8f6f4 v[230:233], v[158:165], v[72:79], v[36:39], v140, v140 op_sel_hi:[0,0,0]
	v_mfma_scale_f32_16x16x128_f8f6f4 v[234:237], v[166:173], v[72:79], v[28:31], v140, v140 op_sel_hi:[0,0,0]
	v_mfma_scale_f32_16x16x128_f8f6f4 v[238:241], v[158:165], v[80:87], v[20:23], v140, v140 op_sel_hi:[0,0,0]
	v_mfma_scale_f32_16x16x128_f8f6f4 v[242:245], v[166:173], v[80:87], v[12:15], v140, v140 op_sel_hi:[0,0,0]
	v_mfma_scale_f32_16x16x128_f8f6f4 v[246:249], v[158:165], v[88:95], v[4:7], v140, v140 op_sel_hi:[0,0,0]
	v_mfma_scale_f32_16x16x128_f8f6f4 v[250:253], v[166:173], v[88:95], v[0:3], v140, v140 op_sel_hi:[0,0,0]
	s_setprio 0
	s_barrier
; #define PG8_WAIT_V(n) asm volatile("s_waitcnt vmcnt(" #n ")" ::: "memory")
; #define PG8_WAIT_L(n) asm volatile("s_waitcnt lgkmcnt(" #n ")" ::: "memory")
; #define PG8_BAR __builtin_amdgcn_s_barrier()
; #define PG8_SCHED __builtin_amdgcn_sched_barrier(0)
;     ...
;             PG8_LDB(B0, 1, 0); PG8_LDB(B1, 1, 1); PG8_SCHED; PG8_LDA(At, 1, 0); PG8_STAGE(PG8_SA(0, 1), a2 + hstepA, voffA);
;             PG8_WAIT_V(8); PG8_WAIT_L(0); PG8_BAR; PG8_MMA(0, 0, At, B0); PG8_MMA(0, 1, At, B1); PG8_BAR; PG8_SCHED;
;             if constexpr (!HALFU) PG8_LDA(At, 1, 1); PG8_STAGE(PG8_SB(1, 0), b3, voffB); PG8_STAGE(PG8_SB(1, 1), b3 + hstep, voffB); PG8_STAGE(PG8_SA(1, 0), a3, voffA);
;             PG8_WAIT_V(8); PG8_WAIT_L(0); PG8_BAR; if constexpr (!HALFU) { PG8_MMA(1, 0, At, B0); PG8_MMA(1, 1, At, B1); } PG8_BAR; PG8_SCHED;
	s_add_i32 s62, 0, 0x18000
	s_add_i32 s63, 0, 0x1c000
	s_nop 0
	v_add_u32_e32 v12, s62, v136
	v_add_u32_e32 v16, s63, v136
	ds_read_b128 v[0:3], v12
	ds_read_b128 v[4:7], v12 offset:1024
	ds_read_b128 v[8:11], v12 offset:2048
	ds_read_b128 v[12:15], v12 offset:3072
	ds_read_b128 v[142:145], v16
	ds_read_b128 v[146:149], v16 offset:1024
	ds_read_b128 v[150:153], v16 offset:2048
	ds_read_b128 v[154:157], v16 offset:3072
	s_add_u32 s28, s40, 0x40000
	s_addc_u32 s29, s41, 0
	s_mov_b32 m0, s47
	ds_read_b128 v[16:19], v139 offset:32768
	ds_read_b128 v[20:23], v139 offset:33792
	ds_read_b128 v[24:27], v139 offset:34816
	ds_read_b128 v[28:31], v139 offset:35840
	ds_read_b128 v[32:35], v139 offset:36864
	ds_read_b128 v[36:39], v139 offset:37888
	ds_read_b128 v[40:43], v139 offset:38912
	ds_read_b128 v[44:47], v139 offset:39936
	global_load_lds_dwordx4 v128, s[28:29]
	s_mov_b32 m0, s48
	s_nop 0
	global_load_lds_dwordx4 v130, s[28:29]
	s_mov_b32 m0, s45
	s_nop 0
	global_load_lds_dwordx4 v128, s[40:41]
	s_mov_b32 m0, s46
	s_nop 0
	global_load_lds_dwordx4 v130, s[40:41]
	s_waitcnt vmcnt(8)
	s_waitcnt lgkmcnt(0)
	s_barrier
	s_setprio 1
	s_waitcnt lgkmcnt(0)
	v_mfma_scale_f32_16x16x128_f8f6f4 v[124:127], v[0:7], v[16:23], v[124:127], v140, v140 op_sel_hi:[0,0,0]
	v_mfma_scale_f32_16x16x128_f8f6f4 v[120:123], v[8:15], v[16:23], v[120:123], v140, v140 op_sel_hi:[0,0,0]
	v_mfma_scale_f32_16x16x128_f8f6f4 v[108:111], v[0:7], v[24:31], v[108:111], v140, v140 op_sel_hi:[0,0,0]
	v_mfma_scale_f32_16x16x128_f8f6f4 v[104:107], v[8:15], v[24:31], v[104:107], v140, v140 op_sel_hi:[0,0,0]
	v_mfma_scale_f32_16x16x128_f8f6f4 v[96:99], v[0:7], v[32:39], v[96:99], v140, v140 op_sel_hi:[0,0,0]
	v_mfma_scale_f32_16x16x128_f8f6f4 v[88:91], v[8:15], v[32:39], v[206:209], v140, v140 op_sel_hi:[0,0,0]
	v_mfma_scale_f32_16x16x128_f8f6f4 v[80:83], v[0:7], v[40:47], v[210:213], v140, v140 op_sel_hi:[0,0,0]
	v_mfma_scale_f32_16x16x128_f8f6f4 v[72:75], v[8:15], v[40:47], v[214:217], v140, v140 op_sel_hi:[0,0,0]
	s_setprio 0
	s_setprio 1
	v_mfma_scale_f32_16x16x128_f8f6f4 v[116:119], v[142:149], v[16:23], v[116:119], v140, v140 op_sel_hi:[0,0,0]
	v_mfma_scale_f32_16x16x128_f8f6f4 v[112:115], v[150:157], v[16:23], v[112:115], v140, v140 op_sel_hi:[0,0,0]
	v_mfma_scale_f32_16x16x128_f8f6f4 v[100:103], v[142:149], v[24:31], v[100:103], v140, v140 op_sel_hi:[0,0,0]
	v_mfma_scale_f32_16x16x128_f8f6f4 v[92:95], v[150:157], v[24:31], v[174:177], v140, v140 op_sel_hi:[0,0,0]
	v_mfma_scale_f32_16x16x128_f8f6f4 v[84:87], v[142:149], v[32:39], v[178:181], v140, v140 op_sel_hi:[0,0,0]
	v_mfma_scale_f32_16x16x128_f8f6f4 v[76:79], v[150:157], v[32:39], v[182:185], v140, v140 op_sel_hi:[0,0,0]
	v_mfma_scale_f32_16x16x128_f8f6f4 v[68:71], v[142:149], v[40:47], v[186:189], v140, v140 op_sel_hi:[0,0,0]
	v_mfma_scale_f32_16x16x128_f8f6f4 v[64:67], v[150:157], v[40:47], v[190:193], v140, v140 op_sel_hi:[0,0,0]
	s_setprio 0
	s_barrier
	s_add_u32 s28, s38, 0x80
	s_addc_u32 s29, s39, 0
	s_add_i32 s40, s62, s43
	s_mov_b32 m0, s40
	ds_read_b128 v[158:161], v139 offset:49152
	ds_read_b128 v[162:165], v139 offset:50176
	ds_read_b128 v[166:169], v139 offset:51200
	ds_read_b128 v[170:173], v139 offset:52224
	ds_read_b128 v[174:177], v139 offset:53248
	ds_read_b128 v[178:181], v139 offset:54272
	ds_read_b128 v[182:185], v139 offset:55296
	ds_read_b128 v[186:189], v139 offset:56320
	global_load_lds_dwordx4 v128, s[28:29]
	s_add_i32 m0, s40, 0x2000
	v_lshl_add_u64 v[16:17], s[28:29], 0, v[130:131]
	s_add_u32 s28, s38, 0x40080
	s_addc_u32 s29, s39, 0
	s_add_i32 s38, s63, s43
	global_load_lds_dwordx4 v[16:17], off
	s_mov_b32 m0, s38
	s_nop 0
	global_load_lds_dwordx4 v128, s[28:29]
	s_add_i32 m0, s38, 0x2000
	s_nop 0
	global_load_lds_dwordx4 v130, s[28:29]
	s_waitcnt vmcnt(4)
	s_waitcnt lgkmcnt(0)
	s_barrier
	s_setprio 1
	s_waitcnt lgkmcnt(0)
	v_mfma_scale_f32_16x16x128_f8f6f4 v[60:63], v[0:7], v[158:165], v[60:63], v140, v140 op_sel_hi:[0,0,0]
	v_mfma_scale_f32_16x16x128_f8f6f4 v[56:59], v[8:15], v[158:165], v[56:59], v140, v140 op_sel_hi:[0,0,0]
	v_mfma_scale_f32_16x16x128_f8f6f4 v[48:51], v[0:7], v[166:173], v[48:51], v140, v140 op_sel_hi:[0,0,0]
	v_mfma_scale_f32_16x16x128_f8f6f4 v[40:43], v[8:15], v[166:173], v[194:197], v140, v140 op_sel_hi:[0,0,0]
	v_mfma_scale_f32_16x16x128_f8f6f4 v[32:35], v[0:7], v[174:181], v[198:201], v140, v140 op_sel_hi:[0,0,0]
	v_mfma_scale_f32_16x16x128_f8f6f4 v[24:27], v[8:15], v[174:181], v[202:205], v140, v140 op_sel_hi:[0,0,0]
	v_mfma_scale_f32_16x16x128_f8f6f4 v[16:19], v[0:7], v[182:189], v[218:221], v140, v140 op_sel_hi:[0,0,0]
	v_mfma_scale_f32_16x16x128_f8f6f4 v[8:11], v[8:15], v[182:189], v[222:225], v140, v140 op_sel_hi:[0,0,0]
	s_setprio 0
	s_setprio 1
	v_mfma_scale_f32_16x16x128_f8f6f4 v[52:55], v[142:149], v[158:165], v[52:55], v140, v140 op_sel_hi:[0,0,0]
	v_mfma_scale_f32_16x16x128_f8f6f4 v[44:47], v[150:157], v[158:165], v[226:229], v140, v140 op_sel_hi:[0,0,0]
	v_mfma_scale_f32_16x16x128_f8f6f4 v[36:39], v[142:149], v[166:173], v[230:233], v140, v140 op_sel_hi:[0,0,0]
	v_mfma_scale_f32_16x16x128_f8f6f4 v[28:31], v[150:157], v[166:173], v[234:237], v140, v140 op_sel_hi:[0,0,0]
	v_mfma_scale_f32_16x16x128_f8f6f4 v[20:23], v[142:149], v[174:181], v[238:241], v140, v140 op_sel_hi:[0,0,0]
	v_mfma_scale_f32_16x16x128_f8f6f4 v[12:15], v[150:157], v[174:181], v[242:245], v140, v140 op_sel_hi:[0,0,0]
	v_mfma_scale_f32_16x16x128_f8f6f4 v[4:7], v[142:149], v[182:189], v[246:249], v140, v140 op_sel_hi:[0,0,0]
	v_mfma_scale_f32_16x16x128_f8f6f4 v[0:3], v[150:157], v[182:189], v[250:253], v140, v140 op_sel_hi:[0,0,0]
	s_setprio 0
	s_barrier
	s_add_i32 s61, s61, 2
	s_add_u32 s59, s59, 0x100
	s_addc_u32 s60, s60, 0
	s_cmp_gt_u32 s61, 13
	s_mov_b64 s[28:29], s[30:31]
	s_cbranch_scc0 .LBB0_542
	s_and_b64 vcc, exec, s[6:7]
	s_cbranch_vccz .LBB0_545
	s_barrier

; #define PG8_WAIT_V(n) asm volatile("s_waitcnt vmcnt(" #n ")" ::: "memory")
; #define PG8_WAIT_L(n) asm volatile("s_waitcnt lgkmcnt(" #n ")" ::: "memory")
; #define PG8_BAR __builtin_amdgcn_s_barrier()
; #define PG8_SCHED __builtin_amdgcn_sched_barrier(0)
;     ...
;             const char* a1 = cA + (size_t)(t + 1) * kstep;
;             const char* a2 = last ? nA : cA + (size_t)(t + 2) * kstep; const char* b2 = last ? nB : cB + (size_t)(t + 2) * kstep;
;             const char* a3 = a2 + kstep; const char* b3 = b2 + kstep;
;             if (last && has_next) S.a_ready(nxt);
;             if constexpr (SP2) {
;             PG8_LDB(B0, 0, 0); PG8_LDB(B1, 0, 1); PG8_SCHED; PG8_LDA(At, 0, 0); PG8_STAGE(PG8_SA(1, 1), a1 + hstepA, voffA);
;             PG8_WAIT_V(8); PG8_WAIT_L(0); PG8_BAR; PG8_MMA(0, 0, At, B0); PG8_MMA(0, 1, At, B1); PG8_BAR; PG8_SCHED;
;             if constexpr (!HALFU) PG8_LDA(At, 0, 1); PG8_STAGE(PG8_SB(0, 0), b2, voffB); PG8_STAGE(PG8_SB(0, 1), b2 + hstep, voffB); PG8_STAGE(PG8_SA(0, 0), a2, voffA);
;             PG8_WAIT_V(8); PG8_WAIT_L(0); PG8_BAR; if constexpr (!HALFU) { PG8_MMA(1, 0, At, B0); PG8_MMA(1, 1, At, B1); } PG8_BAR; PG8_SCHED;
.LBB0_670:
	s_add_u32 s98, s18, 0x80
	s_addc_u32 s99, s19, 0
	ds_read_b128 v[144:147], v141
	ds_read_b128 v[148:151], v141 offset:1024
	ds_read_b128 v[152:155], v141 offset:2048
	ds_read_b128 v[156:159], v141 offset:3072
	ds_read_b128 v[160:163], v142
	ds_read_b128 v[164:167], v142 offset:1024
	ds_read_b128 v[168:171], v142 offset:2048
	ds_read_b128 v[172:175], v142 offset:3072
	s_add_u32 s20, s18, 0x100
	s_addc_u32 s21, s19, 0
	s_cmp_eq_u32 s53, 60
	s_cselect_b32 s26, s49, s20
	s_cselect_b32 s27, s11, s21
	s_cselect_b32 s24, s50, s51
	s_cselect_b32 s25, s9, s52
	s_add_u32 s22, s26, 0x80
	s_addc_u32 s23, s27, 0
	s_add_u32 s18, s18, 0x100080
	s_addc_u32 s19, s19, 0
	s_add_i32 m0, s17, 0xc000
	ds_read_b128 v[176:179], v143
	ds_read_b128 v[180:183], v143 offset:1024
	ds_read_b128 v[184:187], v143 offset:2048
	ds_read_b128 v[188:191], v143 offset:3072
	ds_read_b128 v[192:195], v143 offset:4096
	ds_read_b128 v[196:199], v143 offset:5120
	ds_read_b128 v[200:203], v143 offset:6144
	ds_read_b128 v[204:207], v143 offset:7168
	global_load_lds_dwordx4 v134, s[18:19]
	s_add_i32 m0, s17, 0xe000
	s_nop 0
	global_load_lds_dwordx4 v132, s[18:19]
	s_mov_b32 m0, s43
	s_nop 0
	global_load_lds_dwordx4 v134, s[98:99]
	s_mov_b32 m0, s44
	s_nop 0
	global_load_lds_dwordx4 v132, s[98:99]
	s_waitcnt vmcnt(8)
	s_waitcnt lgkmcnt(0)
	s_barrier
	s_setprio 1
	s_waitcnt lgkmcnt(0)
	v_mfma_f32_16x16x32_bf16 v[124:127], v[144:147], v[176:179], v[124:127]
	v_mfma_f32_16x16x32_bf16 v[120:123], v[152:155], v[176:179], v[120:123]
	v_mfma_f32_16x16x32_bf16 v[108:111], v[144:147], v[184:187], v[108:111]
	v_mfma_f32_16x16x32_bf16 v[104:107], v[152:155], v[184:187], v[104:107]
	v_mfma_f32_16x16x32_bf16 v[92:95], v[144:147], v[192:195], v[92:95]
	v_mfma_f32_16x16x32_bf16 v[88:91], v[152:155], v[192:195], v[88:91]
	v_mfma_f32_16x16x32_bf16 v[76:79], v[144:147], v[200:203], v[76:79]
	v_mfma_f32_16x16x32_bf16 v[72:75], v[152:155], v[200:203], v[72:75]
	v_mfma_f32_16x16x32_bf16 v[124:127], v[148:151], v[180:183], v[124:127]
	v_mfma_f32_16x16x32_bf16 v[120:123], v[156:159], v[180:183], v[120:123]
	v_mfma_f32_16x16x32_bf16 v[108:111], v[148:151], v[188:191], v[108:111]
	v_mfma_f32_16x16x32_bf16 v[104:107], v[156:159], v[188:191], v[104:107]
	v_mfma_f32_16x16x32_bf16 v[92:95], v[148:151], v[196:199], v[92:95]
	v_mfma_f32_16x16x32_bf16 v[88:91], v[156:159], v[196:199], v[88:91]
	v_mfma_f32_16x16x32_bf16 v[76:79], v[148:151], v[204:207], v[76:79]
	v_mfma_f32_16x16x32_bf16 v[72:75], v[156:159], v[204:207], v[72:75]
	s_setprio 0
	s_setprio 1
	v_mfma_f32_16x16x32_bf16 v[116:119], v[160:163], v[176:179], v[116:119]
	v_mfma_f32_16x16x32_bf16 v[112:115], v[168:171], v[176:179], v[112:115]
	v_mfma_f32_16x16x32_bf16 v[100:103], v[160:163], v[184:187], v[100:103]
	v_mfma_f32_16x16x32_bf16 v[96:99], v[168:171], v[184:187], v[96:99]
	v_mfma_f32_16x16x32_bf16 v[84:87], v[160:163], v[192:195], v[84:87]
	v_mfma_f32_16x16x32_bf16 v[80:83], v[168:171], v[192:195], v[80:83]
	v_mfma_f32_16x16x32_bf16 v[68:71], v[160:163], v[200:203], v[68:71]
	v_mfma_f32_16x16x32_bf16 v[64:67], v[168:171], v[200:203], v[64:67]
	v_mfma_f32_16x16x32_bf16 v[116:119], v[164:167], v[180:183], v[116:119]
	v_mfma_f32_16x16x32_bf16 v[112:115], v[172:175], v[180:183], v[112:115]
	v_mfma_f32_16x16x32_bf16 v[100:103], v[164:167], v[188:191], v[100:103]
	v_mfma_f32_16x16x32_bf16 v[96:99], v[172:175], v[188:191], v[96:99]
	v_mfma_f32_16x16x32_bf16 v[84:87], v[164:167], v[196:199], v[84:87]
	v_mfma_f32_16x16x32_bf16 v[80:83], v[172:175], v[196:199], v[80:83]
	v_mfma_f32_16x16x32_bf16 v[68:71], v[164:167], v[204:207], v[68:71]
	v_mfma_f32_16x16x32_bf16 v[64:67], v[172:175], v[204:207], v[64:67]
	s_setprio 0
	s_barrier
	s_add_i32 s18, s45, s30
	s_mov_b32 m0, s18
	ds_read_b128 v[176:179], v143 offset:16384
	ds_read_b128 v[180:183], v143 offset:17408
	ds_read_b128 v[184:187], v143 offset:18432
	ds_read_b128 v[188:191], v143 offset:19456
	ds_read_b128 v[192:195], v143 offset:20480
	ds_read_b128 v[196:199], v143 offset:21504
	ds_read_b128 v[200:203], v143 offset:22528
	ds_read_b128 v[204:207], v143 offset:23552
	global_load_lds_dwordx4 v128, s[24:25]
	s_add_i32 m0, s18, 0x2000
	s_add_u32 s18, s24, 0x100000
	s_addc_u32 s19, s25, 0
	s_add_i32 s54, s46, s30
	global_load_lds_dwordx4 v130, s[24:25]
	s_mov_b32 m0, s54
	s_nop 0
	global_load_lds_dwordx4 v128, s[18:19]
	s_add_i32 m0, s54, 0x2000
	s_nop 0
	global_load_lds_dwordx4 v130, s[18:19]
	s_waitcnt vmcnt(4)
	s_waitcnt lgkmcnt(0)
	s_barrier
	s_setprio 1
	s_waitcnt lgkmcnt(0)
	v_mfma_f32_16x16x32_bf16 v[60:63], v[144:147], v[176:179], v[60:63]
	v_mfma_f32_16x16x32_bf16 v[56:59], v[152:155], v[176:179], v[56:59]
	v_mfma_f32_16x16x32_bf16 v[44:47], v[144:147], v[184:187], v[44:47]
	v_mfma_f32_16x16x32_bf16 v[40:43], v[152:155], v[184:187], v[40:43]
	v_mfma_f32_16x16x32_bf16 v[28:31], v[144:147], v[192:195], v[28:31]
	v_mfma_f32_16x16x32_bf16 v[24:27], v[152:155], v[192:195], v[24:27]
	v_mfma_f32_16x16x32_bf16 v[12:15], v[144:147], v[200:203], v[12:15]
	v_mfma_f32_16x16x32_bf16 v[8:11], v[152:155], v[200:203], v[8:11]
	v_mfma_f32_16x16x32_bf16 v[60:63], v[148:151], v[180:183], v[60:63]
	v_mfma_f32_16x16x32_bf16 v[56:59], v[156:159], v[180:183], v[56:59]
	v_mfma_f32_16x16x32_bf16 v[44:47], v[148:151], v[188:191], v[44:47]
	v_mfma_f32_16x16x32_bf16 v[40:43], v[156:159], v[188:191], v[40:43]
	v_mfma_f32_16x16x32_bf16 v[28:31], v[148:151], v[196:199], v[28:31]
	v_mfma_f32_16x16x32_bf16 v[24:27], v[156:159], v[196:199], v[24:27]
	v_mfma_f32_16x16x32_bf16 v[12:15], v[148:151], v[204:207], v[12:15]
	v_mfma_f32_16x16x32_bf16 v[8:11], v[156:159], v[204:207], v[8:11]
	s_setprio 0
	s_setprio 1
	v_mfma_f32_16x16x32_bf16 v[52:55], v[160:163], v[176:179], v[52:55]
	v_mfma_f32_16x16x32_bf16 v[48:51], v[168:171], v[176:179], v[48:51]
	v_mfma_f32_16x16x32_bf16 v[36:39], v[160:163], v[184:187], v[36:39]
	v_mfma_f32_16x16x32_bf16 v[32:35], v[168:171], v[184:187], v[32:35]
	v_mfma_f32_16x16x32_bf16 v[20:23], v[160:163], v[192:195], v[20:23]
	v_mfma_f32_16x16x32_bf16 v[16:19], v[168:171], v[192:195], v[16:19]
	v_mfma_f32_16x16x32_bf16 v[4:7], v[160:163], v[200:203], v[4:7]
	v_mfma_f32_16x16x32_bf16 v[0:3], v[168:171], v[200:203], v[0:3]
	v_mfma_f32_16x16x32_bf16 v[52:55], v[164:167], v[180:183], v[52:55]
	v_mfma_f32_16x16x32_bf16 v[48:51], v[172:175], v[180:183], v[48:51]
	v_mfma_f32_16x16x32_bf16 v[36:39], v[164:167], v[188:191], v[36:39]
	v_mfma_f32_16x16x32_bf16 v[32:35], v[172:175], v[188:191], v[32:35]
	v_mfma_f32_16x16x32_bf16 v[20:23], v[164:167], v[196:199], v[20:23]
	v_mfma_f32_16x16x32_bf16 v[16:19], v[172:175], v[196:199], v[16:19]
	v_mfma_f32_16x16x32_bf16 v[4:7], v[164:167], v[204:207], v[4:7]
	v_mfma_f32_16x16x32_bf16 v[0:3], v[172:175], v[204:207], v[0:3]
	s_setprio 0
	s_barrier
; #define PG8_WAIT_V(n) asm volatile("s_waitcnt vmcnt(" #n ")" ::: "memory")
; #define PG8_WAIT_L(n) asm volatile("s_waitcnt lgkmcnt(" #n ")" ::: "memory")
; #define PG8_BAR __builtin_amdgcn_s_barrier()
; #define PG8_SCHED __builtin_amdgcn_sched_barrier(0)
;     ...
;             PG8_LDB(B0, 1, 0); PG8_LDB(B1, 1, 1); PG8_SCHED; PG8_LDA(At, 1, 0); PG8_STAGE(PG8_SA(0, 1), a2 + hstepA, voffA);
;             PG8_WAIT_V(8); PG8_WAIT_L(0); PG8_BAR; PG8_MMA(0, 0, At, B0); PG8_MMA(0, 1, At, B1); PG8_BAR; PG8_SCHED;
;             if constexpr (!HALFU) PG8_LDA(At, 1, 1); PG8_STAGE(PG8_SB(1, 0), b3, voffB); PG8_STAGE(PG8_SB(1, 1), b3 + hstep, voffB); PG8_STAGE(PG8_SA(1, 0), a3, voffA);
;             PG8_WAIT_V(8); PG8_WAIT_L(0); PG8_BAR; if constexpr (!HALFU) { PG8_MMA(1, 0, At, B0); PG8_MMA(1, 1, At, B1); } PG8_BAR; PG8_SCHED;
	s_add_i32 s54, 0, 0x18000
	s_add_i32 s55, 0, 0x1c000
	v_add_u32_e32 v156, s54, v140
	v_add_u32_e32 v172, s55, v140
	ds_read_b128 v[144:147], v156
	ds_read_b128 v[148:151], v156 offset:1024
	ds_read_b128 v[152:155], v156 offset:2048
	ds_read_b128 v[156:159], v156 offset:3072
	ds_read_b128 v[160:163], v172
	ds_read_b128 v[164:167], v172 offset:1024
	ds_read_b128 v[168:171], v172 offset:2048
	ds_read_b128 v[172:175], v172 offset:3072
	s_add_u32 s18, s26, 0x100000
	s_addc_u32 s19, s27, 0
	s_mov_b32 m0, s37
	ds_read_b128 v[176:179], v143 offset:32768
	ds_read_b128 v[180:183], v143 offset:33792
	ds_read_b128 v[184:187], v143 offset:34816
	ds_read_b128 v[188:191], v143 offset:35840
	ds_read_b128 v[192:195], v143 offset:36864
	ds_read_b128 v[196:199], v143 offset:37888
	ds_read_b128 v[200:203], v143 offset:38912
	ds_read_b128 v[204:207], v143 offset:39936
	global_load_lds_dwordx4 v134, s[18:19]
	s_mov_b32 m0, s38
	s_nop 0
	global_load_lds_dwordx4 v132, s[18:19]
	s_mov_b32 m0, s17
	s_nop 0
	global_load_lds_dwordx4 v134, s[26:27]
	s_mov_b32 m0, s36
	s_nop 0
	global_load_lds_dwordx4 v132, s[26:27]
	s_waitcnt vmcnt(8)
	s_waitcnt lgkmcnt(0)
	s_barrier
	s_setprio 1
	s_waitcnt lgkmcnt(0)
	v_mfma_f32_16x16x32_bf16 v[124:127], v[144:147], v[176:179], v[124:127]
	v_mfma_f32_16x16x32_bf16 v[120:123], v[152:155], v[176:179], v[120:123]
	v_mfma_f32_16x16x32_bf16 v[108:111], v[144:147], v[184:187], v[108:111]
	v_mfma_f32_16x16x32_bf16 v[104:107], v[152:155], v[184:187], v[104:107]
	v_mfma_f32_16x16x32_bf16 v[92:95], v[144:147], v[192:195], v[92:95]
	v_mfma_f32_16x16x32_bf16 v[88:91], v[152:155], v[192:195], v[88:91]
	v_mfma_f32_16x16x32_bf16 v[76:79], v[144:147], v[200:203], v[76:79]
	v_mfma_f32_16x16x32_bf16 v[72:75], v[152:155], v[200:203], v[72:75]
	v_mfma_f32_16x16x32_bf16 v[124:127], v[148:151], v[180:183], v[124:127]
	v_mfma_f32_16x16x32_bf16 v[120:123], v[156:159], v[180:183], v[120:123]
	v_mfma_f32_16x16x32_bf16 v[108:111], v[148:151], v[188:191], v[108:111]
	v_mfma_f32_16x16x32_bf16 v[104:107], v[156:159], v[188:191], v[104:107]
	v_mfma_f32_16x16x32_bf16 v[92:95], v[148:151], v[196:199], v[92:95]
	v_mfma_f32_16x16x32_bf16 v[88:91], v[156:159], v[196:199], v[88:91]
	v_mfma_f32_16x16x32_bf16 v[76:79], v[148:151], v[204:207], v[76:79]
	v_mfma_f32_16x16x32_bf16 v[72:75], v[156:159], v[204:207], v[72:75]
	s_setprio 0
	s_setprio 1
	v_mfma_f32_16x16x32_bf16 v[116:119], v[160:163], v[176:179], v[116:119]
	v_mfma_f32_16x16x32_bf16 v[112:115], v[168:171], v[176:179], v[112:115]
	v_mfma_f32_16x16x32_bf16 v[100:103], v[160:163], v[184:187], v[100:103]
	v_mfma_f32_16x16x32_bf16 v[96:99], v[168:171], v[184:187], v[96:99]
	v_mfma_f32_16x16x32_bf16 v[84:87], v[160:163], v[192:195], v[84:87]
	v_mfma_f32_16x16x32_bf16 v[80:83], v[168:171], v[192:195], v[80:83]
	v_mfma_f32_16x16x32_bf16 v[68:71], v[160:163], v[200:203], v[68:71]
	v_mfma_f32_16x16x32_bf16 v[64:67], v[168:171], v[200:203], v[64:67]
	v_mfma_f32_16x16x32_bf16 v[116:119], v[164:167], v[180:183], v[116:119]
	v_mfma_f32_16x16x32_bf16 v[112:115], v[172:175], v[180:183], v[112:115]
	v_mfma_f32_16x16x32_bf16 v[100:103], v[164:167], v[188:191], v[100:103]
	v_mfma_f32_16x16x32_bf16 v[96:99], v[172:175], v[188:191], v[96:99]
	v_mfma_f32_16x16x32_bf16 v[84:87], v[164:167], v[196:199], v[84:87]
	v_mfma_f32_16x16x32_bf16 v[80:83], v[172:175], v[196:199], v[80:83]
	v_mfma_f32_16x16x32_bf16 v[68:71], v[164:167], v[204:207], v[68:71]
	v_mfma_f32_16x16x32_bf16 v[64:67], v[172:175], v[204:207], v[64:67]
	s_setprio 0
	s_barrier
	s_add_u32 s18, s24, 0x80
	s_addc_u32 s19, s25, 0
	s_add_i32 s26, s54, s30
	s_mov_b32 m0, s26
	ds_read_b128 v[176:179], v143 offset:49152
	ds_read_b128 v[180:183], v143 offset:50176
	ds_read_b128 v[184:187], v143 offset:51200
	ds_read_b128 v[188:191], v143 offset:52224
	ds_read_b128 v[192:195], v143 offset:53248
	ds_read_b128 v[196:199], v143 offset:54272
	ds_read_b128 v[200:203], v143 offset:55296
	ds_read_b128 v[204:207], v143 offset:56320
	global_load_lds_dwordx4 v128, s[18:19]
	s_add_i32 m0, s26, 0x2000
	v_lshl_add_u64 v[208:209], s[18:19], 0, v[130:131]
	s_add_u32 s18, s24, 0x100080
	s_addc_u32 s19, s25, 0
	s_add_i32 s24, s55, s30
	global_load_lds_dwordx4 v[208:209], off
	s_mov_b32 m0, s24
	s_nop 0
	global_load_lds_dwordx4 v128, s[18:19]
	s_add_i32 m0, s24, 0x2000
	s_nop 0
	global_load_lds_dwordx4 v130, s[18:19]
	s_waitcnt vmcnt(4)
	s_waitcnt lgkmcnt(0)
	s_barrier
	s_setprio 1
	s_waitcnt lgkmcnt(0)
	v_mfma_f32_16x16x32_bf16 v[60:63], v[144:147], v[176:179], v[60:63]
	v_mfma_f32_16x16x32_bf16 v[56:59], v[152:155], v[176:179], v[56:59]
	v_mfma_f32_16x16x32_bf16 v[44:47], v[144:147], v[184:187], v[44:47]
	v_mfma_f32_16x16x32_bf16 v[40:43], v[152:155], v[184:187], v[40:43]
	v_mfma_f32_16x16x32_bf16 v[28:31], v[144:147], v[192:195], v[28:31]
	v_mfma_f32_16x16x32_bf16 v[24:27], v[152:155], v[192:195], v[24:27]
	v_mfma_f32_16x16x32_bf16 v[12:15], v[144:147], v[200:203], v[12:15]
	v_mfma_f32_16x16x32_bf16 v[8:11], v[152:155], v[200:203], v[8:11]
	v_mfma_f32_16x16x32_bf16 v[60:63], v[148:151], v[180:183], v[60:63]
	v_mfma_f32_16x16x32_bf16 v[56:59], v[156:159], v[180:183], v[56:59]
	v_mfma_f32_16x16x32_bf16 v[44:47], v[148:151], v[188:191], v[44:47]
	v_mfma_f32_16x16x32_bf16 v[40:43], v[156:159], v[188:191], v[40:43]
	v_mfma_f32_16x16x32_bf16 v[28:31], v[148:151], v[196:199], v[28:31]
	v_mfma_f32_16x16x32_bf16 v[24:27], v[156:159], v[196:199], v[24:27]
	v_mfma_f32_16x16x32_bf16 v[12:15], v[148:151], v[204:207], v[12:15]
	v_mfma_f32_16x16x32_bf16 v[8:11], v[156:159], v[204:207], v[8:11]
	s_setprio 0
	s_setprio 1
	v_mfma_f32_16x16x32_bf16 v[52:55], v[160:163], v[176:179], v[52:55]
	v_mfma_f32_16x16x32_bf16 v[48:51], v[168:171], v[176:179], v[48:51]
	v_mfma_f32_16x16x32_bf16 v[36:39], v[160:163], v[184:187], v[36:39]
	v_mfma_f32_16x16x32_bf16 v[32:35], v[168:171], v[184:187], v[32:35]
	v_mfma_f32_16x16x32_bf16 v[20:23], v[160:163], v[192:195], v[20:23]
	v_mfma_f32_16x16x32_bf16 v[16:19], v[168:171], v[192:195], v[16:19]
	v_mfma_f32_16x16x32_bf16 v[4:7], v[160:163], v[200:203], v[4:7]
	v_mfma_f32_16x16x32_bf16 v[0:3], v[168:171], v[200:203], v[0:3]
	v_mfma_f32_16x16x32_bf16 v[52:55], v[164:167], v[180:183], v[52:55]
	v_mfma_f32_16x16x32_bf16 v[48:51], v[172:175], v[180:183], v[48:51]
	v_mfma_f32_16x16x32_bf16 v[36:39], v[164:167], v[188:191], v[36:39]
	v_mfma_f32_16x16x32_bf16 v[32:35], v[172:175], v[188:191], v[32:35]
	v_mfma_f32_16x16x32_bf16 v[20:23], v[164:167], v[196:199], v[20:23]
	v_mfma_f32_16x16x32_bf16 v[16:19], v[172:175], v[196:199], v[16:19]
	v_mfma_f32_16x16x32_bf16 v[4:7], v[164:167], v[204:207], v[4:7]
	v_mfma_f32_16x16x32_bf16 v[0:3], v[172:175], v[204:207], v[0:3]
	s_setprio 0
	s_barrier
	s_add_i32 s53, s53, 2
	s_add_u32 s51, s51, 0x100
	s_addc_u32 s52, s52, 0
	s_cmp_gt_u32 s53, 61
	s_mov_b64 s[18:19], s[20:21]
	s_cbranch_scc0 .LBB0_670
	s_and_b64 vcc, exec, s[6:7]
	s_cbranch_vccz .LBB0_673
	s_barrier

; #define PG8_WAIT_V(n) asm volatile("s_waitcnt vmcnt(" #n ")" ::: "memory")
; #define PG8_WAIT_L(n) asm volatile("s_waitcnt lgkmcnt(" #n ")" ::: "memory")
; #define PG8_BAR __builtin_amdgcn_s_barrier()
; #define PG8_SCHED __builtin_amdgcn_sched_barrier(0)
;     ...
;             const char* a1 = cA + (size_t)(t + 1) * kstep;
;             const char* a2 = last ? nA : cA + (size_t)(t + 2) * kstep; const char* b2 = last ? nB : cB + (size_t)(t + 2) * kstep;
;             const char* a3 = a2 + kstep; const char* b3 = b2 + kstep;
;             if (last && has_next) S.a_ready(nxt);
;             if constexpr (SP2) {
;             PG8_LDB(B0, 0, 0); PG8_LDB(B1, 0, 1); PG8_SCHED; PG8_LDA(At, 0, 0); PG8_STAGE(PG8_SA(1, 1), a1 + hstepA, voffA);
;             PG8_WAIT_V(8); PG8_WAIT_L(0); PG8_BAR; PG8_MMA(0, 0, At, B0); PG8_MMA(0, 1, At, B1); PG8_BAR; PG8_SCHED;
;             if constexpr (!HALFU) PG8_LDA(At, 0, 1); PG8_STAGE(PG8_SB(0, 0), b2, voffB); PG8_STAGE(PG8_SB(0, 1), b2 + hstep, voffB); PG8_STAGE(PG8_SA(0, 0), a2, voffA);
;             PG8_WAIT_V(8); PG8_WAIT_L(0); PG8_BAR; if constexpr (!HALFU) { PG8_MMA(1, 0, At, B0); PG8_MMA(1, 1, At, B1); } PG8_BAR; PG8_SCHED;
.LBB0_793:
	s_add_u32 s98, s10, 0x80
	s_addc_u32 s99, s11, 0
	ds_read_b128 v[140:143], v137
	ds_read_b128 v[144:147], v137 offset:1024
	ds_read_b128 v[148:151], v137 offset:2048
	ds_read_b128 v[152:155], v137 offset:3072
	ds_read_b128 v[156:159], v138
	ds_read_b128 v[160:163], v138 offset:1024
	ds_read_b128 v[164:167], v138 offset:2048
	ds_read_b128 v[168:171], v138 offset:3072
	s_add_u32 s22, s10, 0x100
	s_addc_u32 s23, s11, 0
	s_cmpk_eq_i32 s54, 0xa8
	s_cselect_b32 s28, s6, s22
	s_cselect_b32 s29, s7, s23
	s_cselect_b32 s26, s20, s52
	s_cselect_b32 s27, s21, s53
	s_add_u32 s24, s28, 0x80
	s_addc_u32 s25, s29, 0
	s_add_u32 s10, s10, 0x2b0080
	s_addc_u32 s11, s11, 0
	s_add_i32 m0, s36, 0xc000
	ds_read_b128 v[172:175], v139
	ds_read_b128 v[176:179], v139 offset:1024
	ds_read_b128 v[180:183], v139 offset:2048
	ds_read_b128 v[184:187], v139 offset:3072
	ds_read_b128 v[188:191], v139 offset:4096
	ds_read_b128 v[192:195], v139 offset:5120
	ds_read_b128 v[196:199], v139 offset:6144
	ds_read_b128 v[200:203], v139 offset:7168
	global_load_lds_dwordx4 v128, s[10:11]
	s_add_i32 m0, s36, 0xe000
	s_nop 0
	global_load_lds_dwordx4 v130, s[10:11]
	s_mov_b32 m0, s43
	s_nop 0
	global_load_lds_dwordx4 v128, s[98:99]
	s_mov_b32 m0, s44
	s_nop 0
	global_load_lds_dwordx4 v130, s[98:99]
	s_waitcnt vmcnt(8)
	s_waitcnt lgkmcnt(0)
	s_barrier
	s_setprio 1
	s_waitcnt lgkmcnt(0)
	v_mfma_f32_16x16x32_bf16 v[124:127], v[140:143], v[172:175], v[124:127]
	v_mfma_f32_16x16x32_bf16 v[120:123], v[148:151], v[172:175], v[120:123]
	v_mfma_f32_16x16x32_bf16 v[112:115], v[140:143], v[180:183], v[112:115]
	v_mfma_f32_16x16x32_bf16 v[104:107], v[148:151], v[180:183], v[104:107]
	v_mfma_f32_16x16x32_bf16 v[96:99], v[140:143], v[188:191], v[96:99]
	v_mfma_f32_16x16x32_bf16 v[88:91], v[148:151], v[188:191], v[88:91]
	v_mfma_f32_16x16x32_bf16 v[80:83], v[140:143], v[196:199], v[80:83]
	v_mfma_f32_16x16x32_bf16 v[72:75], v[148:151], v[196:199], v[72:75]
	v_mfma_f32_16x16x32_bf16 v[124:127], v[144:147], v[176:179], v[124:127]
	v_mfma_f32_16x16x32_bf16 v[120:123], v[152:155], v[176:179], v[120:123]
	v_mfma_f32_16x16x32_bf16 v[112:115], v[144:147], v[184:187], v[112:115]
	v_mfma_f32_16x16x32_bf16 v[104:107], v[152:155], v[184:187], v[104:107]
	v_mfma_f32_16x16x32_bf16 v[96:99], v[144:147], v[192:195], v[96:99]
	v_mfma_f32_16x16x32_bf16 v[88:91], v[152:155], v[192:195], v[88:91]
	v_mfma_f32_16x16x32_bf16 v[80:83], v[144:147], v[200:203], v[80:83]
	v_mfma_f32_16x16x32_bf16 v[72:75], v[152:155], v[200:203], v[72:75]
	s_setprio 0
	s_setprio 1
	v_mfma_f32_16x16x32_bf16 v[116:119], v[156:159], v[172:175], v[116:119]
	v_mfma_f32_16x16x32_bf16 v[108:111], v[164:167], v[172:175], v[108:111]
	v_mfma_f32_16x16x32_bf16 v[100:103], v[156:159], v[180:183], v[100:103]
	v_mfma_f32_16x16x32_bf16 v[92:95], v[164:167], v[180:183], v[92:95]
	v_mfma_f32_16x16x32_bf16 v[84:87], v[156:159], v[188:191], v[84:87]
	v_mfma_f32_16x16x32_bf16 v[76:79], v[164:167], v[188:191], v[76:79]
	v_mfma_f32_16x16x32_bf16 v[68:71], v[156:159], v[196:199], v[68:71]
	v_mfma_f32_16x16x32_bf16 v[64:67], v[164:167], v[196:199], v[64:67]
	v_mfma_f32_16x16x32_bf16 v[116:119], v[160:163], v[176:179], v[116:119]
	v_mfma_f32_16x16x32_bf16 v[108:111], v[168:171], v[176:179], v[108:111]
	v_mfma_f32_16x16x32_bf16 v[100:103], v[160:163], v[184:187], v[100:103]
	v_mfma_f32_16x16x32_bf16 v[92:95], v[168:171], v[184:187], v[92:95]
	v_mfma_f32_16x16x32_bf16 v[84:87], v[160:163], v[192:195], v[84:87]
	v_mfma_f32_16x16x32_bf16 v[76:79], v[168:171], v[192:195], v[76:79]
	v_mfma_f32_16x16x32_bf16 v[68:71], v[160:163], v[200:203], v[68:71]
	v_mfma_f32_16x16x32_bf16 v[64:67], v[168:171], v[200:203], v[64:67]
	s_setprio 0
	s_barrier
	s_add_i32 s10, s46, s31
	s_mov_b32 m0, s10
	ds_read_b128 v[172:175], v139 offset:16384
	ds_read_b128 v[176:179], v139 offset:17408
	ds_read_b128 v[180:183], v139 offset:18432
	ds_read_b128 v[184:187], v139 offset:19456
	ds_read_b128 v[188:191], v139 offset:20480
	ds_read_b128 v[192:195], v139 offset:21504
	ds_read_b128 v[196:199], v139 offset:22528
	ds_read_b128 v[200:203], v139 offset:23552
	global_load_lds_dwordx4 v128, s[26:27]
	s_add_i32 m0, s10, 0x2000
	s_add_u32 s10, s26, 0x2b0000
	s_addc_u32 s11, s27, 0
	s_add_i32 s55, s47, s31
	global_load_lds_dwordx4 v130, s[26:27]
	s_mov_b32 m0, s55
	s_nop 0
	global_load_lds_dwordx4 v128, s[10:11]
	s_add_i32 m0, s55, 0x2000
	s_nop 0
	global_load_lds_dwordx4 v130, s[10:11]
	s_waitcnt vmcnt(4)
	s_waitcnt lgkmcnt(0)
	s_barrier
	s_setprio 1
	s_waitcnt lgkmcnt(0)
	v_mfma_f32_16x16x32_bf16 v[60:63], v[140:143], v[172:175], v[60:63]
	v_mfma_f32_16x16x32_bf16 v[56:59], v[148:151], v[172:175], v[56:59]
	v_mfma_f32_16x16x32_bf16 v[48:51], v[140:143], v[180:183], v[48:51]
	v_mfma_f32_16x16x32_bf16 v[40:43], v[148:151], v[180:183], v[40:43]
	v_mfma_f32_16x16x32_bf16 v[32:35], v[140:143], v[188:191], v[32:35]
	v_mfma_f32_16x16x32_bf16 v[24:27], v[148:151], v[188:191], v[24:27]
	v_mfma_f32_16x16x32_bf16 v[16:19], v[140:143], v[196:199], v[16:19]
	v_mfma_f32_16x16x32_bf16 v[8:11], v[148:151], v[196:199], v[8:11]
	v_mfma_f32_16x16x32_bf16 v[60:63], v[144:147], v[176:179], v[60:63]
	v_mfma_f32_16x16x32_bf16 v[56:59], v[152:155], v[176:179], v[56:59]
	v_mfma_f32_16x16x32_bf16 v[48:51], v[144:147], v[184:187], v[48:51]
	v_mfma_f32_16x16x32_bf16 v[40:43], v[152:155], v[184:187], v[40:43]
	v_mfma_f32_16x16x32_bf16 v[32:35], v[144:147], v[192:195], v[32:35]
	v_mfma_f32_16x16x32_bf16 v[24:27], v[152:155], v[192:195], v[24:27]
	v_mfma_f32_16x16x32_bf16 v[16:19], v[144:147], v[200:203], v[16:19]
	v_mfma_f32_16x16x32_bf16 v[8:11], v[152:155], v[200:203], v[8:11]
	s_setprio 0
	s_setprio 1
	v_mfma_f32_16x16x32_bf16 v[52:55], v[156:159], v[172:175], v[52:55]
	v_mfma_f32_16x16x32_bf16 v[44:47], v[164:167], v[172:175], v[44:47]
	v_mfma_f32_16x16x32_bf16 v[36:39], v[156:159], v[180:183], v[36:39]
	v_mfma_f32_16x16x32_bf16 v[28:31], v[164:167], v[180:183], v[28:31]
	v_mfma_f32_16x16x32_bf16 v[20:23], v[156:159], v[188:191], v[20:23]
	v_mfma_f32_16x16x32_bf16 v[12:15], v[164:167], v[188:191], v[12:15]
	v_mfma_f32_16x16x32_bf16 v[4:7], v[156:159], v[196:199], v[4:7]
	v_mfma_f32_16x16x32_bf16 v[0:3], v[164:167], v[196:199], v[0:3]
	v_mfma_f32_16x16x32_bf16 v[52:55], v[160:163], v[176:179], v[52:55]
	v_mfma_f32_16x16x32_bf16 v[44:47], v[168:171], v[176:179], v[44:47]
	v_mfma_f32_16x16x32_bf16 v[36:39], v[160:163], v[184:187], v[36:39]
	v_mfma_f32_16x16x32_bf16 v[28:31], v[168:171], v[184:187], v[28:31]
	v_mfma_f32_16x16x32_bf16 v[20:23], v[160:163], v[192:195], v[20:23]
	v_mfma_f32_16x16x32_bf16 v[12:15], v[168:171], v[192:195], v[12:15]
	v_mfma_f32_16x16x32_bf16 v[4:7], v[160:163], v[200:203], v[4:7]
	v_mfma_f32_16x16x32_bf16 v[0:3], v[168:171], v[200:203], v[0:3]
	s_setprio 0
	s_barrier
; #define PG8_WAIT_V(n) asm volatile("s_waitcnt vmcnt(" #n ")" ::: "memory")
; #define PG8_WAIT_L(n) asm volatile("s_waitcnt lgkmcnt(" #n ")" ::: "memory")
; #define PG8_BAR __builtin_amdgcn_s_barrier()
; #define PG8_SCHED __builtin_amdgcn_sched_barrier(0)
;     ...
;             PG8_LDB(B0, 1, 0); PG8_LDB(B1, 1, 1); PG8_SCHED; PG8_LDA(At, 1, 0); PG8_STAGE(PG8_SA(0, 1), a2 + hstepA, voffA);
;             PG8_WAIT_V(8); PG8_WAIT_L(0); PG8_BAR; PG8_MMA(0, 0, At, B0); PG8_MMA(0, 1, At, B1); PG8_BAR; PG8_SCHED;
;             if constexpr (!HALFU) PG8_LDA(At, 1, 1); PG8_STAGE(PG8_SB(1, 0), b3, voffB); PG8_STAGE(PG8_SB(1, 1), b3 + hstep, voffB); PG8_STAGE(PG8_SA(1, 0), a3, voffA);
;             PG8_WAIT_V(8); PG8_WAIT_L(0); PG8_BAR; if constexpr (!HALFU) { PG8_MMA(1, 0, At, B0); PG8_MMA(1, 1, At, B1); } PG8_BAR; PG8_SCHED;
	s_add_i32 s55, 0, 0x18000
	s_add_i32 s56, 0, 0x1c000
	v_add_u32_e32 v152, s55, v136
	v_add_u32_e32 v168, s56, v136
	ds_read_b128 v[140:143], v152
	ds_read_b128 v[144:147], v152 offset:1024
	ds_read_b128 v[148:151], v152 offset:2048
	ds_read_b128 v[152:155], v152 offset:3072
	ds_read_b128 v[156:159], v168
	ds_read_b128 v[160:163], v168 offset:1024
	ds_read_b128 v[164:167], v168 offset:2048
	ds_read_b128 v[168:171], v168 offset:3072
	s_add_u32 s10, s28, 0x2b0000
	s_addc_u32 s11, s29, 0
	s_mov_b32 m0, s38
	ds_read_b128 v[172:175], v139 offset:32768
	ds_read_b128 v[176:179], v139 offset:33792
	ds_read_b128 v[180:183], v139 offset:34816
	ds_read_b128 v[184:187], v139 offset:35840
	ds_read_b128 v[188:191], v139 offset:36864
	ds_read_b128 v[192:195], v139 offset:37888
	ds_read_b128 v[196:199], v139 offset:38912
	ds_read_b128 v[200:203], v139 offset:39936
	global_load_lds_dwordx4 v128, s[10:11]
	s_mov_b32 m0, s39
	s_nop 0
	global_load_lds_dwordx4 v130, s[10:11]
	s_mov_b32 m0, s36
	s_nop 0
	global_load_lds_dwordx4 v128, s[28:29]
	s_mov_b32 m0, s37
	s_nop 0
	global_load_lds_dwordx4 v130, s[28:29]
	s_waitcnt vmcnt(8)
	s_waitcnt lgkmcnt(0)
	s_barrier
	s_setprio 1
	s_waitcnt lgkmcnt(0)
	v_mfma_f32_16x16x32_bf16 v[124:127], v[140:143], v[172:175], v[124:127]
	v_mfma_f32_16x16x32_bf16 v[120:123], v[148:151], v[172:175], v[120:123]
	v_mfma_f32_16x16x32_bf16 v[112:115], v[140:143], v[180:183], v[112:115]
	v_mfma_f32_16x16x32_bf16 v[104:107], v[148:151], v[180:183], v[104:107]
	v_mfma_f32_16x16x32_bf16 v[96:99], v[140:143], v[188:191], v[96:99]
	v_mfma_f32_16x16x32_bf16 v[88:91], v[148:151], v[188:191], v[88:91]
	v_mfma_f32_16x16x32_bf16 v[80:83], v[140:143], v[196:199], v[80:83]
	v_mfma_f32_16x16x32_bf16 v[72:75], v[148:151], v[196:199], v[72:75]
	v_mfma_f32_16x16x32_bf16 v[124:127], v[144:147], v[176:179], v[124:127]
	v_mfma_f32_16x16x32_bf16 v[120:123], v[152:155], v[176:179], v[120:123]
	v_mfma_f32_16x16x32_bf16 v[112:115], v[144:147], v[184:187], v[112:115]
	v_mfma_f32_16x16x32_bf16 v[104:107], v[152:155], v[184:187], v[104:107]
	v_mfma_f32_16x16x32_bf16 v[96:99], v[144:147], v[192:195], v[96:99]
	v_mfma_f32_16x16x32_bf16 v[88:91], v[152:155], v[192:195], v[88:91]
	v_mfma_f32_16x16x32_bf16 v[80:83], v[144:147], v[200:203], v[80:83]
	v_mfma_f32_16x16x32_bf16 v[72:75], v[152:155], v[200:203], v[72:75]
	s_setprio 0
	s_setprio 1
	v_mfma_f32_16x16x32_bf16 v[116:119], v[156:159], v[172:175], v[116:119]
	v_mfma_f32_16x16x32_bf16 v[108:111], v[164:167], v[172:175], v[108:111]
	v_mfma_f32_16x16x32_bf16 v[100:103], v[156:159], v[180:183], v[100:103]
	v_mfma_f32_16x16x32_bf16 v[92:95], v[164:167], v[180:183], v[92:95]
	v_mfma_f32_16x16x32_bf16 v[84:87], v[156:159], v[188:191], v[84:87]
	v_mfma_f32_16x16x32_bf16 v[76:79], v[164:167], v[188:191], v[76:79]
	v_mfma_f32_16x16x32_bf16 v[68:71], v[156:159], v[196:199], v[68:71]
	v_mfma_f32_16x16x32_bf16 v[64:67], v[164:167], v[196:199], v[64:67]
	v_mfma_f32_16x16x32_bf16 v[116:119], v[160:163], v[176:179], v[116:119]
	v_mfma_f32_16x16x32_bf16 v[108:111], v[168:171], v[176:179], v[108:111]
	v_mfma_f32_16x16x32_bf16 v[100:103], v[160:163], v[184:187], v[100:103]
	v_mfma_f32_16x16x32_bf16 v[92:95], v[168:171], v[184:187], v[92:95]
	v_mfma_f32_16x16x32_bf16 v[84:87], v[160:163], v[192:195], v[84:87]
	v_mfma_f32_16x16x32_bf16 v[76:79], v[168:171], v[192:195], v[76:79]
	v_mfma_f32_16x16x32_bf16 v[68:71], v[160:163], v[200:203], v[68:71]
	v_mfma_f32_16x16x32_bf16 v[64:67], v[168:171], v[200:203], v[64:67]
	s_setprio 0
	s_barrier
	s_add_u32 s10, s26, 0x80
	s_addc_u32 s11, s27, 0
	s_add_i32 s28, s55, s31
	s_mov_b32 m0, s28
	ds_read_b128 v[172:175], v139 offset:49152
	ds_read_b128 v[176:179], v139 offset:50176
	ds_read_b128 v[180:183], v139 offset:51200
	ds_read_b128 v[184:187], v139 offset:52224
	ds_read_b128 v[188:191], v139 offset:53248
	ds_read_b128 v[192:195], v139 offset:54272
	ds_read_b128 v[196:199], v139 offset:55296
	ds_read_b128 v[200:203], v139 offset:56320
	global_load_lds_dwordx4 v128, s[10:11]
	s_add_i32 m0, s28, 0x2000
	v_lshl_add_u64 v[204:205], s[10:11], 0, v[130:131]
	s_add_u32 s10, s26, 0x2b0080
	s_addc_u32 s11, s27, 0
	s_add_i32 s26, s56, s31
	global_load_lds_dwordx4 v[204:205], off
	s_mov_b32 m0, s26
	s_nop 0
	global_load_lds_dwordx4 v128, s[10:11]
	s_add_i32 m0, s26, 0x2000
	s_nop 0
	global_load_lds_dwordx4 v130, s[10:11]
	s_waitcnt vmcnt(4)
	s_waitcnt lgkmcnt(0)
	s_barrier
	s_setprio 1
	s_waitcnt lgkmcnt(0)
	v_mfma_f32_16x16x32_bf16 v[60:63], v[140:143], v[172:175], v[60:63]
	v_mfma_f32_16x16x32_bf16 v[56:59], v[148:151], v[172:175], v[56:59]
	v_mfma_f32_16x16x32_bf16 v[48:51], v[140:143], v[180:183], v[48:51]
	v_mfma_f32_16x16x32_bf16 v[40:43], v[148:151], v[180:183], v[40:43]
	v_mfma_f32_16x16x32_bf16 v[32:35], v[140:143], v[188:191], v[32:35]
	v_mfma_f32_16x16x32_bf16 v[24:27], v[148:151], v[188:191], v[24:27]
	v_mfma_f32_16x16x32_bf16 v[16:19], v[140:143], v[196:199], v[16:19]
	v_mfma_f32_16x16x32_bf16 v[8:11], v[148:151], v[196:199], v[8:11]
	v_mfma_f32_16x16x32_bf16 v[60:63], v[144:147], v[176:179], v[60:63]
	v_mfma_f32_16x16x32_bf16 v[56:59], v[152:155], v[176:179], v[56:59]
	v_mfma_f32_16x16x32_bf16 v[48:51], v[144:147], v[184:187], v[48:51]
	v_mfma_f32_16x16x32_bf16 v[40:43], v[152:155], v[184:187], v[40:43]
	v_mfma_f32_16x16x32_bf16 v[32:35], v[144:147], v[192:195], v[32:35]
	v_mfma_f32_16x16x32_bf16 v[24:27], v[152:155], v[192:195], v[24:27]
	v_mfma_f32_16x16x32_bf16 v[16:19], v[144:147], v[200:203], v[16:19]
	v_mfma_f32_16x16x32_bf16 v[8:11], v[152:155], v[200:203], v[8:11]
	s_setprio 0
	s_setprio 1
	v_mfma_f32_16x16x32_bf16 v[52:55], v[156:159], v[172:175], v[52:55]
	v_mfma_f32_16x16x32_bf16 v[44:47], v[164:167], v[172:175], v[44:47]
	v_mfma_f32_16x16x32_bf16 v[36:39], v[156:159], v[180:183], v[36:39]
	v_mfma_f32_16x16x32_bf16 v[28:31], v[164:167], v[180:183], v[28:31]
	v_mfma_f32_16x16x32_bf16 v[20:23], v[156:159], v[188:191], v[20:23]
	v_mfma_f32_16x16x32_bf16 v[12:15], v[164:167], v[188:191], v[12:15]
	v_mfma_f32_16x16x32_bf16 v[4:7], v[156:159], v[196:199], v[4:7]
	v_mfma_f32_16x16x32_bf16 v[0:3], v[164:167], v[196:199], v[0:3]
	v_mfma_f32_16x16x32_bf16 v[52:55], v[160:163], v[176:179], v[52:55]
	v_mfma_f32_16x16x32_bf16 v[44:47], v[168:171], v[176:179], v[44:47]
	v_mfma_f32_16x16x32_bf16 v[36:39], v[160:163], v[184:187], v[36:39]
	v_mfma_f32_16x16x32_bf16 v[28:31], v[168:171], v[184:187], v[28:31]
	v_mfma_f32_16x16x32_bf16 v[20:23], v[160:163], v[192:195], v[20:23]
	v_mfma_f32_16x16x32_bf16 v[12:15], v[168:171], v[192:195], v[12:15]
	v_mfma_f32_16x16x32_bf16 v[4:7], v[160:163], v[200:203], v[4:7]
	v_mfma_f32_16x16x32_bf16 v[0:3], v[168:171], v[200:203], v[0:3]
	s_setprio 0
	s_barrier
	s_add_i32 s54, s54, 2
	s_add_u32 s52, s52, 0x100
	s_addc_u32 s53, s53, 0
	s_cmpk_gt_u32 s54, 0xa9
	s_mov_b64 s[10:11], s[22:23]
	s_cbranch_scc0 .LBB0_793
	s_and_b64 vcc, exec, s[12:13]
	s_cbranch_vccz .LBB0_796
	s_barrier

; #define PG8_WAIT_V(n) asm volatile("s_waitcnt vmcnt(" #n ")" ::: "memory")
; #define PG8_WAIT_L(n) asm volatile("s_waitcnt lgkmcnt(" #n ")" ::: "memory")
; #define PG8_BAR __builtin_amdgcn_s_barrier()
; #define PG8_SCHED __builtin_amdgcn_sched_barrier(0)
;     ...
;             const char* a1 = cA + (size_t)(t + 1) * kstep;
;             const char* a2 = last ? nA : cA + (size_t)(t + 2) * kstep; const char* b2 = last ? nB : cB + (size_t)(t + 2) * kstep;
;             const char* a3 = a2 + kstep; const char* b3 = b2 + kstep;
;             if (last && has_next) S.a_ready(nxt);
;             if constexpr (SP2) {
;             PG8_LDB(B0, 0, 0); PG8_LDB(B1, 0, 1); PG8_SCHED; PG8_LDA(At, 0, 0); PG8_STAGE(PG8_SA(1, 1), a1 + hstepA, voffA);
;             PG8_WAIT_V(8); PG8_WAIT_L(0); PG8_BAR; PG8_MMA(0, 0, At, B0); PG8_MMA(0, 1, At, B1); PG8_BAR; PG8_SCHED;
;             if constexpr (!HALFU) PG8_LDA(At, 0, 1); PG8_STAGE(PG8_SB(0, 0), b2, voffB); PG8_STAGE(PG8_SB(0, 1), b2 + hstep, voffB); PG8_STAGE(PG8_SA(0, 0), a2, voffA);
;             PG8_WAIT_V(8); PG8_WAIT_L(0); PG8_BAR; if constexpr (!HALFU) { PG8_MMA(1, 0, At, B0); PG8_MMA(1, 1, At, B1); } PG8_BAR; PG8_SCHED;
.LBB0_1200:
	s_add_u32 s98, s10, 0x80
	s_addc_u32 s99, s11, 0
	ds_read_b128 v[128:131], v149
	ds_read_b128 v[132:135], v149 offset:1024
	ds_read_b128 v[154:157], v149 offset:2048
	ds_read_b128 v[158:161], v149 offset:3072
	ds_read_b128 v[162:165], v150
	ds_read_b128 v[166:169], v150 offset:1024
	ds_read_b128 v[170:173], v150 offset:2048
	ds_read_b128 v[174:177], v150 offset:3072
	s_add_u32 s26, s10, 0x100
	s_addc_u32 s27, s11, 0
	s_cmp_eq_u32 s76, 28
	s_cselect_b32 s50, s9, s26
	s_cselect_b32 s51, s7, s27
	s_cselect_b32 s48, s43, s74
	s_cselect_b32 s49, s41, s75
	s_add_u32 s30, s50, 0x80
	s_addc_u32 s31, s51, 0
	s_add_u32 s10, s10, 0x80080
	s_addc_u32 s11, s11, 0
	s_add_i32 m0, s57, 0xc000
	ds_read_b128 v[178:181], v151
	ds_read_b128 v[182:185], v151 offset:1024
	ds_read_b128 v[186:189], v151 offset:2048
	ds_read_b128 v[190:193], v151 offset:3072
	ds_read_b128 v[194:197], v151 offset:4096
	ds_read_b128 v[198:201], v151 offset:5120
	ds_read_b128 v[202:205], v151 offset:6144
	ds_read_b128 v[206:209], v151 offset:7168
	global_load_lds_dwordx4 v136, s[10:11]
	s_add_i32 m0, s57, 0xe000
	s_nop 0
	global_load_lds_dwordx4 v140, s[10:11]
	s_mov_b32 m0, s68
	s_nop 0
	global_load_lds_dwordx4 v136, s[98:99]
	s_mov_b32 m0, s69
	s_nop 0
	global_load_lds_dwordx4 v140, s[98:99]
	s_waitcnt vmcnt(8)
	s_waitcnt lgkmcnt(0)
	s_barrier
	s_setprio 1
	s_waitcnt lgkmcnt(0)
	v_mfma_scale_f32_16x16x128_f8f6f4 v[124:127], v[128:135], v[178:185], v[124:127], v152, v152 op_sel_hi:[0,0,0]
	v_mfma_scale_f32_16x16x128_f8f6f4 v[120:123], v[154:161], v[178:185], v[120:123], v152, v152 op_sel_hi:[0,0,0]
	v_mfma_scale_f32_16x16x128_f8f6f4 v[108:111], v[128:135], v[186:193], v[108:111], v152, v152 op_sel_hi:[0,0,0]
	v_mfma_scale_f32_16x16x128_f8f6f4 v[104:107], v[154:161], v[186:193], v[104:107], v152, v152 op_sel_hi:[0,0,0]
	v_mfma_scale_f32_16x16x128_f8f6f4 v[210:213], v[128:135], v[194:201], v[92:95], v152, v152 op_sel_hi:[0,0,0]
	v_mfma_scale_f32_16x16x128_f8f6f4 v[214:217], v[154:161], v[194:201], v[88:91], v152, v152 op_sel_hi:[0,0,0]
	v_mfma_scale_f32_16x16x128_f8f6f4 v[218:221], v[128:135], v[202:209], v[76:79], v152, v152 op_sel_hi:[0,0,0]
	v_mfma_scale_f32_16x16x128_f8f6f4 v[222:225], v[154:161], v[202:209], v[72:75], v152, v152 op_sel_hi:[0,0,0]
	s_setprio 0
	s_setprio 1
	v_mfma_scale_f32_16x16x128_f8f6f4 v[116:119], v[162:169], v[178:185], v[116:119], v152, v152 op_sel_hi:[0,0,0]
	v_mfma_scale_f32_16x16x128_f8f6f4 v[112:115], v[170:177], v[178:185], v[112:115], v152, v152 op_sel_hi:[0,0,0]
	v_mfma_scale_f32_16x16x128_f8f6f4 v[100:103], v[162:169], v[186:193], v[100:103], v152, v152 op_sel_hi:[0,0,0]
	v_mfma_scale_f32_16x16x128_f8f6f4 v[96:99], v[170:177], v[186:193], v[96:99], v152, v152 op_sel_hi:[0,0,0]
	v_mfma_scale_f32_16x16x128_f8f6f4 v[178:181], v[162:169], v[194:201], v[84:87], v152, v152 op_sel_hi:[0,0,0]
	v_mfma_scale_f32_16x16x128_f8f6f4 v[182:185], v[170:177], v[194:201], v[80:83], v152, v152 op_sel_hi:[0,0,0]
	v_mfma_scale_f32_16x16x128_f8f6f4 v[186:189], v[162:169], v[202:209], v[68:71], v152, v152 op_sel_hi:[0,0,0]
	v_mfma_scale_f32_16x16x128_f8f6f4 v[190:193], v[170:177], v[202:209], v[64:67], v152, v152 op_sel_hi:[0,0,0]
	s_setprio 0
	s_barrier
	s_add_i32 s10, s71, s56
	s_mov_b32 m0, s10
	s_nop 1
	ds_read_b128 v[64:67], v151 offset:16384
	ds_read_b128 v[68:71], v151 offset:17408
	ds_read_b128 v[72:75], v151 offset:18432
	ds_read_b128 v[76:79], v151 offset:19456
	ds_read_b128 v[80:83], v151 offset:20480
	ds_read_b128 v[84:87], v151 offset:21504
	ds_read_b128 v[88:91], v151 offset:22528
	ds_read_b128 v[92:95], v151 offset:23552
	global_load_lds_dwordx4 v138, s[48:49]
	s_add_i32 m0, s10, 0x2000
	s_add_u32 s10, s48, 0x80000
	s_addc_u32 s11, s49, 0
	s_add_i32 s77, s72, s56
	global_load_lds_dwordx4 v142, s[48:49]
	s_mov_b32 m0, s77
	s_nop 0
	global_load_lds_dwordx4 v138, s[10:11]
	s_add_i32 m0, s77, 0x2000
	s_nop 0
	global_load_lds_dwordx4 v142, s[10:11]
	s_waitcnt vmcnt(4)
	s_waitcnt lgkmcnt(0)
	s_barrier
	s_setprio 1
	s_waitcnt lgkmcnt(0)
	v_mfma_scale_f32_16x16x128_f8f6f4 v[60:63], v[128:135], v[64:71], v[60:63], v152, v152 op_sel_hi:[0,0,0]
	v_mfma_scale_f32_16x16x128_f8f6f4 v[56:59], v[154:161], v[64:71], v[56:59], v152, v152 op_sel_hi:[0,0,0]
	v_mfma_scale_f32_16x16x128_f8f6f4 v[194:197], v[128:135], v[72:79], v[44:47], v152, v152 op_sel_hi:[0,0,0]
	v_mfma_scale_f32_16x16x128_f8f6f4 v[198:201], v[154:161], v[72:79], v[40:43], v152, v152 op_sel_hi:[0,0,0]
	v_mfma_scale_f32_16x16x128_f8f6f4 v[202:205], v[128:135], v[80:87], v[28:31], v152, v152 op_sel_hi:[0,0,0]
	v_mfma_scale_f32_16x16x128_f8f6f4 v[206:209], v[154:161], v[80:87], v[24:27], v152, v152 op_sel_hi:[0,0,0]
	v_mfma_scale_f32_16x16x128_f8f6f4 v[226:229], v[128:135], v[88:95], v[12:15], v152, v152 op_sel_hi:[0,0,0]
	v_mfma_scale_f32_16x16x128_f8f6f4 v[230:233], v[154:161], v[88:95], v[8:11], v152, v152 op_sel_hi:[0,0,0]
	s_setprio 0
	s_setprio 1
	v_mfma_scale_f32_16x16x128_f8f6f4 v[52:55], v[162:169], v[64:71], v[52:55], v152, v152 op_sel_hi:[0,0,0]
	v_mfma_scale_f32_16x16x128_f8f6f4 v[48:51], v[170:177], v[64:71], v[48:51], v152, v152 op_sel_hi:[0,0,0]
	v_mfma_scale_f32_16x16x128_f8f6f4 v[234:237], v[162:169], v[72:79], v[36:39], v152, v152 op_sel_hi:[0,0,0]
	v_mfma_scale_f32_16x16x128_f8f6f4 v[238:241], v[170:177], v[72:79], v[32:35], v152, v152 op_sel_hi:[0,0,0]
	v_mfma_scale_f32_16x16x128_f8f6f4 v[242:245], v[162:169], v[80:87], v[20:23], v152, v152 op_sel_hi:[0,0,0]
	v_mfma_scale_f32_16x16x128_f8f6f4 v[246:249], v[170:177], v[80:87], v[16:19], v152, v152 op_sel_hi:[0,0,0]
	v_mfma_scale_f32_16x16x128_f8f6f4 v[250:253], v[162:169], v[88:95], v[4:7], v152, v152 op_sel_hi:[0,0,0]
	v_mfma_scale_f32_16x16x128_f8f6f4 v[144:147], v[170:177], v[88:95], v[0:3], v152, v152 op_sel_hi:[0,0,0]
	s_setprio 0
	s_barrier
; #define PG8_WAIT_V(n) asm volatile("s_waitcnt vmcnt(" #n ")" ::: "memory")
; #define PG8_WAIT_L(n) asm volatile("s_waitcnt lgkmcnt(" #n ")" ::: "memory")
; #define PG8_BAR __builtin_amdgcn_s_barrier()
; #define PG8_SCHED __builtin_amdgcn_sched_barrier(0)
;     ...
;             PG8_LDB(B0, 1, 0); PG8_LDB(B1, 1, 1); PG8_SCHED; PG8_LDA(At, 1, 0); PG8_STAGE(PG8_SA(0, 1), a2 + hstepA, voffA);
;             PG8_WAIT_V(8); PG8_WAIT_L(0); PG8_BAR; PG8_MMA(0, 0, At, B0); PG8_MMA(0, 1, At, B1); PG8_BAR; PG8_SCHED;
;             if constexpr (!HALFU) PG8_LDA(At, 1, 1); PG8_STAGE(PG8_SB(1, 0), b3, voffB); PG8_STAGE(PG8_SB(1, 1), b3 + hstep, voffB); PG8_STAGE(PG8_SA(1, 0), a3, voffA);
;             PG8_WAIT_V(8); PG8_WAIT_L(0); PG8_BAR; if constexpr (!HALFU) { PG8_MMA(1, 0, At, B0); PG8_MMA(1, 1, At, B1); } PG8_BAR; PG8_SCHED;
	s_add_i32 s77, 0, 0x18000
	v_add_u32_e32 v8, s77, v148
	s_add_i32 s78, 0, 0x1c000
	s_nop 1
	ds_read_b128 v[0:3], v8
	ds_read_b128 v[4:7], v8 offset:1024
	ds_read_b128 v[16:19], v8 offset:2048
	ds_read_b128 v[20:23], v8 offset:3072
	v_add_u32_e32 v8, s78, v148
	ds_read_b128 v[128:131], v8
	ds_read_b128 v[132:135], v8 offset:1024
	ds_read_b128 v[154:157], v8 offset:2048
	ds_read_b128 v[158:161], v8 offset:3072
	s_add_u32 s10, s50, 0x80000
	s_addc_u32 s11, s51, 0
	s_mov_b32 m0, s63
	ds_read_b128 v[8:11], v151 offset:32768
	ds_read_b128 v[12:15], v151 offset:33792
	ds_read_b128 v[24:27], v151 offset:34816
	ds_read_b128 v[28:31], v151 offset:35840
	ds_read_b128 v[32:35], v151 offset:36864
	ds_read_b128 v[36:39], v151 offset:37888
	ds_read_b128 v[40:43], v151 offset:38912
	ds_read_b128 v[44:47], v151 offset:39936
	global_load_lds_dwordx4 v136, s[10:11]
	s_mov_b32 m0, s64
	s_nop 0
	global_load_lds_dwordx4 v140, s[10:11]
	s_mov_b32 m0, s57
	s_nop 0
	global_load_lds_dwordx4 v136, s[50:51]
	s_mov_b32 m0, s62
	s_nop 0
	global_load_lds_dwordx4 v140, s[50:51]
	s_waitcnt vmcnt(8)
	s_waitcnt lgkmcnt(0)
	s_barrier
	s_setprio 1
	s_waitcnt lgkmcnt(0)
	v_mfma_scale_f32_16x16x128_f8f6f4 v[124:127], v[0:7], v[8:15], v[124:127], v152, v152 op_sel_hi:[0,0,0]
	v_mfma_scale_f32_16x16x128_f8f6f4 v[120:123], v[16:23], v[8:15], v[120:123], v152, v152 op_sel_hi:[0,0,0]
	v_mfma_scale_f32_16x16x128_f8f6f4 v[108:111], v[0:7], v[24:31], v[108:111], v152, v152 op_sel_hi:[0,0,0]
	v_mfma_scale_f32_16x16x128_f8f6f4 v[104:107], v[16:23], v[24:31], v[104:107], v152, v152 op_sel_hi:[0,0,0]
	v_mfma_scale_f32_16x16x128_f8f6f4 v[92:95], v[0:7], v[32:39], v[210:213], v152, v152 op_sel_hi:[0,0,0]
	v_mfma_scale_f32_16x16x128_f8f6f4 v[88:91], v[16:23], v[32:39], v[214:217], v152, v152 op_sel_hi:[0,0,0]
	v_mfma_scale_f32_16x16x128_f8f6f4 v[76:79], v[0:7], v[40:47], v[218:221], v152, v152 op_sel_hi:[0,0,0]
	v_mfma_scale_f32_16x16x128_f8f6f4 v[72:75], v[16:23], v[40:47], v[222:225], v152, v152 op_sel_hi:[0,0,0]
	s_setprio 0
	s_setprio 1
	v_mfma_scale_f32_16x16x128_f8f6f4 v[116:119], v[128:135], v[8:15], v[116:119], v152, v152 op_sel_hi:[0,0,0]
	v_mfma_scale_f32_16x16x128_f8f6f4 v[112:115], v[154:161], v[8:15], v[112:115], v152, v152 op_sel_hi:[0,0,0]
	v_mfma_scale_f32_16x16x128_f8f6f4 v[100:103], v[128:135], v[24:31], v[100:103], v152, v152 op_sel_hi:[0,0,0]
	v_mfma_scale_f32_16x16x128_f8f6f4 v[96:99], v[154:161], v[24:31], v[96:99], v152, v152 op_sel_hi:[0,0,0]
	v_mfma_scale_f32_16x16x128_f8f6f4 v[84:87], v[128:135], v[32:39], v[178:181], v152, v152 op_sel_hi:[0,0,0]
	v_mfma_scale_f32_16x16x128_f8f6f4 v[80:83], v[154:161], v[32:39], v[182:185], v152, v152 op_sel_hi:[0,0,0]
	v_mfma_scale_f32_16x16x128_f8f6f4 v[68:71], v[128:135], v[40:47], v[186:189], v152, v152 op_sel_hi:[0,0,0]
	v_mfma_scale_f32_16x16x128_f8f6f4 v[64:67], v[154:161], v[40:47], v[190:193], v152, v152 op_sel_hi:[0,0,0]
	s_setprio 0
	s_barrier
	s_add_u32 s10, s48, 0x80
	s_addc_u32 s11, s49, 0
	s_add_i32 s50, s77, s56
	s_mov_b32 m0, s50
	ds_read_b128 v[32:35], v151 offset:49152
	ds_read_b128 v[36:39], v151 offset:50176
	ds_read_b128 v[162:165], v151 offset:51200
	ds_read_b128 v[166:169], v151 offset:52224
	ds_read_b128 v[170:173], v151 offset:53248
	ds_read_b128 v[174:177], v151 offset:54272
	ds_read_b128 v[178:181], v151 offset:55296
	ds_read_b128 v[182:185], v151 offset:56320
	global_load_lds_dwordx4 v138, s[10:11]
	s_add_i32 m0, s50, 0x2000
	v_lshl_add_u64 v[8:9], s[10:11], 0, v[142:143]
	s_add_u32 s10, s48, 0x80080
	s_addc_u32 s11, s49, 0
	s_add_i32 s48, s78, s56
	global_load_lds_dwordx4 v[8:9], off
	s_mov_b32 m0, s48
	s_nop 0
	global_load_lds_dwordx4 v138, s[10:11]
	s_add_i32 m0, s48, 0x2000
	s_nop 0
	global_load_lds_dwordx4 v142, s[10:11]
	s_waitcnt vmcnt(4)
	s_waitcnt lgkmcnt(0)
	s_barrier
	s_setprio 1
	s_waitcnt lgkmcnt(0)
	v_mfma_scale_f32_16x16x128_f8f6f4 v[60:63], v[0:7], v[32:39], v[60:63], v152, v152 op_sel_hi:[0,0,0]
	v_mfma_scale_f32_16x16x128_f8f6f4 v[56:59], v[16:23], v[32:39], v[56:59], v152, v152 op_sel_hi:[0,0,0]
	v_mfma_scale_f32_16x16x128_f8f6f4 v[44:47], v[0:7], v[162:169], v[194:197], v152, v152 op_sel_hi:[0,0,0]
	v_mfma_scale_f32_16x16x128_f8f6f4 v[40:43], v[16:23], v[162:169], v[198:201], v152, v152 op_sel_hi:[0,0,0]
	v_mfma_scale_f32_16x16x128_f8f6f4 v[28:31], v[0:7], v[170:177], v[202:205], v152, v152 op_sel_hi:[0,0,0]
	v_mfma_scale_f32_16x16x128_f8f6f4 v[24:27], v[16:23], v[170:177], v[206:209], v152, v152 op_sel_hi:[0,0,0]
	v_mfma_scale_f32_16x16x128_f8f6f4 v[12:15], v[0:7], v[178:185], v[226:229], v152, v152 op_sel_hi:[0,0,0]
	v_mfma_scale_f32_16x16x128_f8f6f4 v[8:11], v[16:23], v[178:185], v[230:233], v152, v152 op_sel_hi:[0,0,0]
	s_setprio 0
	s_setprio 1
	v_mfma_scale_f32_16x16x128_f8f6f4 v[52:55], v[128:135], v[32:39], v[52:55], v152, v152 op_sel_hi:[0,0,0]
	v_mfma_scale_f32_16x16x128_f8f6f4 v[48:51], v[154:161], v[32:39], v[48:51], v152, v152 op_sel_hi:[0,0,0]
	v_mfma_scale_f32_16x16x128_f8f6f4 v[36:39], v[128:135], v[162:169], v[234:237], v152, v152 op_sel_hi:[0,0,0]
	v_mfma_scale_f32_16x16x128_f8f6f4 v[32:35], v[154:161], v[162:169], v[238:241], v152, v152 op_sel_hi:[0,0,0]
	v_mfma_scale_f32_16x16x128_f8f6f4 v[20:23], v[128:135], v[170:177], v[242:245], v152, v152 op_sel_hi:[0,0,0]
	v_mfma_scale_f32_16x16x128_f8f6f4 v[16:19], v[154:161], v[170:177], v[246:249], v152, v152 op_sel_hi:[0,0,0]
	v_mfma_scale_f32_16x16x128_f8f6f4 v[4:7], v[128:135], v[178:185], v[250:253], v152, v152 op_sel_hi:[0,0,0]
	v_mfma_scale_f32_16x16x128_f8f6f4 v[0:3], v[154:161], v[178:185], v[144:147], v152, v152 op_sel_hi:[0,0,0]
	s_setprio 0
	s_barrier
	s_add_i32 s76, s76, 2
	s_add_u32 s74, s74, 0x100
	s_addc_u32 s75, s75, 0
	s_cmp_gt_u32 s76, 29
	s_mov_b64 s[10:11], s[26:27]
	s_cbranch_scc0 .LBB0_1200
	s_and_b64 vcc, exec, s[36:37]
	s_cbranch_vccz .LBB0_1203
	s_barrier

; #define PG8_WAIT_V(n) asm volatile("s_waitcnt vmcnt(" #n ")" ::: "memory")
; #define PG8_WAIT_L(n) asm volatile("s_waitcnt lgkmcnt(" #n ")" ::: "memory")
; #define PG8_BAR __builtin_amdgcn_s_barrier()
; #define PG8_SCHED __builtin_amdgcn_sched_barrier(0)
;     ...
;             const char* a1 = cA + (size_t)(t + 1) * kstep;
;             const char* a2 = last ? nA : cA + (size_t)(t + 2) * kstep; const char* b2 = last ? nB : cB + (size_t)(t + 2) * kstep;
;             const char* a3 = a2 + kstep; const char* b3 = b2 + kstep;
;             if (last && has_next) S.a_ready(nxt);
;             if constexpr (SP2) {
;             PG8_LDB(B0, 0, 0); PG8_LDB(B1, 0, 1); PG8_SCHED; PG8_LDA(At, 0, 0); PG8_STAGE(PG8_SA(1, 1), a1 + hstepA, voffA);
;             PG8_WAIT_V(8); PG8_WAIT_L(0); PG8_BAR; PG8_MMA(0, 0, At, B0); PG8_MMA(0, 1, At, B1); PG8_BAR; PG8_SCHED;
;             if constexpr (!HALFU) PG8_LDA(At, 0, 1); PG8_STAGE(PG8_SB(0, 0), b2, voffB); PG8_STAGE(PG8_SB(0, 1), b2 + hstep, voffB); PG8_STAGE(PG8_SA(0, 0), a2, voffA);
;             PG8_WAIT_V(8); PG8_WAIT_L(0); PG8_BAR; if constexpr (!HALFU) { PG8_MMA(1, 0, At, B0); PG8_MMA(1, 1, At, B1); } PG8_BAR; PG8_SCHED;
.LBB0_1370:
	s_add_u32 s98, s10, 0x80
	s_addc_u32 s99, s11, 0
	ds_read_b128 v[128:131], v163
	ds_read_b128 v[132:135], v163 offset:1024
	ds_read_b128 v[150:153], v163 offset:2048
	ds_read_b128 v[154:157], v163 offset:3072
	ds_read_b128 v[158:161], v164
	ds_read_b128 v[166:169], v164 offset:1024
	ds_read_b128 v[170:173], v164 offset:2048
	ds_read_b128 v[174:177], v164 offset:3072
	s_add_u32 s12, s10, 0x100
	s_addc_u32 s13, s11, 0
	s_cmp_eq_u32 s53, 60
	s_cselect_b32 s50, s7, s12
	s_cselect_b32 s51, s0, s13
	s_cselect_b32 s48, s39, s41
	s_cselect_b32 s49, s9, s52
	s_add_u32 s46, s50, 0x80
	s_addc_u32 s47, s51, 0
	s_add_u32 s10, s10, 0x100080
	s_addc_u32 s11, s11, 0
	s_add_i32 m0, s37, 0xc000
	ds_read_b128 v[178:181], v165
	ds_read_b128 v[182:185], v165 offset:1024
	ds_read_b128 v[186:189], v165 offset:2048
	ds_read_b128 v[190:193], v165 offset:3072
	ds_read_b128 v[194:197], v165 offset:4096
	ds_read_b128 v[198:201], v165 offset:5120
	ds_read_b128 v[202:205], v165 offset:6144
	ds_read_b128 v[206:209], v165 offset:7168
	global_load_lds_dwordx4 v136, s[10:11]
	s_add_i32 m0, s37, 0xe000
	s_nop 0
	global_load_lds_dwordx4 v140, s[10:11]
	s_mov_b32 m0, s67
	s_nop 0
	global_load_lds_dwordx4 v136, s[98:99]
	s_mov_b32 m0, s68
	s_nop 0
	global_load_lds_dwordx4 v140, s[98:99]
	s_waitcnt vmcnt(8)
	s_waitcnt lgkmcnt(0)
	s_barrier
	s_setprio 1
	s_waitcnt lgkmcnt(0)
	v_mfma_f32_16x16x32_bf16 v[124:127], v[128:131], v[178:181], v[124:127]
	v_mfma_f32_16x16x32_bf16 v[120:123], v[150:153], v[178:181], v[120:123]
	v_mfma_f32_16x16x32_bf16 v[108:111], v[128:131], v[186:189], v[108:111]
	v_mfma_f32_16x16x32_bf16 v[104:107], v[150:153], v[186:189], v[104:107]
	v_mfma_f32_16x16x32_bf16 v[92:95], v[128:131], v[194:197], v[92:95]
	v_mfma_f32_16x16x32_bf16 v[88:91], v[150:153], v[194:197], v[88:91]
	v_mfma_f32_16x16x32_bf16 v[76:79], v[128:131], v[202:205], v[76:79]
	v_mfma_f32_16x16x32_bf16 v[72:75], v[150:153], v[202:205], v[72:75]
	v_mfma_f32_16x16x32_bf16 v[124:127], v[132:135], v[182:185], v[124:127]
	v_mfma_f32_16x16x32_bf16 v[120:123], v[154:157], v[182:185], v[120:123]
	v_mfma_f32_16x16x32_bf16 v[108:111], v[132:135], v[190:193], v[108:111]
	v_mfma_f32_16x16x32_bf16 v[104:107], v[154:157], v[190:193], v[104:107]
	v_mfma_f32_16x16x32_bf16 v[92:95], v[132:135], v[198:201], v[92:95]
	v_mfma_f32_16x16x32_bf16 v[88:91], v[154:157], v[198:201], v[88:91]
	v_mfma_f32_16x16x32_bf16 v[76:79], v[132:135], v[206:209], v[76:79]
	v_mfma_f32_16x16x32_bf16 v[72:75], v[154:157], v[206:209], v[72:75]
	s_setprio 0
	s_setprio 1
	v_mfma_f32_16x16x32_bf16 v[116:119], v[158:161], v[178:181], v[116:119]
	v_mfma_f32_16x16x32_bf16 v[112:115], v[170:173], v[178:181], v[112:115]
	v_mfma_f32_16x16x32_bf16 v[100:103], v[158:161], v[186:189], v[100:103]
	v_mfma_f32_16x16x32_bf16 v[96:99], v[170:173], v[186:189], v[96:99]
	v_mfma_f32_16x16x32_bf16 v[84:87], v[158:161], v[194:197], v[84:87]
	v_mfma_f32_16x16x32_bf16 v[80:83], v[170:173], v[194:197], v[80:83]
	v_mfma_f32_16x16x32_bf16 v[68:71], v[158:161], v[202:205], v[68:71]
	v_mfma_f32_16x16x32_bf16 v[64:67], v[170:173], v[202:205], v[64:67]
	v_mfma_f32_16x16x32_bf16 v[116:119], v[166:169], v[182:185], v[116:119]
	v_mfma_f32_16x16x32_bf16 v[112:115], v[174:177], v[182:185], v[112:115]
	v_mfma_f32_16x16x32_bf16 v[100:103], v[166:169], v[190:193], v[100:103]
	v_mfma_f32_16x16x32_bf16 v[96:99], v[174:177], v[190:193], v[96:99]
	v_mfma_f32_16x16x32_bf16 v[84:87], v[166:169], v[198:201], v[84:87]
	v_mfma_f32_16x16x32_bf16 v[80:83], v[174:177], v[198:201], v[80:83]
	v_mfma_f32_16x16x32_bf16 v[68:71], v[166:169], v[206:209], v[68:71]
	v_mfma_f32_16x16x32_bf16 v[64:67], v[174:177], v[206:209], v[64:67]
	s_setprio 0
	s_barrier
	s_add_i32 s10, s71, s21
	s_mov_b32 m0, s10
	ds_read_b128 v[178:181], v165 offset:16384
	ds_read_b128 v[182:185], v165 offset:17408
	ds_read_b128 v[186:189], v165 offset:18432
	ds_read_b128 v[190:193], v165 offset:19456
	ds_read_b128 v[194:197], v165 offset:20480
	ds_read_b128 v[198:201], v165 offset:21504
	ds_read_b128 v[202:205], v165 offset:22528
	ds_read_b128 v[206:209], v165 offset:23552
	global_load_lds_dwordx4 v138, s[48:49]
	s_add_i32 m0, s10, 0x2000
	s_add_u32 s10, s48, 0x100000
	s_addc_u32 s11, s49, 0
	s_add_i32 s54, s72, s21
	global_load_lds_dwordx4 v142, s[48:49]
	s_mov_b32 m0, s54
	s_nop 0
	global_load_lds_dwordx4 v138, s[10:11]
	s_add_i32 m0, s54, 0x2000
	s_nop 0
	global_load_lds_dwordx4 v142, s[10:11]
	s_waitcnt vmcnt(4)
	s_waitcnt lgkmcnt(0)
	s_barrier
	s_setprio 1
	s_waitcnt lgkmcnt(0)
	v_mfma_f32_16x16x32_bf16 v[60:63], v[128:131], v[178:181], v[60:63]
	v_mfma_f32_16x16x32_bf16 v[56:59], v[150:153], v[178:181], v[56:59]
	v_mfma_f32_16x16x32_bf16 v[44:47], v[128:131], v[186:189], v[44:47]
	v_mfma_f32_16x16x32_bf16 v[40:43], v[150:153], v[186:189], v[40:43]
	v_mfma_f32_16x16x32_bf16 v[28:31], v[128:131], v[194:197], v[28:31]
	v_mfma_f32_16x16x32_bf16 v[24:27], v[150:153], v[194:197], v[24:27]
	v_mfma_f32_16x16x32_bf16 v[12:15], v[128:131], v[202:205], v[12:15]
	v_mfma_f32_16x16x32_bf16 v[8:11], v[150:153], v[202:205], v[8:11]
	v_mfma_f32_16x16x32_bf16 v[60:63], v[132:135], v[182:185], v[60:63]
	v_mfma_f32_16x16x32_bf16 v[56:59], v[154:157], v[182:185], v[56:59]
	v_mfma_f32_16x16x32_bf16 v[44:47], v[132:135], v[190:193], v[44:47]
	v_mfma_f32_16x16x32_bf16 v[40:43], v[154:157], v[190:193], v[40:43]
	v_mfma_f32_16x16x32_bf16 v[28:31], v[132:135], v[198:201], v[28:31]
	v_mfma_f32_16x16x32_bf16 v[24:27], v[154:157], v[198:201], v[24:27]
	v_mfma_f32_16x16x32_bf16 v[12:15], v[132:135], v[206:209], v[12:15]
	v_mfma_f32_16x16x32_bf16 v[8:11], v[154:157], v[206:209], v[8:11]
	s_setprio 0
	s_setprio 1
	v_mfma_f32_16x16x32_bf16 v[52:55], v[158:161], v[178:181], v[52:55]
	v_mfma_f32_16x16x32_bf16 v[48:51], v[170:173], v[178:181], v[48:51]
	v_mfma_f32_16x16x32_bf16 v[36:39], v[158:161], v[186:189], v[36:39]
	v_mfma_f32_16x16x32_bf16 v[32:35], v[170:173], v[186:189], v[32:35]
	v_mfma_f32_16x16x32_bf16 v[20:23], v[158:161], v[194:197], v[20:23]
	v_mfma_f32_16x16x32_bf16 v[16:19], v[170:173], v[194:197], v[16:19]
	v_mfma_f32_16x16x32_bf16 v[4:7], v[158:161], v[202:205], v[4:7]
	v_mfma_f32_16x16x32_bf16 v[0:3], v[170:173], v[202:205], v[0:3]
	v_mfma_f32_16x16x32_bf16 v[52:55], v[166:169], v[182:185], v[52:55]
	v_mfma_f32_16x16x32_bf16 v[48:51], v[174:177], v[182:185], v[48:51]
	v_mfma_f32_16x16x32_bf16 v[36:39], v[166:169], v[190:193], v[36:39]
	v_mfma_f32_16x16x32_bf16 v[32:35], v[174:177], v[190:193], v[32:35]
	v_mfma_f32_16x16x32_bf16 v[20:23], v[166:169], v[198:201], v[20:23]
	v_mfma_f32_16x16x32_bf16 v[16:19], v[174:177], v[198:201], v[16:19]
	v_mfma_f32_16x16x32_bf16 v[4:7], v[166:169], v[206:209], v[4:7]
	v_mfma_f32_16x16x32_bf16 v[0:3], v[174:177], v[206:209], v[0:3]
	s_setprio 0
	s_barrier
; #define PG8_WAIT_V(n) asm volatile("s_waitcnt vmcnt(" #n ")" ::: "memory")
; #define PG8_WAIT_L(n) asm volatile("s_waitcnt lgkmcnt(" #n ")" ::: "memory")
; #define PG8_BAR __builtin_amdgcn_s_barrier()
; #define PG8_SCHED __builtin_amdgcn_sched_barrier(0)
;     ...
;             PG8_LDB(B0, 1, 0); PG8_LDB(B1, 1, 1); PG8_SCHED; PG8_LDA(At, 1, 0); PG8_STAGE(PG8_SA(0, 1), a2 + hstepA, voffA);
;             PG8_WAIT_V(8); PG8_WAIT_L(0); PG8_BAR; PG8_MMA(0, 0, At, B0); PG8_MMA(0, 1, At, B1); PG8_BAR; PG8_SCHED;
;             if constexpr (!HALFU) PG8_LDA(At, 1, 1); PG8_STAGE(PG8_SB(1, 0), b3, voffB); PG8_STAGE(PG8_SB(1, 1), b3 + hstep, voffB); PG8_STAGE(PG8_SA(1, 0), a3, voffA);
;             PG8_WAIT_V(8); PG8_WAIT_L(0); PG8_BAR; if constexpr (!HALFU) { PG8_MMA(1, 0, At, B0); PG8_MMA(1, 1, At, B1); } PG8_BAR; PG8_SCHED;
	s_add_i32 s54, 0, 0x18000
	v_add_u32_e32 v144, s54, v162
	s_add_i32 s55, 0, 0x1c000
	ds_read_b128 v[128:131], v144
	ds_read_b128 v[132:135], v144 offset:1024
	ds_read_b128 v[150:153], v144 offset:2048
	ds_read_b128 v[154:157], v144 offset:3072
	v_add_u32_e32 v144, s55, v162
	ds_read_b128 v[158:161], v144
	ds_read_b128 v[166:169], v144 offset:1024
	ds_read_b128 v[170:173], v144 offset:2048
	ds_read_b128 v[174:177], v144 offset:3072
	s_add_u32 s10, s50, 0x100000
	s_addc_u32 s11, s51, 0
	s_mov_b32 m0, s63
	ds_read_b128 v[178:181], v165 offset:32768
	ds_read_b128 v[182:185], v165 offset:33792
	ds_read_b128 v[186:189], v165 offset:34816
	ds_read_b128 v[190:193], v165 offset:35840
	ds_read_b128 v[194:197], v165 offset:36864
	ds_read_b128 v[198:201], v165 offset:37888
	ds_read_b128 v[202:205], v165 offset:38912
	ds_read_b128 v[206:209], v165 offset:39936
	global_load_lds_dwordx4 v136, s[10:11]
	s_mov_b32 m0, s64
	s_nop 0
	global_load_lds_dwordx4 v140, s[10:11]
	s_mov_b32 m0, s37
	s_nop 0
	global_load_lds_dwordx4 v136, s[50:51]
	s_mov_b32 m0, s62
	s_nop 0
	global_load_lds_dwordx4 v140, s[50:51]
	s_waitcnt vmcnt(8)
	s_waitcnt lgkmcnt(0)
	s_barrier
	s_setprio 1
	s_waitcnt lgkmcnt(0)
	v_mfma_f32_16x16x32_bf16 v[124:127], v[128:131], v[178:181], v[124:127]
	v_mfma_f32_16x16x32_bf16 v[120:123], v[150:153], v[178:181], v[120:123]
	v_mfma_f32_16x16x32_bf16 v[108:111], v[128:131], v[186:189], v[108:111]
	v_mfma_f32_16x16x32_bf16 v[104:107], v[150:153], v[186:189], v[104:107]
	v_mfma_f32_16x16x32_bf16 v[92:95], v[128:131], v[194:197], v[92:95]
	v_mfma_f32_16x16x32_bf16 v[88:91], v[150:153], v[194:197], v[88:91]
	v_mfma_f32_16x16x32_bf16 v[76:79], v[128:131], v[202:205], v[76:79]
	v_mfma_f32_16x16x32_bf16 v[72:75], v[150:153], v[202:205], v[72:75]
	v_mfma_f32_16x16x32_bf16 v[124:127], v[132:135], v[182:185], v[124:127]
	v_mfma_f32_16x16x32_bf16 v[120:123], v[154:157], v[182:185], v[120:123]
	v_mfma_f32_16x16x32_bf16 v[108:111], v[132:135], v[190:193], v[108:111]
	v_mfma_f32_16x16x32_bf16 v[104:107], v[154:157], v[190:193], v[104:107]
	v_mfma_f32_16x16x32_bf16 v[92:95], v[132:135], v[198:201], v[92:95]
	v_mfma_f32_16x16x32_bf16 v[88:91], v[154:157], v[198:201], v[88:91]
	v_mfma_f32_16x16x32_bf16 v[76:79], v[132:135], v[206:209], v[76:79]
	v_mfma_f32_16x16x32_bf16 v[72:75], v[154:157], v[206:209], v[72:75]
	s_setprio 0
	s_setprio 1
	v_mfma_f32_16x16x32_bf16 v[116:119], v[158:161], v[178:181], v[116:119]
	v_mfma_f32_16x16x32_bf16 v[112:115], v[170:173], v[178:181], v[112:115]
	v_mfma_f32_16x16x32_bf16 v[100:103], v[158:161], v[186:189], v[100:103]
	v_mfma_f32_16x16x32_bf16 v[96:99], v[170:173], v[186:189], v[96:99]
	v_mfma_f32_16x16x32_bf16 v[84:87], v[158:161], v[194:197], v[84:87]
	v_mfma_f32_16x16x32_bf16 v[80:83], v[170:173], v[194:197], v[80:83]
	v_mfma_f32_16x16x32_bf16 v[68:71], v[158:161], v[202:205], v[68:71]
	v_mfma_f32_16x16x32_bf16 v[64:67], v[170:173], v[202:205], v[64:67]
	v_mfma_f32_16x16x32_bf16 v[116:119], v[166:169], v[182:185], v[116:119]
	v_mfma_f32_16x16x32_bf16 v[112:115], v[174:177], v[182:185], v[112:115]
	v_mfma_f32_16x16x32_bf16 v[100:103], v[166:169], v[190:193], v[100:103]
	v_mfma_f32_16x16x32_bf16 v[96:99], v[174:177], v[190:193], v[96:99]
	v_mfma_f32_16x16x32_bf16 v[84:87], v[166:169], v[198:201], v[84:87]
	v_mfma_f32_16x16x32_bf16 v[80:83], v[174:177], v[198:201], v[80:83]
	v_mfma_f32_16x16x32_bf16 v[68:71], v[166:169], v[206:209], v[68:71]
	v_mfma_f32_16x16x32_bf16 v[64:67], v[174:177], v[206:209], v[64:67]
	s_setprio 0
	s_barrier
	s_add_u32 s10, s48, 0x80
	s_addc_u32 s11, s49, 0
	s_add_i32 s50, s54, s21
	s_mov_b32 m0, s50
	ds_read_b128 v[178:181], v165 offset:49152
	ds_read_b128 v[182:185], v165 offset:50176
	ds_read_b128 v[186:189], v165 offset:51200
	ds_read_b128 v[190:193], v165 offset:52224
	ds_read_b128 v[194:197], v165 offset:53248
	ds_read_b128 v[198:201], v165 offset:54272
	ds_read_b128 v[202:205], v165 offset:55296
	ds_read_b128 v[206:209], v165 offset:56320
	global_load_lds_dwordx4 v138, s[10:11]
	s_add_i32 m0, s50, 0x2000
	v_lshl_add_u64 v[210:211], s[10:11], 0, v[142:143]
	s_add_u32 s10, s48, 0x100080
	s_addc_u32 s11, s49, 0
	s_add_i32 s48, s55, s21
	global_load_lds_dwordx4 v[210:211], off
	s_mov_b32 m0, s48
	s_nop 0
	global_load_lds_dwordx4 v138, s[10:11]
	s_add_i32 m0, s48, 0x2000
	s_nop 0
	global_load_lds_dwordx4 v142, s[10:11]
	s_waitcnt vmcnt(4)
	s_waitcnt lgkmcnt(0)
	s_barrier
	s_setprio 1
	s_waitcnt lgkmcnt(0)
	v_mfma_f32_16x16x32_bf16 v[60:63], v[128:131], v[178:181], v[60:63]
	v_mfma_f32_16x16x32_bf16 v[56:59], v[150:153], v[178:181], v[56:59]
	v_mfma_f32_16x16x32_bf16 v[44:47], v[128:131], v[186:189], v[44:47]
	v_mfma_f32_16x16x32_bf16 v[40:43], v[150:153], v[186:189], v[40:43]
	v_mfma_f32_16x16x32_bf16 v[28:31], v[128:131], v[194:197], v[28:31]
	v_mfma_f32_16x16x32_bf16 v[24:27], v[150:153], v[194:197], v[24:27]
	v_mfma_f32_16x16x32_bf16 v[12:15], v[128:131], v[202:205], v[12:15]
	v_mfma_f32_16x16x32_bf16 v[8:11], v[150:153], v[202:205], v[8:11]
	v_mfma_f32_16x16x32_bf16 v[60:63], v[132:135], v[182:185], v[60:63]
	v_mfma_f32_16x16x32_bf16 v[56:59], v[154:157], v[182:185], v[56:59]
	v_mfma_f32_16x16x32_bf16 v[44:47], v[132:135], v[190:193], v[44:47]
	v_mfma_f32_16x16x32_bf16 v[40:43], v[154:157], v[190:193], v[40:43]
	v_mfma_f32_16x16x32_bf16 v[28:31], v[132:135], v[198:201], v[28:31]
	v_mfma_f32_16x16x32_bf16 v[24:27], v[154:157], v[198:201], v[24:27]
	v_mfma_f32_16x16x32_bf16 v[12:15], v[132:135], v[206:209], v[12:15]
	v_mfma_f32_16x16x32_bf16 v[8:11], v[154:157], v[206:209], v[8:11]
	s_setprio 0
	s_setprio 1
	v_mfma_f32_16x16x32_bf16 v[52:55], v[158:161], v[178:181], v[52:55]
	v_mfma_f32_16x16x32_bf16 v[48:51], v[170:173], v[178:181], v[48:51]
	v_mfma_f32_16x16x32_bf16 v[36:39], v[158:161], v[186:189], v[36:39]
	v_mfma_f32_16x16x32_bf16 v[32:35], v[170:173], v[186:189], v[32:35]
	v_mfma_f32_16x16x32_bf16 v[20:23], v[158:161], v[194:197], v[20:23]
	v_mfma_f32_16x16x32_bf16 v[16:19], v[170:173], v[194:197], v[16:19]
	v_mfma_f32_16x16x32_bf16 v[4:7], v[158:161], v[202:205], v[4:7]
	v_mfma_f32_16x16x32_bf16 v[0:3], v[170:173], v[202:205], v[0:3]
	v_mfma_f32_16x16x32_bf16 v[52:55], v[166:169], v[182:185], v[52:55]
	v_mfma_f32_16x16x32_bf16 v[48:51], v[174:177], v[182:185], v[48:51]
	v_mfma_f32_16x16x32_bf16 v[36:39], v[166:169], v[190:193], v[36:39]
	v_mfma_f32_16x16x32_bf16 v[32:35], v[174:177], v[190:193], v[32:35]
	v_mfma_f32_16x16x32_bf16 v[20:23], v[166:169], v[198:201], v[20:23]
	v_mfma_f32_16x16x32_bf16 v[16:19], v[174:177], v[198:201], v[16:19]
	v_mfma_f32_16x16x32_bf16 v[4:7], v[166:169], v[206:209], v[4:7]
	v_mfma_f32_16x16x32_bf16 v[0:3], v[174:177], v[206:209], v[0:3]
	s_setprio 0
	s_barrier
	s_add_i32 s53, s53, 2
	s_add_u32 s41, s41, 0x100
	s_addc_u32 s52, s52, 0
	s_cmp_gt_u32 s53, 61
	s_mov_b64 s[10:11], s[12:13]
	s_cbranch_scc0 .LBB0_1370
	s_and_b64 vcc, exec, s[28:29]
	s_cbranch_vccz .LBB0_1373
	s_barrier

; #define PG8_WAIT_V(n) asm volatile("s_waitcnt vmcnt(" #n ")" ::: "memory")
; #define PG8_WAIT_L(n) asm volatile("s_waitcnt lgkmcnt(" #n ")" ::: "memory")
; #define PG8_BAR __builtin_amdgcn_s_barrier()
; #define PG8_SCHED __builtin_amdgcn_sched_barrier(0)
;     ...
;             const char* a1 = cA + (size_t)(t + 1) * kstep;
;             const char* a2 = last ? nA : cA + (size_t)(t + 2) * kstep; const char* b2 = last ? nB : cB + (size_t)(t + 2) * kstep;
;             const char* a3 = a2 + kstep; const char* b3 = b2 + kstep;
;             if (last && has_next) S.a_ready(nxt);
;             if constexpr (SP2) {
;             PG8_LDB(B0, 0, 0); PG8_LDB(B1, 0, 1); PG8_SCHED; PG8_LDA(At, 0, 0); PG8_STAGE(PG8_SA(1, 1), a1 + hstepA, voffA);
;             PG8_WAIT_V(8); PG8_WAIT_L(0); PG8_BAR; PG8_MMA(0, 0, At, B0); PG8_MMA(0, 1, At, B1); PG8_BAR; PG8_SCHED;
;             if constexpr (!HALFU) PG8_LDA(At, 0, 1); PG8_STAGE(PG8_SB(0, 0), b2, voffB); PG8_STAGE(PG8_SB(0, 1), b2 + hstep, voffB); PG8_STAGE(PG8_SA(0, 0), a2, voffA);
;             PG8_WAIT_V(8); PG8_WAIT_L(0); PG8_BAR; if constexpr (!HALFU) { PG8_MMA(1, 0, At, B0); PG8_MMA(1, 1, At, B1); } PG8_BAR; PG8_SCHED;
.LBB0_3426:
	s_sub_u32 s98, s28, 0x80000
	s_subb_u32 s99, s29, 0
	ds_read_b128 v[142:145], v137
	ds_read_b128 v[146:149], v137 offset:1024
	ds_read_b128 v[150:153], v137 offset:2048
	ds_read_b128 v[154:157], v137 offset:3072
	ds_read_b128 v[158:161], v138
	ds_read_b128 v[162:165], v138 offset:1024
	ds_read_b128 v[166:169], v138 offset:2048
	ds_read_b128 v[170:173], v138 offset:3072
	s_cmp_eq_u32 s62, 28
	s_cselect_b32 s38, s55, s57
	s_cselect_b32 s39, s23, s59
	s_cselect_b32 s36, s56, s60
	s_cselect_b32 s37, s21, s61
	s_add_u32 s30, s38, 0x80
	s_addc_u32 s31, s39, 0
	s_add_i32 m0, s43, 0xc000
	ds_read_b128 v[174:177], v139
	ds_read_b128 v[178:181], v139 offset:1024
	ds_read_b128 v[182:185], v139 offset:2048
	ds_read_b128 v[186:189], v139 offset:3072
	ds_read_b128 v[190:193], v139 offset:4096
	ds_read_b128 v[194:197], v139 offset:5120
	ds_read_b128 v[198:201], v139 offset:6144
	ds_read_b128 v[202:205], v139 offset:7168
	global_load_lds_dwordx4 v128, s[28:29]
	s_add_i32 m0, s43, 0xe000
	s_nop 0
	global_load_lds_dwordx4 v130, s[28:29]
	s_mov_b32 m0, s50
	s_nop 0
	global_load_lds_dwordx4 v128, s[98:99]
	s_mov_b32 m0, s51
	s_nop 0
	global_load_lds_dwordx4 v130, s[98:99]
	s_waitcnt vmcnt(8)
	s_waitcnt lgkmcnt(0)
	s_barrier
	s_setprio 1
	s_waitcnt lgkmcnt(0)
	v_mfma_scale_f32_16x16x128_f8f6f4 v[124:127], v[142:149], v[174:181], v[124:127], v140, v140 op_sel_hi:[0,0,0]
	v_mfma_scale_f32_16x16x128_f8f6f4 v[120:123], v[150:157], v[174:181], v[120:123], v140, v140 op_sel_hi:[0,0,0]
	v_mfma_scale_f32_16x16x128_f8f6f4 v[112:115], v[142:149], v[182:189], v[112:115], v140, v140 op_sel_hi:[0,0,0]
	v_mfma_scale_f32_16x16x128_f8f6f4 v[104:107], v[150:157], v[182:189], v[104:107], v140, v140 op_sel_hi:[0,0,0]
	v_mfma_scale_f32_16x16x128_f8f6f4 v[96:99], v[142:149], v[190:197], v[96:99], v140, v140 op_sel_hi:[0,0,0]
	v_mfma_scale_f32_16x16x128_f8f6f4 v[206:209], v[150:157], v[190:197], v[88:91], v140, v140 op_sel_hi:[0,0,0]
	v_mfma_scale_f32_16x16x128_f8f6f4 v[210:213], v[142:149], v[198:205], v[80:83], v140, v140 op_sel_hi:[0,0,0]
	v_mfma_scale_f32_16x16x128_f8f6f4 v[214:217], v[150:157], v[198:205], v[72:75], v140, v140 op_sel_hi:[0,0,0]
	s_setprio 0
	s_setprio 1
	v_mfma_scale_f32_16x16x128_f8f6f4 v[116:119], v[158:165], v[174:181], v[116:119], v140, v140 op_sel_hi:[0,0,0]
	v_mfma_scale_f32_16x16x128_f8f6f4 v[108:111], v[166:173], v[174:181], v[108:111], v140, v140 op_sel_hi:[0,0,0]
	v_mfma_scale_f32_16x16x128_f8f6f4 v[100:103], v[158:165], v[182:189], v[100:103], v140, v140 op_sel_hi:[0,0,0]
	v_mfma_scale_f32_16x16x128_f8f6f4 v[174:177], v[166:173], v[182:189], v[92:95], v140, v140 op_sel_hi:[0,0,0]
	v_mfma_scale_f32_16x16x128_f8f6f4 v[178:181], v[158:165], v[190:197], v[84:87], v140, v140 op_sel_hi:[0,0,0]
	v_mfma_scale_f32_16x16x128_f8f6f4 v[182:185], v[166:173], v[190:197], v[76:79], v140, v140 op_sel_hi:[0,0,0]
	v_mfma_scale_f32_16x16x128_f8f6f4 v[186:189], v[158:165], v[198:205], v[68:71], v140, v140 op_sel_hi:[0,0,0]
	v_mfma_scale_f32_16x16x128_f8f6f4 v[190:193], v[166:173], v[198:205], v[64:67], v140, v140 op_sel_hi:[0,0,0]
	s_setprio 0
	s_barrier
	s_add_i32 s63, s53, s41
	s_mov_b32 m0, s63
	s_nop 1
	ds_read_b128 v[64:67], v139 offset:16384
	ds_read_b128 v[68:71], v139 offset:17408
	ds_read_b128 v[72:75], v139 offset:18432
	ds_read_b128 v[76:79], v139 offset:19456
	ds_read_b128 v[80:83], v139 offset:20480
	ds_read_b128 v[84:87], v139 offset:21504
	ds_read_b128 v[88:91], v139 offset:22528
	ds_read_b128 v[92:95], v139 offset:23552
	global_load_lds_dwordx4 v128, s[36:37]
	s_add_i32 m0, s63, 0x2000
	s_add_u32 s64, s36, 0x80000
	s_addc_u32 s65, s37, 0
	s_add_i32 s63, s54, s41
	global_load_lds_dwordx4 v130, s[36:37]
	s_mov_b32 m0, s63
	s_nop 0
	global_load_lds_dwordx4 v128, s[64:65]
	s_add_i32 m0, s63, 0x2000
	s_nop 0
	global_load_lds_dwordx4 v130, s[64:65]
	s_waitcnt vmcnt(4)
	s_waitcnt lgkmcnt(0)
	s_barrier
	s_setprio 1
	s_waitcnt lgkmcnt(0)
	v_mfma_scale_f32_16x16x128_f8f6f4 v[60:63], v[142:149], v[64:71], v[60:63], v140, v140 op_sel_hi:[0,0,0]
	v_mfma_scale_f32_16x16x128_f8f6f4 v[56:59], v[150:157], v[64:71], v[56:59], v140, v140 op_sel_hi:[0,0,0]
	v_mfma_scale_f32_16x16x128_f8f6f4 v[48:51], v[142:149], v[72:79], v[48:51], v140, v140 op_sel_hi:[0,0,0]
	v_mfma_scale_f32_16x16x128_f8f6f4 v[194:197], v[150:157], v[72:79], v[40:43], v140, v140 op_sel_hi:[0,0,0]
	v_mfma_scale_f32_16x16x128_f8f6f4 v[198:201], v[142:149], v[80:87], v[32:35], v140, v140 op_sel_hi:[0,0,0]
	v_mfma_scale_f32_16x16x128_f8f6f4 v[202:205], v[150:157], v[80:87], v[24:27], v140, v140 op_sel_hi:[0,0,0]
	v_mfma_scale_f32_16x16x128_f8f6f4 v[218:221], v[142:149], v[88:95], v[16:19], v140, v140 op_sel_hi:[0,0,0]
	v_mfma_scale_f32_16x16x128_f8f6f4 v[222:225], v[150:157], v[88:95], v[8:11], v140, v140 op_sel_hi:[0,0,0]
	s_setprio 0
	s_setprio 1
	v_mfma_scale_f32_16x16x128_f8f6f4 v[52:55], v[158:165], v[64:71], v[52:55], v140, v140 op_sel_hi:[0,0,0]
	v_mfma_scale_f32_16x16x128_f8f6f4 v[226:229], v[166:173], v[64:71], v[44:47], v140, v140 op_sel_hi:[0,0,0]
	v_mfma_scale_f32_16x16x128_f8f6f4 v[230:233], v[158:165], v[72:79], v[36:39], v140, v140 op_sel_hi:[0,0,0]
	v_mfma_scale_f32_16x16x128_f8f6f4 v[234:237], v[166:173], v[72:79], v[28:31], v140, v140 op_sel_hi:[0,0,0]
	v_mfma_scale_f32_16x16x128_f8f6f4 v[238:241], v[158:165], v[80:87], v[20:23], v140, v140 op_sel_hi:[0,0,0]
	v_mfma_scale_f32_16x16x128_f8f6f4 v[242:245], v[166:173], v[80:87], v[12:15], v140, v140 op_sel_hi:[0,0,0]
	v_mfma_scale_f32_16x16x128_f8f6f4 v[246:249], v[158:165], v[88:95], v[4:7], v140, v140 op_sel_hi:[0,0,0]
	v_mfma_scale_f32_16x16x128_f8f6f4 v[250:253], v[166:173], v[88:95], v[0:3], v140, v140 op_sel_hi:[0,0,0]
	s_setprio 0
	s_barrier
; #define PG8_WAIT_V(n) asm volatile("s_waitcnt vmcnt(" #n ")" ::: "memory")
; #define PG8_WAIT_L(n) asm volatile("s_waitcnt lgkmcnt(" #n ")" ::: "memory")
; #define PG8_BAR __builtin_amdgcn_s_barrier()
; #define PG8_SCHED __builtin_amdgcn_sched_barrier(0)
;     ...
;             PG8_LDB(B0, 1, 0); PG8_LDB(B1, 1, 1); PG8_SCHED; PG8_LDA(At, 1, 0); PG8_STAGE(PG8_SA(0, 1), a2 + hstepA, voffA);
;             PG8_WAIT_V(8); PG8_WAIT_L(0); PG8_BAR; PG8_MMA(0, 0, At, B0); PG8_MMA(0, 1, At, B1); PG8_BAR; PG8_SCHED;
;             if constexpr (!HALFU) PG8_LDA(At, 1, 1); PG8_STAGE(PG8_SB(1, 0), b3, voffB); PG8_STAGE(PG8_SB(1, 1), b3 + hstep, voffB); PG8_STAGE(PG8_SA(1, 0), a3, voffA);
;             PG8_WAIT_V(8); PG8_WAIT_L(0); PG8_BAR; if constexpr (!HALFU) { PG8_MMA(1, 0, At, B0); PG8_MMA(1, 1, At, B1); } PG8_BAR; PG8_SCHED;
	s_mov_b32 m0, s43
	s_nop 0
	global_load_lds_dwordx4 v128, s[38:39]
	s_mov_b32 m0, s44
	s_nop 0
	global_load_lds_dwordx4 v130, s[38:39]
	s_add_i32 s63, 0, 0x18000
	s_add_i32 s64, 0, 0x1c000
	s_nop 0
	v_add_u32_e32 v12, s63, v136
	v_add_u32_e32 v16, s64, v136
	ds_read_b128 v[0:3], v12
	ds_read_b128 v[4:7], v12 offset:1024
	ds_read_b128 v[8:11], v12 offset:2048
	ds_read_b128 v[12:15], v12 offset:3072
	ds_read_b128 v[142:145], v16
	ds_read_b128 v[146:149], v16 offset:1024
	ds_read_b128 v[150:153], v16 offset:2048
	ds_read_b128 v[154:157], v16 offset:3072
	s_add_u32 s38, s38, 0x80000
	s_addc_u32 s39, s39, 0
	s_mov_b32 m0, s45
	ds_read_b128 v[16:19], v139 offset:32768
	ds_read_b128 v[20:23], v139 offset:33792
	ds_read_b128 v[24:27], v139 offset:34816
	ds_read_b128 v[28:31], v139 offset:35840
	ds_read_b128 v[32:35], v139 offset:36864
	ds_read_b128 v[36:39], v139 offset:37888
	ds_read_b128 v[40:43], v139 offset:38912
	ds_read_b128 v[44:47], v139 offset:39936
	global_load_lds_dwordx4 v128, s[38:39]
	s_mov_b32 m0, s46
	s_nop 0
	global_load_lds_dwordx4 v130, s[38:39]
	s_waitcnt vmcnt(8)
	s_waitcnt lgkmcnt(0)
	s_barrier
	s_setprio 1
	s_waitcnt lgkmcnt(0)
	v_mfma_scale_f32_16x16x128_f8f6f4 v[124:127], v[0:7], v[16:23], v[124:127], v140, v140 op_sel_hi:[0,0,0]
	v_mfma_scale_f32_16x16x128_f8f6f4 v[120:123], v[8:15], v[16:23], v[120:123], v140, v140 op_sel_hi:[0,0,0]
	v_mfma_scale_f32_16x16x128_f8f6f4 v[112:115], v[0:7], v[24:31], v[112:115], v140, v140 op_sel_hi:[0,0,0]
	v_mfma_scale_f32_16x16x128_f8f6f4 v[104:107], v[8:15], v[24:31], v[104:107], v140, v140 op_sel_hi:[0,0,0]
	v_mfma_scale_f32_16x16x128_f8f6f4 v[96:99], v[0:7], v[32:39], v[96:99], v140, v140 op_sel_hi:[0,0,0]
	v_mfma_scale_f32_16x16x128_f8f6f4 v[88:91], v[8:15], v[32:39], v[206:209], v140, v140 op_sel_hi:[0,0,0]
	v_mfma_scale_f32_16x16x128_f8f6f4 v[80:83], v[0:7], v[40:47], v[210:213], v140, v140 op_sel_hi:[0,0,0]
	v_mfma_scale_f32_16x16x128_f8f6f4 v[72:75], v[8:15], v[40:47], v[214:217], v140, v140 op_sel_hi:[0,0,0]
	s_setprio 0
	s_setprio 1
	v_mfma_scale_f32_16x16x128_f8f6f4 v[116:119], v[142:149], v[16:23], v[116:119], v140, v140 op_sel_hi:[0,0,0]
	v_mfma_scale_f32_16x16x128_f8f6f4 v[108:111], v[150:157], v[16:23], v[108:111], v140, v140 op_sel_hi:[0,0,0]
	v_mfma_scale_f32_16x16x128_f8f6f4 v[100:103], v[142:149], v[24:31], v[100:103], v140, v140 op_sel_hi:[0,0,0]
	v_mfma_scale_f32_16x16x128_f8f6f4 v[92:95], v[150:157], v[24:31], v[174:177], v140, v140 op_sel_hi:[0,0,0]
	v_mfma_scale_f32_16x16x128_f8f6f4 v[84:87], v[142:149], v[32:39], v[178:181], v140, v140 op_sel_hi:[0,0,0]
	v_mfma_scale_f32_16x16x128_f8f6f4 v[76:79], v[150:157], v[32:39], v[182:185], v140, v140 op_sel_hi:[0,0,0]
	v_mfma_scale_f32_16x16x128_f8f6f4 v[68:71], v[142:149], v[40:47], v[186:189], v140, v140 op_sel_hi:[0,0,0]
	v_mfma_scale_f32_16x16x128_f8f6f4 v[64:67], v[150:157], v[40:47], v[190:193], v140, v140 op_sel_hi:[0,0,0]
	s_setprio 0
	s_barrier
	s_add_u32 s38, s36, 0x80
	s_addc_u32 s39, s37, 0
	s_add_i32 s63, s63, s41
	s_mov_b32 m0, s63
	ds_read_b128 v[158:161], v139 offset:49152
	ds_read_b128 v[162:165], v139 offset:50176
	ds_read_b128 v[166:169], v139 offset:51200
	ds_read_b128 v[170:173], v139 offset:52224
	ds_read_b128 v[174:177], v139 offset:53248
	ds_read_b128 v[178:181], v139 offset:54272
	ds_read_b128 v[182:185], v139 offset:55296
	ds_read_b128 v[186:189], v139 offset:56320
	global_load_lds_dwordx4 v128, s[38:39]
	s_add_i32 m0, s63, 0x2000
	s_add_u32 s36, s36, 0x80080
	v_lshl_add_u64 v[16:17], s[38:39], 0, v[130:131]
	s_addc_u32 s37, s37, 0
	s_add_i32 s38, s64, s41
	global_load_lds_dwordx4 v[16:17], off
	s_mov_b32 m0, s38
	s_nop 0
	global_load_lds_dwordx4 v128, s[36:37]
	s_add_i32 m0, s38, 0x2000
	s_nop 0
	global_load_lds_dwordx4 v130, s[36:37]
	s_waitcnt vmcnt(4)
	s_waitcnt lgkmcnt(0)
	s_barrier
	s_setprio 1
	s_waitcnt lgkmcnt(0)
	v_mfma_scale_f32_16x16x128_f8f6f4 v[60:63], v[0:7], v[158:165], v[60:63], v140, v140 op_sel_hi:[0,0,0]
	v_mfma_scale_f32_16x16x128_f8f6f4 v[56:59], v[8:15], v[158:165], v[56:59], v140, v140 op_sel_hi:[0,0,0]
	v_mfma_scale_f32_16x16x128_f8f6f4 v[48:51], v[0:7], v[166:173], v[48:51], v140, v140 op_sel_hi:[0,0,0]
	v_mfma_scale_f32_16x16x128_f8f6f4 v[40:43], v[8:15], v[166:173], v[194:197], v140, v140 op_sel_hi:[0,0,0]
	v_mfma_scale_f32_16x16x128_f8f6f4 v[32:35], v[0:7], v[174:181], v[198:201], v140, v140 op_sel_hi:[0,0,0]
	v_mfma_scale_f32_16x16x128_f8f6f4 v[24:27], v[8:15], v[174:181], v[202:205], v140, v140 op_sel_hi:[0,0,0]
	v_mfma_scale_f32_16x16x128_f8f6f4 v[16:19], v[0:7], v[182:189], v[218:221], v140, v140 op_sel_hi:[0,0,0]
	v_mfma_scale_f32_16x16x128_f8f6f4 v[8:11], v[8:15], v[182:189], v[222:225], v140, v140 op_sel_hi:[0,0,0]
	s_setprio 0
	s_setprio 1
	v_mfma_scale_f32_16x16x128_f8f6f4 v[52:55], v[142:149], v[158:165], v[52:55], v140, v140 op_sel_hi:[0,0,0]
	v_mfma_scale_f32_16x16x128_f8f6f4 v[44:47], v[150:157], v[158:165], v[226:229], v140, v140 op_sel_hi:[0,0,0]
	v_mfma_scale_f32_16x16x128_f8f6f4 v[36:39], v[142:149], v[166:173], v[230:233], v140, v140 op_sel_hi:[0,0,0]
	v_mfma_scale_f32_16x16x128_f8f6f4 v[28:31], v[150:157], v[166:173], v[234:237], v140, v140 op_sel_hi:[0,0,0]
	v_mfma_scale_f32_16x16x128_f8f6f4 v[20:23], v[142:149], v[174:181], v[238:241], v140, v140 op_sel_hi:[0,0,0]
	v_mfma_scale_f32_16x16x128_f8f6f4 v[12:15], v[150:157], v[174:181], v[242:245], v140, v140 op_sel_hi:[0,0,0]
	v_mfma_scale_f32_16x16x128_f8f6f4 v[4:7], v[142:149], v[182:189], v[246:249], v140, v140 op_sel_hi:[0,0,0]
	v_mfma_scale_f32_16x16x128_f8f6f4 v[0:3], v[150:157], v[182:189], v[250:253], v140, v140 op_sel_hi:[0,0,0]
	s_setprio 0
	s_barrier
	s_add_i32 s62, s62, 2
	s_add_u32 s57, s57, 0x100
	s_addc_u32 s59, s59, 0
	s_add_u32 s60, s60, 0x100
	s_addc_u32 s61, s61, 0
	s_add_u32 s28, s28, 0x100
	s_addc_u32 s29, s29, 0
	s_cmp_gt_u32 s62, 29
	s_cbranch_scc0 .LBB0_3426
	s_and_b64 vcc, exec, s[6:7]
	s_cbranch_vccz .LBB0_3429
	s_barrier

; #define PG8_WAIT_V(n) asm volatile("s_waitcnt vmcnt(" #n ")" ::: "memory")
; #define PG8_WAIT_L(n) asm volatile("s_waitcnt lgkmcnt(" #n ")" ::: "memory")
; #define PG8_BAR __builtin_amdgcn_s_barrier()
; #define PG8_SCHED __builtin_amdgcn_sched_barrier(0)
;     ...
;             const char* a1 = cA + (size_t)(t + 1) * kstep;
;             const char* a2 = last ? nA : cA + (size_t)(t + 2) * kstep; const char* b2 = last ? nB : cB + (size_t)(t + 2) * kstep;
;             const char* a3 = a2 + kstep; const char* b3 = b2 + kstep;
;             if (last && has_next) S.a_ready(nxt);
;             if constexpr (SP2) {
;             PG8_LDB(B0, 0, 0); PG8_LDB(B1, 0, 1); PG8_SCHED; PG8_LDA(At, 0, 0); PG8_STAGE(PG8_SA(1, 1), a1 + hstepA, voffA);
;             PG8_WAIT_V(8); PG8_WAIT_L(0); PG8_BAR; PG8_MMA(0, 0, At, B0); PG8_MMA(0, 1, At, B1); PG8_BAR; PG8_SCHED;
;             if constexpr (!HALFU) PG8_LDA(At, 0, 1); PG8_STAGE(PG8_SB(0, 0), b2, voffB); PG8_STAGE(PG8_SB(0, 1), b2 + hstep, voffB); PG8_STAGE(PG8_SA(0, 0), a2, voffA);
;             PG8_WAIT_V(8); PG8_WAIT_L(0); PG8_BAR; if constexpr (!HALFU) { PG8_MMA(1, 0, At, B0); PG8_MMA(1, 1, At, B1); } PG8_BAR; PG8_SCHED;
.LBB0_3554:
	s_add_u32 s98, s24, 0x80
	s_addc_u32 s99, s25, 0
	ds_read_b128 v[144:147], v141
	ds_read_b128 v[148:151], v141 offset:1024
	ds_read_b128 v[152:155], v141 offset:2048
	ds_read_b128 v[156:159], v141 offset:3072
	ds_read_b128 v[160:163], v142
	ds_read_b128 v[164:167], v142 offset:1024
	ds_read_b128 v[168:171], v142 offset:2048
	ds_read_b128 v[172:175], v142 offset:3072
	s_add_u32 s26, s24, 0x100
	s_addc_u32 s27, s25, 0
	s_cmp_eq_u32 s59, 60
	s_cselect_b32 s36, s54, s26
	s_cselect_b32 s37, s15, s27
	s_cselect_b32 s30, s55, s56
	s_cselect_b32 s31, s13, s57
	s_add_u32 s28, s36, 0x80
	s_addc_u32 s29, s37, 0
	s_add_u32 s24, s24, 0x100080
	s_addc_u32 s25, s25, 0
	s_add_i32 m0, s23, 0xc000
	ds_read_b128 v[176:179], v143
	ds_read_b128 v[180:183], v143 offset:1024
	ds_read_b128 v[184:187], v143 offset:2048
	ds_read_b128 v[188:191], v143 offset:3072
	ds_read_b128 v[192:195], v143 offset:4096
	ds_read_b128 v[196:199], v143 offset:5120
	ds_read_b128 v[200:203], v143 offset:6144
	ds_read_b128 v[204:207], v143 offset:7168
	global_load_lds_dwordx4 v134, s[24:25]
	s_add_i32 m0, s23, 0xe000
	s_nop 0
	global_load_lds_dwordx4 v132, s[24:25]
	s_mov_b32 m0, s49
	s_nop 0
	global_load_lds_dwordx4 v134, s[98:99]
	s_mov_b32 m0, s50
	s_nop 0
	global_load_lds_dwordx4 v132, s[98:99]
	s_waitcnt vmcnt(8)
	s_waitcnt lgkmcnt(0)
	s_barrier
	s_setprio 1
	s_waitcnt lgkmcnt(0)
	v_mfma_f32_16x16x32_bf16 v[124:127], v[144:147], v[176:179], v[124:127]
	v_mfma_f32_16x16x32_bf16 v[120:123], v[152:155], v[176:179], v[120:123]
	v_mfma_f32_16x16x32_bf16 v[108:111], v[144:147], v[184:187], v[108:111]
	v_mfma_f32_16x16x32_bf16 v[104:107], v[152:155], v[184:187], v[104:107]
	v_mfma_f32_16x16x32_bf16 v[92:95], v[144:147], v[192:195], v[92:95]
	v_mfma_f32_16x16x32_bf16 v[88:91], v[152:155], v[192:195], v[88:91]
	v_mfma_f32_16x16x32_bf16 v[76:79], v[144:147], v[200:203], v[76:79]
	v_mfma_f32_16x16x32_bf16 v[72:75], v[152:155], v[200:203], v[72:75]
	v_mfma_f32_16x16x32_bf16 v[124:127], v[148:151], v[180:183], v[124:127]
	v_mfma_f32_16x16x32_bf16 v[120:123], v[156:159], v[180:183], v[120:123]
	v_mfma_f32_16x16x32_bf16 v[108:111], v[148:151], v[188:191], v[108:111]
	v_mfma_f32_16x16x32_bf16 v[104:107], v[156:159], v[188:191], v[104:107]
	v_mfma_f32_16x16x32_bf16 v[92:95], v[148:151], v[196:199], v[92:95]
	v_mfma_f32_16x16x32_bf16 v[88:91], v[156:159], v[196:199], v[88:91]
	v_mfma_f32_16x16x32_bf16 v[76:79], v[148:151], v[204:207], v[76:79]
	v_mfma_f32_16x16x32_bf16 v[72:75], v[156:159], v[204:207], v[72:75]
	s_setprio 0
	s_setprio 1
	v_mfma_f32_16x16x32_bf16 v[116:119], v[160:163], v[176:179], v[116:119]
	v_mfma_f32_16x16x32_bf16 v[112:115], v[168:171], v[176:179], v[112:115]
	v_mfma_f32_16x16x32_bf16 v[100:103], v[160:163], v[184:187], v[100:103]
	v_mfma_f32_16x16x32_bf16 v[96:99], v[168:171], v[184:187], v[96:99]
	v_mfma_f32_16x16x32_bf16 v[84:87], v[160:163], v[192:195], v[84:87]
	v_mfma_f32_16x16x32_bf16 v[80:83], v[168:171], v[192:195], v[80:83]
	v_mfma_f32_16x16x32_bf16 v[68:71], v[160:163], v[200:203], v[68:71]
	v_mfma_f32_16x16x32_bf16 v[64:67], v[168:171], v[200:203], v[64:67]
	v_mfma_f32_16x16x32_bf16 v[116:119], v[164:167], v[180:183], v[116:119]
	v_mfma_f32_16x16x32_bf16 v[112:115], v[172:175], v[180:183], v[112:115]
	v_mfma_f32_16x16x32_bf16 v[100:103], v[164:167], v[188:191], v[100:103]
	v_mfma_f32_16x16x32_bf16 v[96:99], v[172:175], v[188:191], v[96:99]
	v_mfma_f32_16x16x32_bf16 v[84:87], v[164:167], v[196:199], v[84:87]
	v_mfma_f32_16x16x32_bf16 v[80:83], v[172:175], v[196:199], v[80:83]
	v_mfma_f32_16x16x32_bf16 v[68:71], v[164:167], v[204:207], v[68:71]
	v_mfma_f32_16x16x32_bf16 v[64:67], v[172:175], v[204:207], v[64:67]
	s_setprio 0
	s_barrier
	s_add_i32 s24, s6, s40
	s_mov_b32 m0, s24
	ds_read_b128 v[176:179], v143 offset:16384
	ds_read_b128 v[180:183], v143 offset:17408
	ds_read_b128 v[184:187], v143 offset:18432
	ds_read_b128 v[188:191], v143 offset:19456
	ds_read_b128 v[192:195], v143 offset:20480
	ds_read_b128 v[196:199], v143 offset:21504
	ds_read_b128 v[200:203], v143 offset:22528
	ds_read_b128 v[204:207], v143 offset:23552
	global_load_lds_dwordx4 v128, s[30:31]
	s_add_i32 m0, s24, 0x2000
	s_add_u32 s24, s30, 0x100000
	s_addc_u32 s25, s31, 0
	s_add_i32 s60, s51, s40
	global_load_lds_dwordx4 v130, s[30:31]
	s_mov_b32 m0, s60
	s_nop 0
	global_load_lds_dwordx4 v128, s[24:25]
	s_add_i32 m0, s60, 0x2000
	s_nop 0
	global_load_lds_dwordx4 v130, s[24:25]
	s_waitcnt vmcnt(4)
	s_waitcnt lgkmcnt(0)
	s_barrier
	s_setprio 1
	s_waitcnt lgkmcnt(0)
	v_mfma_f32_16x16x32_bf16 v[60:63], v[144:147], v[176:179], v[60:63]
	v_mfma_f32_16x16x32_bf16 v[56:59], v[152:155], v[176:179], v[56:59]
	v_mfma_f32_16x16x32_bf16 v[44:47], v[144:147], v[184:187], v[44:47]
	v_mfma_f32_16x16x32_bf16 v[40:43], v[152:155], v[184:187], v[40:43]
	v_mfma_f32_16x16x32_bf16 v[28:31], v[144:147], v[192:195], v[28:31]
	v_mfma_f32_16x16x32_bf16 v[24:27], v[152:155], v[192:195], v[24:27]
	v_mfma_f32_16x16x32_bf16 v[12:15], v[144:147], v[200:203], v[12:15]
	v_mfma_f32_16x16x32_bf16 v[8:11], v[152:155], v[200:203], v[8:11]
	v_mfma_f32_16x16x32_bf16 v[60:63], v[148:151], v[180:183], v[60:63]
	v_mfma_f32_16x16x32_bf16 v[56:59], v[156:159], v[180:183], v[56:59]
	v_mfma_f32_16x16x32_bf16 v[44:47], v[148:151], v[188:191], v[44:47]
	v_mfma_f32_16x16x32_bf16 v[40:43], v[156:159], v[188:191], v[40:43]
	v_mfma_f32_16x16x32_bf16 v[28:31], v[148:151], v[196:199], v[28:31]
	v_mfma_f32_16x16x32_bf16 v[24:27], v[156:159], v[196:199], v[24:27]
	v_mfma_f32_16x16x32_bf16 v[12:15], v[148:151], v[204:207], v[12:15]
	v_mfma_f32_16x16x32_bf16 v[8:11], v[156:159], v[204:207], v[8:11]
	s_setprio 0
	s_setprio 1
	v_mfma_f32_16x16x32_bf16 v[52:55], v[160:163], v[176:179], v[52:55]
	v_mfma_f32_16x16x32_bf16 v[48:51], v[168:171], v[176:179], v[48:51]
	v_mfma_f32_16x16x32_bf16 v[36:39], v[160:163], v[184:187], v[36:39]
	v_mfma_f32_16x16x32_bf16 v[32:35], v[168:171], v[184:187], v[32:35]
	v_mfma_f32_16x16x32_bf16 v[20:23], v[160:163], v[192:195], v[20:23]
	v_mfma_f32_16x16x32_bf16 v[16:19], v[168:171], v[192:195], v[16:19]
	v_mfma_f32_16x16x32_bf16 v[4:7], v[160:163], v[200:203], v[4:7]
	v_mfma_f32_16x16x32_bf16 v[0:3], v[168:171], v[200:203], v[0:3]
	v_mfma_f32_16x16x32_bf16 v[52:55], v[164:167], v[180:183], v[52:55]
	v_mfma_f32_16x16x32_bf16 v[48:51], v[172:175], v[180:183], v[48:51]
	v_mfma_f32_16x16x32_bf16 v[36:39], v[164:167], v[188:191], v[36:39]
	v_mfma_f32_16x16x32_bf16 v[32:35], v[172:175], v[188:191], v[32:35]
	v_mfma_f32_16x16x32_bf16 v[20:23], v[164:167], v[196:199], v[20:23]
	v_mfma_f32_16x16x32_bf16 v[16:19], v[172:175], v[196:199], v[16:19]
	v_mfma_f32_16x16x32_bf16 v[4:7], v[164:167], v[204:207], v[4:7]
	v_mfma_f32_16x16x32_bf16 v[0:3], v[172:175], v[204:207], v[0:3]
	s_setprio 0
	s_barrier
; #define PG8_WAIT_V(n) asm volatile("s_waitcnt vmcnt(" #n ")" ::: "memory")
; #define PG8_WAIT_L(n) asm volatile("s_waitcnt lgkmcnt(" #n ")" ::: "memory")
; #define PG8_BAR __builtin_amdgcn_s_barrier()
; #define PG8_SCHED __builtin_amdgcn_sched_barrier(0)
;     ...
;             PG8_LDB(B0, 1, 0); PG8_LDB(B1, 1, 1); PG8_SCHED; PG8_LDA(At, 1, 0); PG8_STAGE(PG8_SA(0, 1), a2 + hstepA, voffA);
;             PG8_WAIT_V(8); PG8_WAIT_L(0); PG8_BAR; PG8_MMA(0, 0, At, B0); PG8_MMA(0, 1, At, B1); PG8_BAR; PG8_SCHED;
;             if constexpr (!HALFU) PG8_LDA(At, 1, 1); PG8_STAGE(PG8_SB(1, 0), b3, voffB); PG8_STAGE(PG8_SB(1, 1), b3 + hstep, voffB); PG8_STAGE(PG8_SA(1, 0), a3, voffA);
;             PG8_WAIT_V(8); PG8_WAIT_L(0); PG8_BAR; if constexpr (!HALFU) { PG8_MMA(1, 0, At, B0); PG8_MMA(1, 1, At, B1); } PG8_BAR; PG8_SCHED;
	s_add_i32 s60, 0, 0x18000
	v_add_u32_e32 v138, s60, v140
	s_add_i32 s61, 0, 0x1c000
	ds_read_b128 v[144:147], v138
	ds_read_b128 v[148:151], v138 offset:1024
	ds_read_b128 v[152:155], v138 offset:2048
	ds_read_b128 v[156:159], v138 offset:3072
	v_add_u32_e32 v138, s61, v140
	ds_read_b128 v[160:163], v138
	ds_read_b128 v[164:167], v138 offset:1024
	ds_read_b128 v[168:171], v138 offset:2048
	ds_read_b128 v[172:175], v138 offset:3072
	s_add_u32 s24, s36, 0x100000
	s_addc_u32 s25, s37, 0
	s_mov_b32 m0, s44
	ds_read_b128 v[176:179], v143 offset:32768
	ds_read_b128 v[180:183], v143 offset:33792
	ds_read_b128 v[184:187], v143 offset:34816
	ds_read_b128 v[188:191], v143 offset:35840
	ds_read_b128 v[192:195], v143 offset:36864
	ds_read_b128 v[196:199], v143 offset:37888
	ds_read_b128 v[200:203], v143 offset:38912
	ds_read_b128 v[204:207], v143 offset:39936
	global_load_lds_dwordx4 v134, s[24:25]
	s_mov_b32 m0, s45
	s_nop 0
	global_load_lds_dwordx4 v132, s[24:25]
	s_mov_b32 m0, s23
	s_nop 0
	global_load_lds_dwordx4 v134, s[36:37]
	s_mov_b32 m0, s43
	s_nop 0
	global_load_lds_dwordx4 v132, s[36:37]
	s_waitcnt vmcnt(8)
	s_waitcnt lgkmcnt(0)
	s_barrier
	s_setprio 1
	s_waitcnt lgkmcnt(0)
	v_mfma_f32_16x16x32_bf16 v[124:127], v[144:147], v[176:179], v[124:127]
	v_mfma_f32_16x16x32_bf16 v[120:123], v[152:155], v[176:179], v[120:123]
	v_mfma_f32_16x16x32_bf16 v[108:111], v[144:147], v[184:187], v[108:111]
	v_mfma_f32_16x16x32_bf16 v[104:107], v[152:155], v[184:187], v[104:107]
	v_mfma_f32_16x16x32_bf16 v[92:95], v[144:147], v[192:195], v[92:95]
	v_mfma_f32_16x16x32_bf16 v[88:91], v[152:155], v[192:195], v[88:91]
	v_mfma_f32_16x16x32_bf16 v[76:79], v[144:147], v[200:203], v[76:79]
	v_mfma_f32_16x16x32_bf16 v[72:75], v[152:155], v[200:203], v[72:75]
	v_mfma_f32_16x16x32_bf16 v[124:127], v[148:151], v[180:183], v[124:127]
	v_mfma_f32_16x16x32_bf16 v[120:123], v[156:159], v[180:183], v[120:123]
	v_mfma_f32_16x16x32_bf16 v[108:111], v[148:151], v[188:191], v[108:111]
	v_mfma_f32_16x16x32_bf16 v[104:107], v[156:159], v[188:191], v[104:107]
	v_mfma_f32_16x16x32_bf16 v[92:95], v[148:151], v[196:199], v[92:95]
	v_mfma_f32_16x16x32_bf16 v[88:91], v[156:159], v[196:199], v[88:91]
	v_mfma_f32_16x16x32_bf16 v[76:79], v[148:151], v[204:207], v[76:79]
	v_mfma_f32_16x16x32_bf16 v[72:75], v[156:159], v[204:207], v[72:75]
	s_setprio 0
	s_setprio 1
	v_mfma_f32_16x16x32_bf16 v[116:119], v[160:163], v[176:179], v[116:119]
	v_mfma_f32_16x16x32_bf16 v[112:115], v[168:171], v[176:179], v[112:115]
	v_mfma_f32_16x16x32_bf16 v[100:103], v[160:163], v[184:187], v[100:103]
	v_mfma_f32_16x16x32_bf16 v[96:99], v[168:171], v[184:187], v[96:99]
	v_mfma_f32_16x16x32_bf16 v[84:87], v[160:163], v[192:195], v[84:87]
	v_mfma_f32_16x16x32_bf16 v[80:83], v[168:171], v[192:195], v[80:83]
	v_mfma_f32_16x16x32_bf16 v[68:71], v[160:163], v[200:203], v[68:71]
	v_mfma_f32_16x16x32_bf16 v[64:67], v[168:171], v[200:203], v[64:67]
	v_mfma_f32_16x16x32_bf16 v[116:119], v[164:167], v[180:183], v[116:119]
	v_mfma_f32_16x16x32_bf16 v[112:115], v[172:175], v[180:183], v[112:115]
	v_mfma_f32_16x16x32_bf16 v[100:103], v[164:167], v[188:191], v[100:103]
	v_mfma_f32_16x16x32_bf16 v[96:99], v[172:175], v[188:191], v[96:99]
	v_mfma_f32_16x16x32_bf16 v[84:87], v[164:167], v[196:199], v[84:87]
	v_mfma_f32_16x16x32_bf16 v[80:83], v[172:175], v[196:199], v[80:83]
	v_mfma_f32_16x16x32_bf16 v[68:71], v[164:167], v[204:207], v[68:71]
	v_mfma_f32_16x16x32_bf16 v[64:67], v[172:175], v[204:207], v[64:67]
	s_setprio 0
	s_barrier
	s_add_u32 s24, s30, 0x80
	s_addc_u32 s25, s31, 0
	s_add_i32 s36, s60, s40
	s_mov_b32 m0, s36
	ds_read_b128 v[176:179], v143 offset:49152
	ds_read_b128 v[180:183], v143 offset:50176
	ds_read_b128 v[184:187], v143 offset:51200
	ds_read_b128 v[188:191], v143 offset:52224
	ds_read_b128 v[192:195], v143 offset:53248
	ds_read_b128 v[196:199], v143 offset:54272
	ds_read_b128 v[200:203], v143 offset:55296
	ds_read_b128 v[204:207], v143 offset:56320
	global_load_lds_dwordx4 v128, s[24:25]
	s_add_i32 m0, s36, 0x2000
	v_lshl_add_u64 v[138:139], s[24:25], 0, v[130:131]
	s_add_u32 s24, s30, 0x100080
	s_addc_u32 s25, s31, 0
	s_add_i32 s30, s61, s40
	global_load_lds_dwordx4 v[138:139], off
	s_mov_b32 m0, s30
	s_nop 0
	global_load_lds_dwordx4 v128, s[24:25]
	s_add_i32 m0, s30, 0x2000
	s_nop 0
	global_load_lds_dwordx4 v130, s[24:25]
	s_waitcnt vmcnt(4)
	s_waitcnt lgkmcnt(0)
	s_barrier
	s_setprio 1
	s_waitcnt lgkmcnt(0)
	v_mfma_f32_16x16x32_bf16 v[60:63], v[144:147], v[176:179], v[60:63]
	v_mfma_f32_16x16x32_bf16 v[56:59], v[152:155], v[176:179], v[56:59]
	v_mfma_f32_16x16x32_bf16 v[44:47], v[144:147], v[184:187], v[44:47]
	v_mfma_f32_16x16x32_bf16 v[40:43], v[152:155], v[184:187], v[40:43]
	v_mfma_f32_16x16x32_bf16 v[28:31], v[144:147], v[192:195], v[28:31]
	v_mfma_f32_16x16x32_bf16 v[24:27], v[152:155], v[192:195], v[24:27]
	v_mfma_f32_16x16x32_bf16 v[12:15], v[144:147], v[200:203], v[12:15]
	v_mfma_f32_16x16x32_bf16 v[8:11], v[152:155], v[200:203], v[8:11]
	v_mfma_f32_16x16x32_bf16 v[60:63], v[148:151], v[180:183], v[60:63]
	v_mfma_f32_16x16x32_bf16 v[56:59], v[156:159], v[180:183], v[56:59]
	v_mfma_f32_16x16x32_bf16 v[44:47], v[148:151], v[188:191], v[44:47]
	v_mfma_f32_16x16x32_bf16 v[40:43], v[156:159], v[188:191], v[40:43]
	v_mfma_f32_16x16x32_bf16 v[28:31], v[148:151], v[196:199], v[28:31]
	v_mfma_f32_16x16x32_bf16 v[24:27], v[156:159], v[196:199], v[24:27]
	v_mfma_f32_16x16x32_bf16 v[12:15], v[148:151], v[204:207], v[12:15]
	v_mfma_f32_16x16x32_bf16 v[8:11], v[156:159], v[204:207], v[8:11]
	s_setprio 0
	s_setprio 1
	v_mfma_f32_16x16x32_bf16 v[52:55], v[160:163], v[176:179], v[52:55]
	v_mfma_f32_16x16x32_bf16 v[48:51], v[168:171], v[176:179], v[48:51]
	v_mfma_f32_16x16x32_bf16 v[36:39], v[160:163], v[184:187], v[36:39]
	v_mfma_f32_16x16x32_bf16 v[32:35], v[168:171], v[184:187], v[32:35]
	v_mfma_f32_16x16x32_bf16 v[20:23], v[160:163], v[192:195], v[20:23]
	v_mfma_f32_16x16x32_bf16 v[16:19], v[168:171], v[192:195], v[16:19]
	v_mfma_f32_16x16x32_bf16 v[4:7], v[160:163], v[200:203], v[4:7]
	v_mfma_f32_16x16x32_bf16 v[0:3], v[168:171], v[200:203], v[0:3]
	v_mfma_f32_16x16x32_bf16 v[52:55], v[164:167], v[180:183], v[52:55]
	v_mfma_f32_16x16x32_bf16 v[48:51], v[172:175], v[180:183], v[48:51]
	v_mfma_f32_16x16x32_bf16 v[36:39], v[164:167], v[188:191], v[36:39]
	v_mfma_f32_16x16x32_bf16 v[32:35], v[172:175], v[188:191], v[32:35]
	v_mfma_f32_16x16x32_bf16 v[20:23], v[164:167], v[196:199], v[20:23]
	v_mfma_f32_16x16x32_bf16 v[16:19], v[172:175], v[196:199], v[16:19]
	v_mfma_f32_16x16x32_bf16 v[4:7], v[164:167], v[204:207], v[4:7]
	v_mfma_f32_16x16x32_bf16 v[0:3], v[172:175], v[204:207], v[0:3]
	s_setprio 0
	s_barrier
	s_add_i32 s59, s59, 2
	s_add_u32 s56, s56, 0x100
	s_addc_u32 s57, s57, 0
	s_cmp_gt_u32 s59, 61
	s_mov_b64 s[24:25], s[26:27]
	s_cbranch_scc0 .LBB0_3554
	s_and_b64 vcc, exec, s[10:11]
	s_cbranch_vccz .LBB0_3557
	s_barrier

; #define PG8_WAIT_V(n) asm volatile("s_waitcnt vmcnt(" #n ")" ::: "memory")
; #define PG8_WAIT_L(n) asm volatile("s_waitcnt lgkmcnt(" #n ")" ::: "memory")
; #define PG8_BAR __builtin_amdgcn_s_barrier()
; #define PG8_SCHED __builtin_amdgcn_sched_barrier(0)
;     ...
;             const char* a1 = cA + (size_t)(t + 1) * kstep;
;             const char* a2 = last ? nA : cA + (size_t)(t + 2) * kstep; const char* b2 = last ? nB : cB + (size_t)(t + 2) * kstep;
;             const char* a3 = a2 + kstep; const char* b3 = b2 + kstep;
;             if (last && has_next) S.a_ready(nxt);
;             if constexpr (SP2) {
;             PG8_LDB(B0, 0, 0); PG8_LDB(B1, 0, 1); PG8_SCHED; PG8_LDA(At, 0, 0); PG8_STAGE(PG8_SA(1, 1), a1 + hstepA, voffA);
;             PG8_WAIT_V(8); PG8_WAIT_L(0); PG8_BAR; PG8_MMA(0, 0, At, B0); PG8_MMA(0, 1, At, B1); PG8_BAR; PG8_SCHED;
;             if constexpr (!HALFU) PG8_LDA(At, 0, 1); PG8_STAGE(PG8_SB(0, 0), b2, voffB); PG8_STAGE(PG8_SB(0, 1), b2 + hstep, voffB); PG8_STAGE(PG8_SA(0, 0), a2, voffA);
;             PG8_WAIT_V(8); PG8_WAIT_L(0); PG8_BAR; if constexpr (!HALFU) { PG8_MMA(1, 0, At, B0); PG8_MMA(1, 1, At, B1); } PG8_BAR; PG8_SCHED;
.LBB0_3640:
	s_sub_u32 s98, s10, 0x158000
	s_subb_u32 s99, s11, 0
	ds_read_b128 v[142:145], v137
	ds_read_b128 v[146:149], v137 offset:1024
	ds_read_b128 v[150:153], v137 offset:2048
	ds_read_b128 v[154:157], v137 offset:3072
	ds_read_b128 v[158:161], v138
	ds_read_b128 v[162:165], v138 offset:1024
	ds_read_b128 v[166:169], v138 offset:2048
	ds_read_b128 v[170:173], v138 offset:3072
	s_cmpk_eq_i32 s55, 0x52
	s_cselect_b32 s28, s6, s51
	s_cselect_b32 s29, s7, s52
	s_cselect_b32 s26, s22, s53
	s_cselect_b32 s27, s23, s54
	s_add_u32 s24, s28, 0x80
	s_addc_u32 s25, s29, 0
	s_add_i32 m0, s33, 0xc000
	ds_read_b128 v[174:177], v139
	ds_read_b128 v[178:181], v139 offset:1024
	ds_read_b128 v[182:185], v139 offset:2048
	ds_read_b128 v[186:189], v139 offset:3072
	ds_read_b128 v[190:193], v139 offset:4096
	ds_read_b128 v[194:197], v139 offset:5120
	ds_read_b128 v[198:201], v139 offset:6144
	ds_read_b128 v[202:205], v139 offset:7168
	global_load_lds_dwordx4 v128, s[10:11]
	s_add_i32 m0, s33, 0xe000
	s_nop 0
	global_load_lds_dwordx4 v130, s[10:11]
	s_mov_b32 m0, s42
	s_nop 0
	global_load_lds_dwordx4 v128, s[98:99]
	s_mov_b32 m0, s43
	s_nop 0
	global_load_lds_dwordx4 v130, s[98:99]
	s_waitcnt vmcnt(8)
	s_waitcnt lgkmcnt(0)
	s_barrier
	s_setprio 1
	s_waitcnt lgkmcnt(0)
	v_mfma_scale_f32_16x16x128_f8f6f4 v[124:127], v[142:149], v[174:181], v[124:127], v140, v140 op_sel_hi:[0,0,0]
	v_mfma_scale_f32_16x16x128_f8f6f4 v[120:123], v[150:157], v[174:181], v[120:123], v140, v140 op_sel_hi:[0,0,0]
	v_mfma_scale_f32_16x16x128_f8f6f4 v[112:115], v[142:149], v[182:189], v[112:115], v140, v140 op_sel_hi:[0,0,0]
	v_mfma_scale_f32_16x16x128_f8f6f4 v[104:107], v[150:157], v[182:189], v[104:107], v140, v140 op_sel_hi:[0,0,0]
	v_mfma_scale_f32_16x16x128_f8f6f4 v[96:99], v[142:149], v[190:197], v[96:99], v140, v140 op_sel_hi:[0,0,0]
	v_mfma_scale_f32_16x16x128_f8f6f4 v[206:209], v[150:157], v[190:197], v[88:91], v140, v140 op_sel_hi:[0,0,0]
	v_mfma_scale_f32_16x16x128_f8f6f4 v[210:213], v[142:149], v[198:205], v[80:83], v140, v140 op_sel_hi:[0,0,0]
	v_mfma_scale_f32_16x16x128_f8f6f4 v[214:217], v[150:157], v[198:205], v[72:75], v140, v140 op_sel_hi:[0,0,0]
	s_setprio 0
	s_setprio 1
	v_mfma_scale_f32_16x16x128_f8f6f4 v[116:119], v[158:165], v[174:181], v[116:119], v140, v140 op_sel_hi:[0,0,0]
	v_mfma_scale_f32_16x16x128_f8f6f4 v[108:111], v[166:173], v[174:181], v[108:111], v140, v140 op_sel_hi:[0,0,0]
	v_mfma_scale_f32_16x16x128_f8f6f4 v[100:103], v[158:165], v[182:189], v[100:103], v140, v140 op_sel_hi:[0,0,0]
	v_mfma_scale_f32_16x16x128_f8f6f4 v[174:177], v[166:173], v[182:189], v[92:95], v140, v140 op_sel_hi:[0,0,0]
	v_mfma_scale_f32_16x16x128_f8f6f4 v[178:181], v[158:165], v[190:197], v[84:87], v140, v140 op_sel_hi:[0,0,0]
	v_mfma_scale_f32_16x16x128_f8f6f4 v[182:185], v[166:173], v[190:197], v[76:79], v140, v140 op_sel_hi:[0,0,0]
	v_mfma_scale_f32_16x16x128_f8f6f4 v[186:189], v[158:165], v[198:205], v[68:71], v140, v140 op_sel_hi:[0,0,0]
	v_mfma_scale_f32_16x16x128_f8f6f4 v[190:193], v[166:173], v[198:205], v[64:67], v140, v140 op_sel_hi:[0,0,0]
	s_setprio 0
	s_barrier
	s_add_i32 s56, s45, s30
	s_mov_b32 m0, s56
	s_nop 1
	ds_read_b128 v[64:67], v139 offset:16384
	ds_read_b128 v[68:71], v139 offset:17408
	ds_read_b128 v[72:75], v139 offset:18432
	ds_read_b128 v[76:79], v139 offset:19456
	ds_read_b128 v[80:83], v139 offset:20480
	ds_read_b128 v[84:87], v139 offset:21504
	ds_read_b128 v[88:91], v139 offset:22528
	ds_read_b128 v[92:95], v139 offset:23552
	global_load_lds_dwordx4 v128, s[26:27]
	s_add_i32 m0, s56, 0x2000
	s_add_u32 s56, s26, 0x158000
	s_addc_u32 s57, s27, 0
	s_add_i32 s58, s46, s30
	global_load_lds_dwordx4 v130, s[26:27]
	s_mov_b32 m0, s58
	s_nop 0
	global_load_lds_dwordx4 v128, s[56:57]
	s_add_i32 m0, s58, 0x2000
	s_nop 0
	global_load_lds_dwordx4 v130, s[56:57]
	s_waitcnt vmcnt(4)
	s_waitcnt lgkmcnt(0)
	s_barrier
	s_setprio 1
	s_waitcnt lgkmcnt(0)
	v_mfma_scale_f32_16x16x128_f8f6f4 v[60:63], v[142:149], v[64:71], v[60:63], v140, v140 op_sel_hi:[0,0,0]
	v_mfma_scale_f32_16x16x128_f8f6f4 v[56:59], v[150:157], v[64:71], v[56:59], v140, v140 op_sel_hi:[0,0,0]
	v_mfma_scale_f32_16x16x128_f8f6f4 v[48:51], v[142:149], v[72:79], v[48:51], v140, v140 op_sel_hi:[0,0,0]
	v_mfma_scale_f32_16x16x128_f8f6f4 v[194:197], v[150:157], v[72:79], v[40:43], v140, v140 op_sel_hi:[0,0,0]
	v_mfma_scale_f32_16x16x128_f8f6f4 v[198:201], v[142:149], v[80:87], v[32:35], v140, v140 op_sel_hi:[0,0,0]
	v_mfma_scale_f32_16x16x128_f8f6f4 v[202:205], v[150:157], v[80:87], v[24:27], v140, v140 op_sel_hi:[0,0,0]
	v_mfma_scale_f32_16x16x128_f8f6f4 v[218:221], v[142:149], v[88:95], v[16:19], v140, v140 op_sel_hi:[0,0,0]
	v_mfma_scale_f32_16x16x128_f8f6f4 v[222:225], v[150:157], v[88:95], v[8:11], v140, v140 op_sel_hi:[0,0,0]
	s_setprio 0
	s_setprio 1
	v_mfma_scale_f32_16x16x128_f8f6f4 v[52:55], v[158:165], v[64:71], v[52:55], v140, v140 op_sel_hi:[0,0,0]
	v_mfma_scale_f32_16x16x128_f8f6f4 v[226:229], v[166:173], v[64:71], v[44:47], v140, v140 op_sel_hi:[0,0,0]
	v_mfma_scale_f32_16x16x128_f8f6f4 v[230:233], v[158:165], v[72:79], v[36:39], v140, v140 op_sel_hi:[0,0,0]
	v_mfma_scale_f32_16x16x128_f8f6f4 v[234:237], v[166:173], v[72:79], v[28:31], v140, v140 op_sel_hi:[0,0,0]
	v_mfma_scale_f32_16x16x128_f8f6f4 v[238:241], v[158:165], v[80:87], v[20:23], v140, v140 op_sel_hi:[0,0,0]
	v_mfma_scale_f32_16x16x128_f8f6f4 v[242:245], v[166:173], v[80:87], v[12:15], v140, v140 op_sel_hi:[0,0,0]
	v_mfma_scale_f32_16x16x128_f8f6f4 v[246:249], v[158:165], v[88:95], v[4:7], v140, v140 op_sel_hi:[0,0,0]
	v_mfma_scale_f32_16x16x128_f8f6f4 v[250:253], v[166:173], v[88:95], v[0:3], v140, v140 op_sel_hi:[0,0,0]
	s_setprio 0
	s_barrier
; #define PG8_WAIT_V(n) asm volatile("s_waitcnt vmcnt(" #n ")" ::: "memory")
; #define PG8_WAIT_L(n) asm volatile("s_waitcnt lgkmcnt(" #n ")" ::: "memory")
; #define PG8_BAR __builtin_amdgcn_s_barrier()
; #define PG8_SCHED __builtin_amdgcn_sched_barrier(0)
;     ...
;             PG8_LDB(B0, 1, 0); PG8_LDB(B1, 1, 1); PG8_SCHED; PG8_LDA(At, 1, 0); PG8_STAGE(PG8_SA(0, 1), a2 + hstepA, voffA);
;             PG8_WAIT_V(8); PG8_WAIT_L(0); PG8_BAR; PG8_MMA(0, 0, At, B0); PG8_MMA(0, 1, At, B1); PG8_BAR; PG8_SCHED;
;             if constexpr (!HALFU) PG8_LDA(At, 1, 1); PG8_STAGE(PG8_SB(1, 0), b3, voffB); PG8_STAGE(PG8_SB(1, 1), b3 + hstep, voffB); PG8_STAGE(PG8_SA(1, 0), a3, voffA);
;             PG8_WAIT_V(8); PG8_WAIT_L(0); PG8_BAR; if constexpr (!HALFU) { PG8_MMA(1, 0, At, B0); PG8_MMA(1, 1, At, B1); } PG8_BAR; PG8_SCHED;
	s_mov_b32 m0, s33
	s_nop 0
	global_load_lds_dwordx4 v128, s[28:29]
	s_mov_b32 m0, s36
	s_nop 0
	global_load_lds_dwordx4 v130, s[28:29]
	s_add_i32 s56, 0, 0x18000
	s_add_i32 s57, 0, 0x1c000
	s_nop 0
	v_add_u32_e32 v12, s56, v136
	v_add_u32_e32 v16, s57, v136
	ds_read_b128 v[0:3], v12
	ds_read_b128 v[4:7], v12 offset:1024
	ds_read_b128 v[8:11], v12 offset:2048
	ds_read_b128 v[12:15], v12 offset:3072
	ds_read_b128 v[142:145], v16
	ds_read_b128 v[146:149], v16 offset:1024
	ds_read_b128 v[150:153], v16 offset:2048
	ds_read_b128 v[154:157], v16 offset:3072
	s_add_u32 s28, s28, 0x158000
	s_addc_u32 s29, s29, 0
	s_mov_b32 m0, s37
	ds_read_b128 v[16:19], v139 offset:32768
	ds_read_b128 v[20:23], v139 offset:33792
	ds_read_b128 v[24:27], v139 offset:34816
	ds_read_b128 v[28:31], v139 offset:35840
	ds_read_b128 v[32:35], v139 offset:36864
	ds_read_b128 v[36:39], v139 offset:37888
	ds_read_b128 v[40:43], v139 offset:38912
	ds_read_b128 v[44:47], v139 offset:39936
	global_load_lds_dwordx4 v128, s[28:29]
	s_mov_b32 m0, s38
	s_nop 0
	global_load_lds_dwordx4 v130, s[28:29]
	s_waitcnt vmcnt(8)
	s_waitcnt lgkmcnt(0)
	s_barrier
	s_setprio 1
	s_waitcnt lgkmcnt(0)
	v_mfma_scale_f32_16x16x128_f8f6f4 v[124:127], v[0:7], v[16:23], v[124:127], v140, v140 op_sel_hi:[0,0,0]
	v_mfma_scale_f32_16x16x128_f8f6f4 v[120:123], v[8:15], v[16:23], v[120:123], v140, v140 op_sel_hi:[0,0,0]
	v_mfma_scale_f32_16x16x128_f8f6f4 v[112:115], v[0:7], v[24:31], v[112:115], v140, v140 op_sel_hi:[0,0,0]
	v_mfma_scale_f32_16x16x128_f8f6f4 v[104:107], v[8:15], v[24:31], v[104:107], v140, v140 op_sel_hi:[0,0,0]
	v_mfma_scale_f32_16x16x128_f8f6f4 v[96:99], v[0:7], v[32:39], v[96:99], v140, v140 op_sel_hi:[0,0,0]
	v_mfma_scale_f32_16x16x128_f8f6f4 v[88:91], v[8:15], v[32:39], v[206:209], v140, v140 op_sel_hi:[0,0,0]
	v_mfma_scale_f32_16x16x128_f8f6f4 v[80:83], v[0:7], v[40:47], v[210:213], v140, v140 op_sel_hi:[0,0,0]
	v_mfma_scale_f32_16x16x128_f8f6f4 v[72:75], v[8:15], v[40:47], v[214:217], v140, v140 op_sel_hi:[0,0,0]
	s_setprio 0
	s_setprio 1
	v_mfma_scale_f32_16x16x128_f8f6f4 v[116:119], v[142:149], v[16:23], v[116:119], v140, v140 op_sel_hi:[0,0,0]
	v_mfma_scale_f32_16x16x128_f8f6f4 v[108:111], v[150:157], v[16:23], v[108:111], v140, v140 op_sel_hi:[0,0,0]
	v_mfma_scale_f32_16x16x128_f8f6f4 v[100:103], v[142:149], v[24:31], v[100:103], v140, v140 op_sel_hi:[0,0,0]
	v_mfma_scale_f32_16x16x128_f8f6f4 v[92:95], v[150:157], v[24:31], v[174:177], v140, v140 op_sel_hi:[0,0,0]
	v_mfma_scale_f32_16x16x128_f8f6f4 v[84:87], v[142:149], v[32:39], v[178:181], v140, v140 op_sel_hi:[0,0,0]
	v_mfma_scale_f32_16x16x128_f8f6f4 v[76:79], v[150:157], v[32:39], v[182:185], v140, v140 op_sel_hi:[0,0,0]
	v_mfma_scale_f32_16x16x128_f8f6f4 v[68:71], v[142:149], v[40:47], v[186:189], v140, v140 op_sel_hi:[0,0,0]
	v_mfma_scale_f32_16x16x128_f8f6f4 v[64:67], v[150:157], v[40:47], v[190:193], v140, v140 op_sel_hi:[0,0,0]
	s_setprio 0
	s_barrier
	s_add_u32 s28, s26, 0x80
	s_addc_u32 s29, s27, 0
	s_add_i32 s56, s56, s30
	s_mov_b32 m0, s56
	ds_read_b128 v[158:161], v139 offset:49152
	ds_read_b128 v[162:165], v139 offset:50176
	ds_read_b128 v[166:169], v139 offset:51200
	ds_read_b128 v[170:173], v139 offset:52224
	ds_read_b128 v[174:177], v139 offset:53248
	ds_read_b128 v[178:181], v139 offset:54272
	ds_read_b128 v[182:185], v139 offset:55296
	ds_read_b128 v[186:189], v139 offset:56320
	global_load_lds_dwordx4 v128, s[28:29]
	s_add_i32 m0, s56, 0x2000
	s_add_u32 s26, s26, 0x158080
	v_lshl_add_u64 v[16:17], s[28:29], 0, v[130:131]
	s_addc_u32 s27, s27, 0
	s_add_i32 s28, s57, s30
	global_load_lds_dwordx4 v[16:17], off
	s_mov_b32 m0, s28
	s_nop 0
	global_load_lds_dwordx4 v128, s[26:27]
	s_add_i32 m0, s28, 0x2000
	s_nop 0
	global_load_lds_dwordx4 v130, s[26:27]
	s_waitcnt vmcnt(4)
	s_waitcnt lgkmcnt(0)
	s_barrier
	s_setprio 1
	s_waitcnt lgkmcnt(0)
	v_mfma_scale_f32_16x16x128_f8f6f4 v[60:63], v[0:7], v[158:165], v[60:63], v140, v140 op_sel_hi:[0,0,0]
	v_mfma_scale_f32_16x16x128_f8f6f4 v[56:59], v[8:15], v[158:165], v[56:59], v140, v140 op_sel_hi:[0,0,0]
	v_mfma_scale_f32_16x16x128_f8f6f4 v[48:51], v[0:7], v[166:173], v[48:51], v140, v140 op_sel_hi:[0,0,0]
	v_mfma_scale_f32_16x16x128_f8f6f4 v[40:43], v[8:15], v[166:173], v[194:197], v140, v140 op_sel_hi:[0,0,0]
	v_mfma_scale_f32_16x16x128_f8f6f4 v[32:35], v[0:7], v[174:181], v[198:201], v140, v140 op_sel_hi:[0,0,0]
	v_mfma_scale_f32_16x16x128_f8f6f4 v[24:27], v[8:15], v[174:181], v[202:205], v140, v140 op_sel_hi:[0,0,0]
	v_mfma_scale_f32_16x16x128_f8f6f4 v[16:19], v[0:7], v[182:189], v[218:221], v140, v140 op_sel_hi:[0,0,0]
	v_mfma_scale_f32_16x16x128_f8f6f4 v[8:11], v[8:15], v[182:189], v[222:225], v140, v140 op_sel_hi:[0,0,0]
	s_setprio 0
	s_setprio 1
	v_mfma_scale_f32_16x16x128_f8f6f4 v[52:55], v[142:149], v[158:165], v[52:55], v140, v140 op_sel_hi:[0,0,0]
	v_mfma_scale_f32_16x16x128_f8f6f4 v[44:47], v[150:157], v[158:165], v[226:229], v140, v140 op_sel_hi:[0,0,0]
	v_mfma_scale_f32_16x16x128_f8f6f4 v[36:39], v[142:149], v[166:173], v[230:233], v140, v140 op_sel_hi:[0,0,0]
	v_mfma_scale_f32_16x16x128_f8f6f4 v[28:31], v[150:157], v[166:173], v[234:237], v140, v140 op_sel_hi:[0,0,0]
	v_mfma_scale_f32_16x16x128_f8f6f4 v[20:23], v[142:149], v[174:181], v[238:241], v140, v140 op_sel_hi:[0,0,0]
	v_mfma_scale_f32_16x16x128_f8f6f4 v[12:15], v[150:157], v[174:181], v[242:245], v140, v140 op_sel_hi:[0,0,0]
	v_mfma_scale_f32_16x16x128_f8f6f4 v[4:7], v[142:149], v[182:189], v[246:249], v140, v140 op_sel_hi:[0,0,0]
	v_mfma_scale_f32_16x16x128_f8f6f4 v[0:3], v[150:157], v[182:189], v[250:253], v140, v140 op_sel_hi:[0,0,0]
	s_setprio 0
	s_barrier
	s_add_i32 s55, s55, 2
	s_add_u32 s51, s51, 0x100
	s_addc_u32 s52, s52, 0
	s_add_u32 s53, s53, 0x100
	s_addc_u32 s54, s54, 0
	s_add_u32 s10, s10, 0x100
	s_addc_u32 s11, s11, 0
	s_cmpk_gt_u32 s55, 0x53
	s_cbranch_scc0 .LBB0_3640
	s_and_b64 vcc, exec, s[12:13]
	s_cbranch_vccz .LBB0_3643
	s_barrier
